# v68 plus trailing-half per-unit barrier moved to the peeled-iteration entry (after the unit header)
# baseline (speedup 1.0000x reference)
; #define PG8_WAIT_V(n) asm volatile("s_waitcnt vmcnt(" #n ")" ::: "memory")
; #define PG8_BAR __builtin_amdgcn_s_barrier()
; template <class Epi, class Sched, bool ALIGN_EPI = false, bool SP2 = false, bool ATILED = false>
; __device__ __forceinline__ void gemm_phase(PG8_LAS unsigned char* lds, const Gemm g, const Sched& S, const Epi& E) {
;     const int tid = threadIdx.x, wid = __builtin_amdgcn_readfirstlane(tid >> 6), lane = tid & 63, wr = wid >> 2, wc = wid & 3, fr = lane & 15, fq = lane >> 4;
;     const int K = g.K, nt = K / BK;
;     unsigned voffA[2], voffB[2];
; #pragma unroll
;     for (int i = 0; i < 2; ++i) { int R, C; stage_rc(tid * 16 + i * 8192, R, C); const int Rb = Epi::PERM ? ((R & ~31) + perm32(R & 31)) : R;
;         voffA[i] = (unsigned)(R * (ATILED ? BK : K) + C) * 2u; voffB[i] = (unsigned)(Rb * K + C) * 2u; }
;     const size_t kstep = (size_t)(BK * 2);
;     const size_t hstep = (size_t)HALF * K * 2;
;     const size_t tstep = 2 * hstep;
;     const size_t kstepA = ATILED ? (size_t)(BM * BK * 2) : kstep, hstepA = ATILED ? (size_t)(HALF * BK * 2) : hstep, tstepA = ATILED ? (size_t)nt * (BM * BK * 2) : tstep;
;     const unsigned ldsw = (unsigned)wid * 1024u;
;     const int aoff = lds_byte(wr * 64 + fr, fq * 8), boff = lds_byte(wc * 32 + fr, fq * 8);
;     ...
;     Unit cur, nxt; int ui = 0;
;     if (!S.next(0, cur)) return;
;     f32x4 acc[2][2][4][2];
; #pragma unroll
;     for (int a = 0; a < 2; ++a)
; #pragma unroll
;         for (int b = 0; b < 2; ++b)
; #pragma unroll
;             for (int m = 0; m < 4; ++m)
; #pragma unroll
;                 for (int n = 0; n < 2; ++n) acc[a][b][m][n] = (f32x4){0.f, 0.f, 0.f, 0.f};
;     bf16x8 At[4][2], B0[2][2], B1[2][2];
;     const char* cA = (const char*)g.A + (size_t)cur.pm * tstepA; const char* cB = (const char*)g.Bt + (size_t)cur.pn * tstep;
;     S.a_ready(cur);
;     if constexpr (SP2) {
;         PG8_STAGE(PG8_SB(0, 0), cB, voffB); PG8_STAGE(PG8_SB(0, 1), cB + hstep, voffB); PG8_STAGE(PG8_SA(0, 0), cA, voffA); PG8_STAGE(PG8_SA(0, 1), cA + hstepA, voffA);
;         if (wr == 1) PG8_BAR;
;         PG8_WAIT_V(2); PG8_BAR;
;         PG8_STAGE(PG8_SB(1, 0), cB + kstep, voffB); PG8_STAGE(PG8_SA(1, 0), cA + kstepA, voffA); PG8_STAGE(PG8_SB(1, 1), cB + hstep + kstep, voffB);
;         PG8_WAIT_V(6); PG8_BAR;
.LBB0_123:
	s_waitcnt lgkmcnt(0)
	s_add_u32 s36, s26, 0x8000000
	s_addc_u32 s37, s27, 0
	s_add_u32 s10, s26, 0x24000000
	s_addc_u32 s11, s27, 0
	s_cmp_lt_i32 s30, 2
	s_cselect_b64 s[0:1], -1, 0
	s_cmp_gt_i32 s31, 1
	s_cselect_b64 s[4:5], -1, 0
	s_and_b64 s[0:1], s[0:1], s[4:5]
	s_andn2_b64 vcc, exec, s[0:1]
	s_cbranch_vccnz .LBB0_190
	s_cmpk_gt_i32 s2, 0x15ff
	v_readfirstlane_b32 s1, v198
	s_cbranch_scc1 .LBB0_140
	v_lshrrev_b32_e32 v2, 1, v198
	v_lshrrev_b32_e32 v3, 5, v198
	v_and_b32_e32 v2, 24, v2
	v_and_b32_e32 v3, 4, v3
	v_bfe_u32 v4, v198, 2, 2
	v_lshlrev_b32_e32 v0, 4, v198
	v_and_b32_e32 v1, 32, v198
	v_bfe_u32 v10, v198, 2, 4
	v_or3_b32 v2, v3, v4, v2
	v_lshrrev_b32_e32 v3, 3, v198
	s_movk_i32 s0, 0x70
	v_bitop3_b32 v8, v0, v1, 48 bitop3:0x6c
	v_and_b32_e32 v9, 64, v198
	v_and_or_b32 v4, v3, s0, v10
	s_movk_i32 s0, 0x60
	v_add_u32_e32 v11, 0x2000, v0
	v_or_b32_e32 v1, v8, v9
	v_and_or_b32 v3, v3, s0, v2
	v_lshrrev_b32_e32 v0, 7, v11
	s_movk_i32 s0, 0xf0
	v_lshl_or_b32 v130, v3, 11, v1
	v_and_or_b32 v3, v0, s0, v10
	s_movk_i32 s0, 0xe0
	s_ashr_i32 s29, s2, 31
	v_and_or_b32 v0, v0, s0, v2
	s_lshr_b32 s0, s29, 29
	s_add_i32 s0, s2, s0
	s_lshr_b32 s8, s1, 6
	s_ashr_i32 s4, s0, 3
	s_and_b32 s0, s0, -8
	s_lshr_b32 s9, s1, 8
	s_lshl_b32 s66, s8, 10
	s_sub_i32 s0, s2, s0
	s_cmp_lt_i32 s0, 0
	s_movk_i32 s67, 0x2c1
	s_cselect_b32 s5, s67, 0x2c0
	s_mul_i32 s0, s0, s5
	s_add_i32 s0, s0, s4
	s_mul_hi_i32 s4, s0, 0x2e8ba2e9
	s_lshr_b32 s5, s4, 31
	s_ashr_i32 s4, s4, 5
	s_add_i32 s4, s4, s5
	s_lshl_b32 s5, s4, 3
	s_mulk_i32 s4, 0xb0
	s_sub_i32 s4, s0, s4
	s_bfe_u32 s0, s4, 0x3001c
	s_add_i32 s38, s4, s0
	s_sext_i32_i16 s0, s38
	s_and_b32 s38, s38, 0xfff8
	s_sub_i32 s4, s4, s38
	s_sext_i32_i16 s4, s4
	s_lshr_b32 s0, s0, 3
	s_add_i32 s48, s5, s4
	s_ashr_i32 s49, s48, 31
	s_bfe_i64 s[38:39], s[0:1], 0x100000
	s_lshl_b64 s[4:5], s[48:49], 19
	s_lshl_b64 s[38:39], s[38:39], 19
	s_add_u32 s62, s6, s38
	s_addc_u32 s63, s7, s39
	s_add_i32 s49, s66, 0
	s_add_i32 m0, s49, 0x10000
	v_lshl_or_b32 v134, v0, 11, v1
	global_load_lds_dwordx4 v130, s[62:63]
	s_add_i32 m0, s49, 0x12000
	s_add_u32 s38, s62, 0x40000
	global_load_lds_dwordx4 v134, s[62:63]
	s_addc_u32 s39, s63, 0
	s_add_i32 m0, s49, 0x14000
	v_lshl_or_b32 v128, v4, 11, v1
	global_load_lds_dwordx4 v130, s[38:39]
	s_add_i32 m0, s49, 0x16000
	s_add_u32 s60, s26, s4
	s_addc_u32 s61, s27, s5
	s_add_i32 s68, s49, 0x2000
	global_load_lds_dwordx4 v134, s[38:39]
	s_mov_b32 m0, s49
	s_add_u32 s4, s60, 0x40000
	v_lshl_or_b32 v132, v3, 11, v1
	global_load_lds_dwordx4 v128, s[60:61]
	s_mov_b32 m0, s68
	s_addc_u32 s5, s61, 0
	s_add_i32 s69, s49, 0x4000
	global_load_lds_dwordx4 v132, s[60:61]
	s_mov_b32 m0, s69
	s_add_i32 s70, s49, 0x6000
	global_load_lds_dwordx4 v128, s[4:5]
	s_mov_b32 m0, s70
	v_mov_b32_e32 v137, 0
	global_load_lds_dwordx4 v132, s[4:5]
	v_mov_b32_e32 v131, v137
	v_mov_b32_e32 v135, v137
	v_mov_b32_e32 v129, v137
	v_mov_b32_e32 v133, v137
	s_cmp_eq_u32 s9, 1
	s_movk_i32 s71, 0x2000
	s_mov_b32 s72, 0
	v_lshl_add_u64 v[6:7], s[62:63], 0, v[130:131]
	v_lshl_add_u64 v[4:5], s[62:63], 0, v[134:135]
	v_lshl_add_u64 v[0:1], s[60:61], 0, v[128:129]
	s_cselect_b64 s[4:5], -1, 0
	s_cmp_lg_u32 s9, 1
	v_lshl_add_u64 v[2:3], s[60:61], 0, v[132:133]
.LBB0_127:
	s_lshl_b32 s74, s9, 6
	s_lshl_b32 s40, s9, 13
	s_lshl_b32 s41, s8, 5
	s_mov_b64 s[8:9], 0x80
	s_and_b32 s75, s41, 0x60
	s_add_i32 m0, s49, 0x18000
	v_lshl_add_u64 v[6:7], v[6:7], 0, s[8:9]
	s_ashr_i32 s73, s28, 31
	s_lshl_b32 s42, s75, 7
	s_waitcnt vmcnt(2)
	s_barrier
	global_load_lds_dwordx4 v[6:7], off
	v_lshl_add_u64 v[4:5], v[4:5], 0, s[8:9]
	s_add_i32 m0, s49, 0x1a000
	s_add_i32 s76, s49, 0x8000
	s_add_i32 s77, s49, 0xa000
	global_load_lds_dwordx4 v[4:5], off
	v_lshl_add_u64 v[0:1], v[0:1], 0, s[8:9]
	s_mov_b32 m0, s76
	s_add_u32 s38, s62, 0x40080
	global_load_lds_dwordx4 v[0:1], off
	v_lshl_add_u64 v[0:1], v[2:3], 0, s[8:9]
	s_mov_b32 m0, s77
	s_addc_u32 s39, s63, 0
	global_load_lds_dwordx4 v[0:1], off
	s_add_i32 m0, s49, 0x1c000
	v_lshl_add_u64 v[0:1], s[38:39], 0, v[130:131]
	global_load_lds_dwordx4 v[0:1], off
	v_lshl_add_u64 v[0:1], s[38:39], 0, v[134:135]
	s_add_i32 m0, s49, 0x1e000
	s_sext_i32_i16 s81, s0
	global_load_lds_dwordx4 v[0:1], off
	v_bfe_u32 v0, v198, 4, 2
	v_lshlrev_b32_e32 v1, 3, v0
	v_lshlrev_b32_e32 v136, 4, v0
	v_lshlrev_b32_e32 v0, 6, v198
	s_movk_i32 s0, 0x3c0
	v_lshlrev_b32_e32 v2, 2, v198
	v_and_b32_e32 v154, 15, v198
	v_and_or_b32 v0, v0, s0, v136
	v_and_b32_e32 v2, 32, v2
	v_lshl_or_b32 v3, v154, 6, v136
	v_bitop3_b32 v155, s42, v0, v2 bitop3:0xf6
	v_and_or_b32 v0, s41, 32, v1
	v_lshlrev_b32_e32 v1, 8, v198
	v_bitop3_b32 v3, v3, s40, v2 bitop3:0xde
	v_and_b32_e32 v1, 0x38000, v1
	v_lshlrev_b32_e32 v2, 11, v10
	v_or3_b32 v1, v8, v1, v2
	v_add_u32_e32 v140, v1, v9
	v_lshlrev_b32_e32 v1, 4, v11
	v_and_b32_e32 v1, 0x78000, v1
	s_waitcnt vmcnt(6)
	s_cmpk_lt_u32 s1, 0x100
	v_or3_b32 v1, v8, v1, v2
	s_cselect_b64 s[38:39], -1, 0
	v_add_u32_e32 v142, v1, v9
	s_add_i32 s78, 0, 0x10000
	s_add_i32 s79, 0, 0x14000
	v_mbcnt_lo_u32_b32 v1, -1, 0
	v_lshl_add_u64 v[138:139], s[10:11], 0, v[136:137]
	v_mov_b32_e32 v141, v137
	v_mov_b32_e32 v143, v137
	v_mov_b64_e32 v[144:145], 0x1600
	v_mov_b64_e32 v[146:147], 0x15ff
	v_add_u32_e32 v156, s78, v155
	v_add_u32_e32 v157, s79, v155
	v_add_u32_e32 v158, 0, v3
	v_mbcnt_hi_u32_b32 v159, -1, v1
	v_mov_b32_e32 v160, 0x358637bd
	v_lshlrev_b32_e32 v148, 1, v0
	s_movk_i32 s80, 0x1000
	s_barrier
	s_branch .LBB0_130

; #define PG8_STAGE(bufoff, gbase, voff) do { _Pragma("unroll") for (int _i = 0; _i < 2; ++_i) \
;         __builtin_amdgcn_global_load_lds((const unsigned*)((const char*)(gbase) + (voff)[_i]), (PG8_LAS unsigned*)(lds + (bufoff) + ldsw + _i * 8192), 16, 0, 0); } while (0)
; #define PG8_LDA(dst, b, h) do { _Pragma("unroll") for (int m = 0; m < 4; ++m) _Pragma("unroll") for (int k = 0; k < 2; ++k) dst[m][k] = *(const PG8_LAS bf16x8*)(lds + PG8_SA(b, h) + aoff + m * 2048 + k * 1024); } while (0)
; #define PG8_LDB(dst, b, h) do { _Pragma("unroll") for (int n = 0; n < 2; ++n) _Pragma("unroll") for (int k = 0; k < 2; ++k) dst[n][k] = *(const PG8_LAS bf16x8*)(lds + PG8_SB(b, h) + boff + n * 2048 + k * 1024); } while (0)
; #define PG8_SCHED __builtin_amdgcn_sched_barrier(0)
; template <class Epi, class Sched, bool ALIGN_EPI = false, bool SP2 = false, bool ATILED = false>
; __device__ __forceinline__ void gemm_phase(PG8_LAS unsigned char* lds, const Gemm g, const Sched& S, const Epi& E) {
;     ...
;         const char* nA = has_next ? (const char*)g.A + (size_t)nxt.pm * tstepA : cA; const char* nB = has_next ? (const char*)g.Bt + (size_t)nxt.pn * tstep : cB;
;         for (int t = 0; t < nt; t += 2) {
;             const bool last = (t == nt - 2);
;             const char* a1 = cA + (size_t)(t + 1) * kstepA;
;             const char* a2 = last ? nA : cA + (size_t)(t + 2) * kstepA; const char* b2 = last ? nB : cB + (size_t)(t + 2) * kstep;
;             const char* a3 = a2 + kstepA; const char* b3 = b2 + kstep;
;             if (last && has_next) S.a_ready(nxt);
;             if constexpr (SP2) {
;             PG8_LDB(B0, 0, 0); PG8_LDB(B1, 0, 1); PG8_SCHED; PG8_LDA(At, 0, 0); PG8_STAGE(PG8_SA(1, 1), a1 + hstepA, voffA);
.LBB0_132:
	s_ashr_i32 s43, s42, 31
	s_lshl_b64 s[44:45], s[42:43], 19
	s_add_u32 s44, s26, s44
	s_addc_u32 s45, s27, s45
	s_and_b64 s[46:47], s[0:1], exec
	s_cselect_b32 s43, s45, s61
	s_cselect_b32 s83, s44, s60
	s_ashr_i32 s41, s40, 31
	s_lshl_b64 s[46:47], s[40:41], 19
	s_add_u32 s46, s6, s46
	s_addc_u32 s47, s7, s47
	s_and_b64 s[64:65], s[0:1], exec
	s_cselect_b32 s41, s47, s63
	s_cselect_b32 s84, s46, s62
	s_add_u32 s60, s60, 0x40080
	s_addc_u32 s61, s61, 0
	s_add_u32 s85, s62, 0x100
	s_addc_u32 s86, s63, 0
	s_mov_b32 s87, -2
	s_cmp_lg_u64 s[4:5], 0
	s_cbranch_scc0 .Ltbar_skip0
	s_barrier
.Ltbar_skip0:
	ds_read_b128 v[150:153], v156
	ds_read_b128 v[162:165], v156 offset:1024
	ds_read_b128 v[166:169], v156 offset:2048
	ds_read_b128 v[170:173], v156 offset:3072
	ds_read_b128 v[174:177], v157
	ds_read_b128 v[178:181], v157 offset:1024
	ds_read_b128 v[182:185], v157 offset:2048
	ds_read_b128 v[186:189], v157 offset:3072
	s_add_u32 s62, s60, 0xfffc0080
	s_addc_u32 s63, s61, -1
	s_cmp_eq_u32 s87, 12
	s_cselect_b32 s65, s43, s63
	s_cselect_b32 s64, s83, s62
	s_cselect_b32 s63, s41, s86
	s_cselect_b32 s62, s84, s85

; #define PG8_STAGE(bufoff, gbase, voff) do { _Pragma("unroll") for (int _i = 0; _i < 2; ++_i) \
;         __builtin_amdgcn_global_load_lds((const unsigned*)((const char*)(gbase) + (voff)[_i]), (PG8_LAS unsigned*)(lds + (bufoff) + ldsw + _i * 8192), 16, 0, 0); } while (0)
; #define PG8_LDA(dst, b, h) do { _Pragma("unroll") for (int m = 0; m < 4; ++m) _Pragma("unroll") for (int k = 0; k < 2; ++k) dst[m][k] = *(const PG8_LAS bf16x8*)(lds + PG8_SA(b, h) + aoff + m * 2048 + k * 1024); } while (0)
; #define PG8_LDB(dst, b, h) do { _Pragma("unroll") for (int n = 0; n < 2; ++n) _Pragma("unroll") for (int k = 0; k < 2; ++k) dst[n][k] = *(const PG8_LAS bf16x8*)(lds + PG8_SB(b, h) + boff + n * 2048 + k * 1024); } while (0)
; #define PG8_SCHED __builtin_amdgcn_sched_barrier(0)
; template <class Epi, class Sched, bool ALIGN_EPI = false, bool SP2 = false, bool ATILED = false>
; __device__ __forceinline__ void gemm_phase(PG8_LAS unsigned char* lds, const Gemm g, const Sched& S, const Epi& E) {
;     ...
;             PG8_LDB(B0, 0, 0); PG8_LDB(B1, 0, 1); PG8_SCHED; PG8_LDA(At, 0, 0); PG8_STAGE(PG8_SA(1, 1), a1 + hstepA, voffA);
	s_add_i32 m0, s49, 0xc000
	ds_read_b128 v[190:193], v158
	ds_read_b128 v[194:197], v158 offset:1024
	ds_read_b128 v[200:203], v158 offset:2048
	ds_read_b128 v[204:207], v158 offset:3072
	ds_read_b128 v[208:211], v158 offset:4096
	ds_read_b128 v[212:215], v158 offset:5120
	ds_read_b128 v[216:219], v158 offset:6144
	ds_read_b128 v[220:223], v158 offset:7168
	global_load_lds_dwordx4 v140, s[60:61]

; #define PG8_STAGE(bufoff, gbase, voff) do { _Pragma("unroll") for (int _i = 0; _i < 2; ++_i) \
;         __builtin_amdgcn_global_load_lds((const unsigned*)((const char*)(gbase) + (voff)[_i]), (PG8_LAS unsigned*)(lds + (bufoff) + ldsw + _i * 8192), 16, 0, 0); } while (0)
; #define PG8_LDA(dst, b, h) do { _Pragma("unroll") for (int m = 0; m < 4; ++m) _Pragma("unroll") for (int k = 0; k < 2; ++k) dst[m][k] = *(const PG8_LAS bf16x8*)(lds + PG8_SA(b, h) + aoff + m * 2048 + k * 1024); } while (0)
; #define PG8_LDB(dst, b, h) do { _Pragma("unroll") for (int n = 0; n < 2; ++n) _Pragma("unroll") for (int k = 0; k < 2; ++k) dst[n][k] = *(const PG8_LAS bf16x8*)(lds + PG8_SB(b, h) + boff + n * 2048 + k * 1024); } while (0)
; #define PG8_MMA(ai, bj, At, Bt) do { __builtin_amdgcn_s_setprio(1); _Pragma("unroll") for (int m = 0; m < 4; ++m) _Pragma("unroll") for (int n = 0; n < 2; ++n) _Pragma("unroll") for (int k = 0; k < 2; ++k) \
;         acc[ai][bj][m][n] = __builtin_amdgcn_mfma_f32_16x16x32_bf16(Bt[n][k], At[m][k], acc[ai][bj][m][n], 0, 0, 0); __builtin_amdgcn_s_setprio(0); } while (0)
; #define PG8_WAIT_V(n) asm volatile("s_waitcnt vmcnt(" #n ")" ::: "memory")
; #define PG8_WAIT_L(n) asm volatile("s_waitcnt lgkmcnt(" #n ")" ::: "memory")
; #define PG8_BAR __builtin_amdgcn_s_barrier()
; #define PG8_SCHED __builtin_amdgcn_sched_barrier(0)
; template <class Epi, class Sched, bool ALIGN_EPI = false, bool SP2 = false, bool ATILED = false>
; __device__ __forceinline__ void gemm_phase(PG8_LAS unsigned char* lds, const Gemm g, const Sched& S, const Epi& E) {
;     ...
;             PG8_LDB(B0, 0, 0); PG8_LDB(B1, 0, 1); PG8_SCHED; PG8_LDA(At, 0, 0); PG8_STAGE(PG8_SA(1, 1), a1 + hstepA, voffA);
;             PG8_WAIT_V(8); PG8_WAIT_L(0); PG8_BAR; PG8_MMA(0, 0, At, B0); PG8_MMA(0, 1, At, B1); PG8_BAR; PG8_SCHED;
	s_add_i32 m0, s49, 0xe000
	s_nop 0
	global_load_lds_dwordx4 v142, s[60:61]
	s_waitcnt vmcnt(8)
	s_waitcnt lgkmcnt(0)
	s_barrier
	s_setprio 1
	s_waitcnt lgkmcnt(0)
	v_mfma_f32_16x16x32_bf16 v[124:127], v[150:153], v[190:193], 0
	v_mfma_f32_16x16x32_bf16 v[120:123], v[166:169], v[190:193], 0
	v_mfma_f32_16x16x32_bf16 v[108:111], v[150:153], v[200:203], 0
	v_mfma_f32_16x16x32_bf16 v[104:107], v[166:169], v[200:203], 0
	v_mfma_f32_16x16x32_bf16 v[92:95], v[150:153], v[208:211], 0
	v_mfma_f32_16x16x32_bf16 v[88:91], v[166:169], v[208:211], 0
	v_mfma_f32_16x16x32_bf16 v[76:79], v[150:153], v[216:219], 0
	v_mfma_f32_16x16x32_bf16 v[72:75], v[166:169], v[216:219], 0
	v_mfma_f32_16x16x32_bf16 v[124:127], v[162:165], v[194:197], v[124:127]
	v_mfma_f32_16x16x32_bf16 v[120:123], v[170:173], v[194:197], v[120:123]
	v_mfma_f32_16x16x32_bf16 v[108:111], v[162:165], v[204:207], v[108:111]
	v_mfma_f32_16x16x32_bf16 v[104:107], v[170:173], v[204:207], v[104:107]
	v_mfma_f32_16x16x32_bf16 v[92:95], v[162:165], v[212:215], v[92:95]
	v_mfma_f32_16x16x32_bf16 v[88:91], v[170:173], v[212:215], v[88:91]
	v_mfma_f32_16x16x32_bf16 v[76:79], v[162:165], v[220:223], v[76:79]
	v_mfma_f32_16x16x32_bf16 v[72:75], v[170:173], v[220:223], v[72:75]
	s_setprio 0
	s_setprio 1
	v_mfma_f32_16x16x32_bf16 v[116:119], v[174:177], v[190:193], 0
	v_mfma_f32_16x16x32_bf16 v[112:115], v[182:185], v[190:193], 0
	v_mfma_f32_16x16x32_bf16 v[100:103], v[174:177], v[200:203], 0
	v_mfma_f32_16x16x32_bf16 v[96:99], v[182:185], v[200:203], 0
	v_mfma_f32_16x16x32_bf16 v[84:87], v[174:177], v[208:211], 0
	v_mfma_f32_16x16x32_bf16 v[80:83], v[182:185], v[208:211], 0
	v_mfma_f32_16x16x32_bf16 v[68:71], v[174:177], v[216:219], 0
	v_mfma_f32_16x16x32_bf16 v[64:67], v[182:185], v[216:219], 0
	v_mfma_f32_16x16x32_bf16 v[116:119], v[178:181], v[194:197], v[116:119]
	v_mfma_f32_16x16x32_bf16 v[112:115], v[186:189], v[194:197], v[112:115]
	v_mfma_f32_16x16x32_bf16 v[100:103], v[178:181], v[204:207], v[100:103]
	v_mfma_f32_16x16x32_bf16 v[96:99], v[186:189], v[204:207], v[96:99]
	v_mfma_f32_16x16x32_bf16 v[84:87], v[178:181], v[212:215], v[84:87]
	v_mfma_f32_16x16x32_bf16 v[80:83], v[186:189], v[212:215], v[80:83]
	v_mfma_f32_16x16x32_bf16 v[68:71], v[178:181], v[220:223], v[68:71]
	v_mfma_f32_16x16x32_bf16 v[64:67], v[186:189], v[220:223], v[64:67]
	s_setprio 0
	s_barrier
	s_add_u32 s98, s62, s8
	s_addc_u32 s99, s63, s9
	s_add_u32 s100, s64, s8
	s_addc_u32 s101, s65, s9
	s_add_i32 s88, s78, s66

; #define PG8_STAGE(bufoff, gbase, voff) do { _Pragma("unroll") for (int _i = 0; _i < 2; ++_i) \
;         __builtin_amdgcn_global_load_lds((const unsigned*)((const char*)(gbase) + (voff)[_i]), (PG8_LAS unsigned*)(lds + (bufoff) + ldsw + _i * 8192), 16, 0, 0); } while (0)
; #define PG8_LDA(dst, b, h) do { _Pragma("unroll") for (int m = 0; m < 4; ++m) _Pragma("unroll") for (int k = 0; k < 2; ++k) dst[m][k] = *(const PG8_LAS bf16x8*)(lds + PG8_SA(b, h) + aoff + m * 2048 + k * 1024); } while (0)
; template <class Epi, class Sched, bool ALIGN_EPI = false, bool SP2 = false, bool ATILED = false>
; __device__ __forceinline__ void gemm_phase(PG8_LAS unsigned char* lds, const Gemm g, const Sched& S, const Epi& E) {
;     ...
;             PG8_LDA(At, 0, 1); PG8_STAGE(PG8_SB(0, 0), b2, voffB); PG8_STAGE(PG8_SB(0, 1), b2 + hstep, voffB); PG8_STAGE(PG8_SA(0, 0), a2, voffA);
	s_mov_b32 m0, s88
	ds_read_b128 v[190:193], v158 offset:16384
	ds_read_b128 v[194:197], v158 offset:17408
	ds_read_b128 v[200:203], v158 offset:18432
	ds_read_b128 v[204:207], v158 offset:19456
	ds_read_b128 v[208:211], v158 offset:20480
	ds_read_b128 v[212:215], v158 offset:21504
	ds_read_b128 v[216:219], v158 offset:22528
	ds_read_b128 v[220:223], v158 offset:23552
	global_load_lds_dwordx4 v130, s[62:63]
	s_add_i32 m0, s88, 0x2000
	s_add_u32 s88, s62, 0x40000

; #define PG8_STAGE(bufoff, gbase, voff) do { _Pragma("unroll") for (int _i = 0; _i < 2; ++_i) \
;         __builtin_amdgcn_global_load_lds((const unsigned*)((const char*)(gbase) + (voff)[_i]), (PG8_LAS unsigned*)(lds + (bufoff) + ldsw + _i * 8192), 16, 0, 0); } while (0)
; #define PG8_LDA(dst, b, h) do { _Pragma("unroll") for (int m = 0; m < 4; ++m) _Pragma("unroll") for (int k = 0; k < 2; ++k) dst[m][k] = *(const PG8_LAS bf16x8*)(lds + PG8_SA(b, h) + aoff + m * 2048 + k * 1024); } while (0)
; template <class Epi, class Sched, bool ALIGN_EPI = false, bool SP2 = false, bool ATILED = false>
; __device__ __forceinline__ void gemm_phase(PG8_LAS unsigned char* lds, const Gemm g, const Sched& S, const Epi& E) {
;     ...
;             PG8_LDA(At, 0, 1); PG8_STAGE(PG8_SB(0, 0), b2, voffB); PG8_STAGE(PG8_SB(0, 1), b2 + hstep, voffB); PG8_STAGE(PG8_SA(0, 0), a2, voffA);
	s_addc_u32 s89, s63, 0
	s_add_i32 s90, s79, s66
	global_load_lds_dwordx4 v134, s[62:63]

; #define PG8_STAGE(bufoff, gbase, voff) do { _Pragma("unroll") for (int _i = 0; _i < 2; ++_i) \
;         __builtin_amdgcn_global_load_lds((const unsigned*)((const char*)(gbase) + (voff)[_i]), (PG8_LAS unsigned*)(lds + (bufoff) + ldsw + _i * 8192), 16, 0, 0); } while (0)
; #define PG8_LDA(dst, b, h) do { _Pragma("unroll") for (int m = 0; m < 4; ++m) _Pragma("unroll") for (int k = 0; k < 2; ++k) dst[m][k] = *(const PG8_LAS bf16x8*)(lds + PG8_SA(b, h) + aoff + m * 2048 + k * 1024); } while (0)
; template <class Epi, class Sched, bool ALIGN_EPI = false, bool SP2 = false, bool ATILED = false>
; __device__ __forceinline__ void gemm_phase(PG8_LAS unsigned char* lds, const Gemm g, const Sched& S, const Epi& E) {
;     ...
;             PG8_LDA(At, 0, 1); PG8_STAGE(PG8_SB(0, 0), b2, voffB); PG8_STAGE(PG8_SB(0, 1), b2 + hstep, voffB); PG8_STAGE(PG8_SA(0, 0), a2, voffA);
	s_mov_b32 m0, s90

; #define PG8_STAGE(bufoff, gbase, voff) do { _Pragma("unroll") for (int _i = 0; _i < 2; ++_i) \
;         __builtin_amdgcn_global_load_lds((const unsigned*)((const char*)(gbase) + (voff)[_i]), (PG8_LAS unsigned*)(lds + (bufoff) + ldsw + _i * 8192), 16, 0, 0); } while (0)
; #define PG8_LDA(dst, b, h) do { _Pragma("unroll") for (int m = 0; m < 4; ++m) _Pragma("unroll") for (int k = 0; k < 2; ++k) dst[m][k] = *(const PG8_LAS bf16x8*)(lds + PG8_SA(b, h) + aoff + m * 2048 + k * 1024); } while (0)
; template <class Epi, class Sched, bool ALIGN_EPI = false, bool SP2 = false, bool ATILED = false>
; __device__ __forceinline__ void gemm_phase(PG8_LAS unsigned char* lds, const Gemm g, const Sched& S, const Epi& E) {
;     ...
;             PG8_LDA(At, 0, 1); PG8_STAGE(PG8_SB(0, 0), b2, voffB); PG8_STAGE(PG8_SB(0, 1), b2 + hstep, voffB); PG8_STAGE(PG8_SA(0, 0), a2, voffA);
	s_nop 0
	global_load_lds_dwordx4 v130, s[88:89]

; #define PG8_STAGE(bufoff, gbase, voff) do { _Pragma("unroll") for (int _i = 0; _i < 2; ++_i) \
;         __builtin_amdgcn_global_load_lds((const unsigned*)((const char*)(gbase) + (voff)[_i]), (PG8_LAS unsigned*)(lds + (bufoff) + ldsw + _i * 8192), 16, 0, 0); } while (0)
; #define PG8_LDA(dst, b, h) do { _Pragma("unroll") for (int m = 0; m < 4; ++m) _Pragma("unroll") for (int k = 0; k < 2; ++k) dst[m][k] = *(const PG8_LAS bf16x8*)(lds + PG8_SA(b, h) + aoff + m * 2048 + k * 1024); } while (0)
; template <class Epi, class Sched, bool ALIGN_EPI = false, bool SP2 = false, bool ATILED = false>
; __device__ __forceinline__ void gemm_phase(PG8_LAS unsigned char* lds, const Gemm g, const Sched& S, const Epi& E) {
;     ...
;             PG8_LDA(At, 0, 1); PG8_STAGE(PG8_SB(0, 0), b2, voffB); PG8_STAGE(PG8_SB(0, 1), b2 + hstep, voffB); PG8_STAGE(PG8_SA(0, 0), a2, voffA);
	s_add_i32 m0, s90, 0x2000
	s_nop 0
	global_load_lds_dwordx4 v134, s[88:89]

; #define PG8_STAGE(bufoff, gbase, voff) do { _Pragma("unroll") for (int _i = 0; _i < 2; ++_i) \
;         __builtin_amdgcn_global_load_lds((const unsigned*)((const char*)(gbase) + (voff)[_i]), (PG8_LAS unsigned*)(lds + (bufoff) + ldsw + _i * 8192), 16, 0, 0); } while (0)
; #define PG8_LDA(dst, b, h) do { _Pragma("unroll") for (int m = 0; m < 4; ++m) _Pragma("unroll") for (int k = 0; k < 2; ++k) dst[m][k] = *(const PG8_LAS bf16x8*)(lds + PG8_SA(b, h) + aoff + m * 2048 + k * 1024); } while (0)
; #define PG8_LDB(dst, b, h) do { _Pragma("unroll") for (int n = 0; n < 2; ++n) _Pragma("unroll") for (int k = 0; k < 2; ++k) dst[n][k] = *(const PG8_LAS bf16x8*)(lds + PG8_SB(b, h) + boff + n * 2048 + k * 1024); } while (0)
; #define PG8_MMA(ai, bj, At, Bt) do { __builtin_amdgcn_s_setprio(1); _Pragma("unroll") for (int m = 0; m < 4; ++m) _Pragma("unroll") for (int n = 0; n < 2; ++n) _Pragma("unroll") for (int k = 0; k < 2; ++k) \
;         acc[ai][bj][m][n] = __builtin_amdgcn_mfma_f32_16x16x32_bf16(Bt[n][k], At[m][k], acc[ai][bj][m][n], 0, 0, 0); __builtin_amdgcn_s_setprio(0); } while (0)
; #define PG8_WAIT_V(n) asm volatile("s_waitcnt vmcnt(" #n ")" ::: "memory")
; #define PG8_WAIT_L(n) asm volatile("s_waitcnt lgkmcnt(" #n ")" ::: "memory")
; #define PG8_BAR __builtin_amdgcn_s_barrier()
; #define PG8_SCHED __builtin_amdgcn_sched_barrier(0)
; template <class Epi, class Sched, bool ALIGN_EPI = false, bool SP2 = false, bool ATILED = false>
; __device__ __forceinline__ void gemm_phase(PG8_LAS unsigned char* lds, const Gemm g, const Sched& S, const Epi& E) {
;     ...
;             PG8_LDA(At, 0, 1); PG8_STAGE(PG8_SB(0, 0), b2, voffB); PG8_STAGE(PG8_SB(0, 1), b2 + hstep, voffB); PG8_STAGE(PG8_SA(0, 0), a2, voffA);
;             PG8_WAIT_V(8); PG8_WAIT_L(0); PG8_BAR; PG8_MMA(1, 0, At, B0); PG8_MMA(1, 1, At, B1); PG8_BAR; PG8_SCHED;
;             PG8_LDB(B0, 1, 0); PG8_LDB(B1, 1, 1); PG8_SCHED; PG8_LDA(At, 1, 0); PG8_STAGE(PG8_SA(0, 1), a2 + hstepA, voffA);
	s_mov_b32 m0, s49
	s_nop 0
	global_load_lds_dwordx4 v128, s[64:65]
	s_mov_b32 m0, s68
	s_nop 0
	global_load_lds_dwordx4 v132, s[64:65]
	s_waitcnt vmcnt(8)
	s_waitcnt lgkmcnt(0)
	s_barrier
	s_setprio 1
	s_waitcnt lgkmcnt(0)
	v_mfma_f32_16x16x32_bf16 v[60:63], v[150:153], v[190:193], 0
	v_mfma_f32_16x16x32_bf16 v[56:59], v[166:169], v[190:193], 0
	v_mfma_f32_16x16x32_bf16 v[44:47], v[150:153], v[200:203], 0
	v_mfma_f32_16x16x32_bf16 v[40:43], v[166:169], v[200:203], 0
	v_mfma_f32_16x16x32_bf16 v[28:31], v[150:153], v[208:211], 0
	v_mfma_f32_16x16x32_bf16 v[24:27], v[166:169], v[208:211], 0
	v_mfma_f32_16x16x32_bf16 v[12:15], v[150:153], v[216:219], 0
	v_mfma_f32_16x16x32_bf16 v[8:11], v[166:169], v[216:219], 0
	v_mfma_f32_16x16x32_bf16 v[60:63], v[162:165], v[194:197], v[60:63]
	v_mfma_f32_16x16x32_bf16 v[56:59], v[170:173], v[194:197], v[56:59]
	v_mfma_f32_16x16x32_bf16 v[44:47], v[162:165], v[204:207], v[44:47]
	v_mfma_f32_16x16x32_bf16 v[40:43], v[170:173], v[204:207], v[40:43]
	v_mfma_f32_16x16x32_bf16 v[28:31], v[162:165], v[212:215], v[28:31]
	v_mfma_f32_16x16x32_bf16 v[24:27], v[170:173], v[212:215], v[24:27]
	v_mfma_f32_16x16x32_bf16 v[12:15], v[162:165], v[220:223], v[12:15]
	v_mfma_f32_16x16x32_bf16 v[8:11], v[170:173], v[220:223], v[8:11]
	s_setprio 0
	s_setprio 1
	v_mfma_f32_16x16x32_bf16 v[52:55], v[174:177], v[190:193], 0
	v_mfma_f32_16x16x32_bf16 v[48:51], v[182:185], v[190:193], 0
	v_mfma_f32_16x16x32_bf16 v[36:39], v[174:177], v[200:203], 0
	v_mfma_f32_16x16x32_bf16 v[32:35], v[182:185], v[200:203], 0
	v_mfma_f32_16x16x32_bf16 v[20:23], v[174:177], v[208:211], 0
	v_mfma_f32_16x16x32_bf16 v[16:19], v[182:185], v[208:211], 0
	v_mfma_f32_16x16x32_bf16 v[4:7], v[174:177], v[216:219], 0
	v_mfma_f32_16x16x32_bf16 v[0:3], v[182:185], v[216:219], 0
	v_mfma_f32_16x16x32_bf16 v[52:55], v[178:181], v[194:197], v[52:55]
	v_mfma_f32_16x16x32_bf16 v[48:51], v[186:189], v[194:197], v[48:51]
	v_mfma_f32_16x16x32_bf16 v[36:39], v[178:181], v[204:207], v[36:39]
	v_mfma_f32_16x16x32_bf16 v[32:35], v[186:189], v[204:207], v[32:35]
	v_mfma_f32_16x16x32_bf16 v[20:23], v[178:181], v[212:215], v[20:23]
	v_mfma_f32_16x16x32_bf16 v[16:19], v[186:189], v[212:215], v[16:19]
	v_mfma_f32_16x16x32_bf16 v[4:7], v[178:181], v[220:223], v[4:7]
	v_mfma_f32_16x16x32_bf16 v[0:3], v[186:189], v[220:223], v[0:3]
	s_setprio 0
	s_barrier
	s_add_i32 s88, 0, 0x18000
	v_add_u32_e32 v136, s88, v155
	s_add_i32 s89, 0, 0x1c000
	ds_read_b128 v[150:153], v136
	ds_read_b128 v[162:165], v136 offset:1024
	ds_read_b128 v[166:169], v136 offset:2048
	ds_read_b128 v[170:173], v136 offset:3072
	v_add_u32_e32 v136, s89, v155
	ds_read_b128 v[174:177], v136
	ds_read_b128 v[178:181], v136 offset:1024
	ds_read_b128 v[182:185], v136 offset:2048
	ds_read_b128 v[186:189], v136 offset:3072
	s_add_u32 s64, s64, 0x40000
	s_addc_u32 s65, s65, 0
	s_mov_b32 m0, s69

; #define PG8_STAGE(bufoff, gbase, voff) do { _Pragma("unroll") for (int _i = 0; _i < 2; ++_i) \
;         __builtin_amdgcn_global_load_lds((const unsigned*)((const char*)(gbase) + (voff)[_i]), (PG8_LAS unsigned*)(lds + (bufoff) + ldsw + _i * 8192), 16, 0, 0); } while (0)
; #define PG8_LDA(dst, b, h) do { _Pragma("unroll") for (int m = 0; m < 4; ++m) _Pragma("unroll") for (int k = 0; k < 2; ++k) dst[m][k] = *(const PG8_LAS bf16x8*)(lds + PG8_SA(b, h) + aoff + m * 2048 + k * 1024); } while (0)
; #define PG8_LDB(dst, b, h) do { _Pragma("unroll") for (int n = 0; n < 2; ++n) _Pragma("unroll") for (int k = 0; k < 2; ++k) dst[n][k] = *(const PG8_LAS bf16x8*)(lds + PG8_SB(b, h) + boff + n * 2048 + k * 1024); } while (0)
; #define PG8_SCHED __builtin_amdgcn_sched_barrier(0)
; template <class Epi, class Sched, bool ALIGN_EPI = false, bool SP2 = false, bool ATILED = false>
; __device__ __forceinline__ void gemm_phase(PG8_LAS unsigned char* lds, const Gemm g, const Sched& S, const Epi& E) {
;     ...
;             PG8_LDB(B0, 1, 0); PG8_LDB(B1, 1, 1); PG8_SCHED; PG8_LDA(At, 1, 0); PG8_STAGE(PG8_SA(0, 1), a2 + hstepA, voffA);
	ds_read_b128 v[190:193], v158 offset:32768
	ds_read_b128 v[194:197], v158 offset:33792
	ds_read_b128 v[200:203], v158 offset:34816
	ds_read_b128 v[204:207], v158 offset:35840
	ds_read_b128 v[208:211], v158 offset:36864
	ds_read_b128 v[212:215], v158 offset:37888
	ds_read_b128 v[216:219], v158 offset:38912
	ds_read_b128 v[220:223], v158 offset:39936
	global_load_lds_dwordx4 v128, s[64:65]

; #define PG8_STAGE(bufoff, gbase, voff) do { _Pragma("unroll") for (int _i = 0; _i < 2; ++_i) \
;         __builtin_amdgcn_global_load_lds((const unsigned*)((const char*)(gbase) + (voff)[_i]), (PG8_LAS unsigned*)(lds + (bufoff) + ldsw + _i * 8192), 16, 0, 0); } while (0)
; #define PG8_LDA(dst, b, h) do { _Pragma("unroll") for (int m = 0; m < 4; ++m) _Pragma("unroll") for (int k = 0; k < 2; ++k) dst[m][k] = *(const PG8_LAS bf16x8*)(lds + PG8_SA(b, h) + aoff + m * 2048 + k * 1024); } while (0)
; #define PG8_LDB(dst, b, h) do { _Pragma("unroll") for (int n = 0; n < 2; ++n) _Pragma("unroll") for (int k = 0; k < 2; ++k) dst[n][k] = *(const PG8_LAS bf16x8*)(lds + PG8_SB(b, h) + boff + n * 2048 + k * 1024); } while (0)
; #define PG8_MMA(ai, bj, At, Bt) do { __builtin_amdgcn_s_setprio(1); _Pragma("unroll") for (int m = 0; m < 4; ++m) _Pragma("unroll") for (int n = 0; n < 2; ++n) _Pragma("unroll") for (int k = 0; k < 2; ++k) \
;         acc[ai][bj][m][n] = __builtin_amdgcn_mfma_f32_16x16x32_bf16(Bt[n][k], At[m][k], acc[ai][bj][m][n], 0, 0, 0); __builtin_amdgcn_s_setprio(0); } while (0)
; #define PG8_WAIT_V(n) asm volatile("s_waitcnt vmcnt(" #n ")" ::: "memory")
; #define PG8_WAIT_L(n) asm volatile("s_waitcnt lgkmcnt(" #n ")" ::: "memory")
; #define PG8_BAR __builtin_amdgcn_s_barrier()
; #define PG8_SCHED __builtin_amdgcn_sched_barrier(0)
; template <class Epi, class Sched, bool ALIGN_EPI = false, bool SP2 = false, bool ATILED = false>
; __device__ __forceinline__ void gemm_phase(PG8_LAS unsigned char* lds, const Gemm g, const Sched& S, const Epi& E) {
;     ...
;             PG8_LDB(B0, 1, 0); PG8_LDB(B1, 1, 1); PG8_SCHED; PG8_LDA(At, 1, 0); PG8_STAGE(PG8_SA(0, 1), a2 + hstepA, voffA);
;             PG8_WAIT_V(8); PG8_WAIT_L(0); PG8_BAR; PG8_MMA(0, 0, At, B0); PG8_MMA(0, 1, At, B1); PG8_BAR; PG8_SCHED;
	s_mov_b32 m0, s70
	s_nop 0
	global_load_lds_dwordx4 v132, s[64:65]
	s_waitcnt vmcnt(8)
	s_waitcnt lgkmcnt(0)
	s_barrier
	s_setprio 1
	s_waitcnt lgkmcnt(0)
	v_mfma_f32_16x16x32_bf16 v[124:127], v[150:153], v[190:193], v[124:127]
	v_mfma_f32_16x16x32_bf16 v[120:123], v[166:169], v[190:193], v[120:123]
	v_mfma_f32_16x16x32_bf16 v[108:111], v[150:153], v[200:203], v[108:111]
	v_mfma_f32_16x16x32_bf16 v[104:107], v[166:169], v[200:203], v[104:107]
	v_mfma_f32_16x16x32_bf16 v[92:95], v[150:153], v[208:211], v[92:95]
	v_mfma_f32_16x16x32_bf16 v[88:91], v[166:169], v[208:211], v[88:91]
	v_mfma_f32_16x16x32_bf16 v[76:79], v[150:153], v[216:219], v[76:79]
	v_mfma_f32_16x16x32_bf16 v[72:75], v[166:169], v[216:219], v[72:75]
	v_mfma_f32_16x16x32_bf16 v[124:127], v[162:165], v[194:197], v[124:127]
	v_mfma_f32_16x16x32_bf16 v[120:123], v[170:173], v[194:197], v[120:123]
	v_mfma_f32_16x16x32_bf16 v[108:111], v[162:165], v[204:207], v[108:111]
	v_mfma_f32_16x16x32_bf16 v[104:107], v[170:173], v[204:207], v[104:107]
	v_mfma_f32_16x16x32_bf16 v[92:95], v[162:165], v[212:215], v[92:95]
	v_mfma_f32_16x16x32_bf16 v[88:91], v[170:173], v[212:215], v[88:91]
	v_mfma_f32_16x16x32_bf16 v[76:79], v[162:165], v[220:223], v[76:79]
	v_mfma_f32_16x16x32_bf16 v[72:75], v[170:173], v[220:223], v[72:75]
	s_setprio 0
	s_setprio 1
	v_mfma_f32_16x16x32_bf16 v[116:119], v[174:177], v[190:193], v[116:119]
	v_mfma_f32_16x16x32_bf16 v[112:115], v[182:185], v[190:193], v[112:115]
	v_mfma_f32_16x16x32_bf16 v[100:103], v[174:177], v[200:203], v[100:103]
	v_mfma_f32_16x16x32_bf16 v[96:99], v[182:185], v[200:203], v[96:99]
	v_mfma_f32_16x16x32_bf16 v[84:87], v[174:177], v[208:211], v[84:87]
	v_mfma_f32_16x16x32_bf16 v[80:83], v[182:185], v[208:211], v[80:83]
	v_mfma_f32_16x16x32_bf16 v[68:71], v[174:177], v[216:219], v[68:71]
	v_mfma_f32_16x16x32_bf16 v[64:67], v[182:185], v[216:219], v[64:67]
	v_mfma_f32_16x16x32_bf16 v[116:119], v[178:181], v[194:197], v[116:119]
	v_mfma_f32_16x16x32_bf16 v[112:115], v[186:189], v[194:197], v[112:115]
	v_mfma_f32_16x16x32_bf16 v[100:103], v[178:181], v[204:207], v[100:103]
	v_mfma_f32_16x16x32_bf16 v[96:99], v[186:189], v[204:207], v[96:99]
	v_mfma_f32_16x16x32_bf16 v[84:87], v[178:181], v[212:215], v[84:87]
	v_mfma_f32_16x16x32_bf16 v[80:83], v[186:189], v[212:215], v[80:83]
	v_mfma_f32_16x16x32_bf16 v[68:71], v[178:181], v[220:223], v[68:71]
	v_mfma_f32_16x16x32_bf16 v[64:67], v[186:189], v[220:223], v[64:67]
	s_setprio 0
	s_barrier
	s_add_i32 s64, s88, s66

; #define PG8_STAGE(bufoff, gbase, voff) do { _Pragma("unroll") for (int _i = 0; _i < 2; ++_i) \
;         __builtin_amdgcn_global_load_lds((const unsigned*)((const char*)(gbase) + (voff)[_i]), (PG8_LAS unsigned*)(lds + (bufoff) + ldsw + _i * 8192), 16, 0, 0); } while (0)
; #define PG8_LDA(dst, b, h) do { _Pragma("unroll") for (int m = 0; m < 4; ++m) _Pragma("unroll") for (int k = 0; k < 2; ++k) dst[m][k] = *(const PG8_LAS bf16x8*)(lds + PG8_SA(b, h) + aoff + m * 2048 + k * 1024); } while (0)
; template <class Epi, class Sched, bool ALIGN_EPI = false, bool SP2 = false, bool ATILED = false>
; __device__ __forceinline__ void gemm_phase(PG8_LAS unsigned char* lds, const Gemm g, const Sched& S, const Epi& E) {
;     ...
;             PG8_LDA(At, 1, 1); PG8_STAGE(PG8_SB(1, 0), b3, voffB); PG8_STAGE(PG8_SB(1, 1), b3 + hstep, voffB); PG8_STAGE(PG8_SA(1, 0), a3, voffA);
	s_mov_b32 m0, s64
	ds_read_b128 v[190:193], v158 offset:49152
	ds_read_b128 v[194:197], v158 offset:50176
	ds_read_b128 v[200:203], v158 offset:51200
	ds_read_b128 v[204:207], v158 offset:52224
	ds_read_b128 v[208:211], v158 offset:53248
	ds_read_b128 v[212:215], v158 offset:54272
	ds_read_b128 v[216:219], v158 offset:55296
	ds_read_b128 v[220:223], v158 offset:56320
	global_load_lds_dwordx4 v130, s[98:99]
	s_add_i32 m0, s64, 0x2000
	s_add_u32 s62, s62, 0x40080

; #define PG8_STAGE(bufoff, gbase, voff) do { _Pragma("unroll") for (int _i = 0; _i < 2; ++_i) \
;         __builtin_amdgcn_global_load_lds((const unsigned*)((const char*)(gbase) + (voff)[_i]), (PG8_LAS unsigned*)(lds + (bufoff) + ldsw + _i * 8192), 16, 0, 0); } while (0)
; #define PG8_LDA(dst, b, h) do { _Pragma("unroll") for (int m = 0; m < 4; ++m) _Pragma("unroll") for (int k = 0; k < 2; ++k) dst[m][k] = *(const PG8_LAS bf16x8*)(lds + PG8_SA(b, h) + aoff + m * 2048 + k * 1024); } while (0)
; template <class Epi, class Sched, bool ALIGN_EPI = false, bool SP2 = false, bool ATILED = false>
; __device__ __forceinline__ void gemm_phase(PG8_LAS unsigned char* lds, const Gemm g, const Sched& S, const Epi& E) {
;     ...
;             PG8_LDA(At, 1, 1); PG8_STAGE(PG8_SB(1, 0), b3, voffB); PG8_STAGE(PG8_SB(1, 1), b3 + hstep, voffB); PG8_STAGE(PG8_SA(1, 0), a3, voffA);
	s_addc_u32 s63, s63, 0
	s_add_i32 s64, s89, s66
	global_load_lds_dwordx4 v134, s[98:99]

; #define PG8_STAGE(bufoff, gbase, voff) do { _Pragma("unroll") for (int _i = 0; _i < 2; ++_i) \
;         __builtin_amdgcn_global_load_lds((const unsigned*)((const char*)(gbase) + (voff)[_i]), (PG8_LAS unsigned*)(lds + (bufoff) + ldsw + _i * 8192), 16, 0, 0); } while (0)
; #define PG8_LDA(dst, b, h) do { _Pragma("unroll") for (int m = 0; m < 4; ++m) _Pragma("unroll") for (int k = 0; k < 2; ++k) dst[m][k] = *(const PG8_LAS bf16x8*)(lds + PG8_SA(b, h) + aoff + m * 2048 + k * 1024); } while (0)
; template <class Epi, class Sched, bool ALIGN_EPI = false, bool SP2 = false, bool ATILED = false>
; __device__ __forceinline__ void gemm_phase(PG8_LAS unsigned char* lds, const Gemm g, const Sched& S, const Epi& E) {
;     ...
;             PG8_LDA(At, 1, 1); PG8_STAGE(PG8_SB(1, 0), b3, voffB); PG8_STAGE(PG8_SB(1, 1), b3 + hstep, voffB); PG8_STAGE(PG8_SA(1, 0), a3, voffA);
	s_mov_b32 m0, s64
	s_nop 0
	global_load_lds_dwordx4 v130, s[62:63]

; #define PG8_STAGE(bufoff, gbase, voff) do { _Pragma("unroll") for (int _i = 0; _i < 2; ++_i) \
;         __builtin_amdgcn_global_load_lds((const unsigned*)((const char*)(gbase) + (voff)[_i]), (PG8_LAS unsigned*)(lds + (bufoff) + ldsw + _i * 8192), 16, 0, 0); } while (0)
; #define PG8_LDA(dst, b, h) do { _Pragma("unroll") for (int m = 0; m < 4; ++m) _Pragma("unroll") for (int k = 0; k < 2; ++k) dst[m][k] = *(const PG8_LAS bf16x8*)(lds + PG8_SA(b, h) + aoff + m * 2048 + k * 1024); } while (0)
; template <class Epi, class Sched, bool ALIGN_EPI = false, bool SP2 = false, bool ATILED = false>
; __device__ __forceinline__ void gemm_phase(PG8_LAS unsigned char* lds, const Gemm g, const Sched& S, const Epi& E) {
;     ...
;             PG8_LDA(At, 1, 1); PG8_STAGE(PG8_SB(1, 0), b3, voffB); PG8_STAGE(PG8_SB(1, 1), b3 + hstep, voffB); PG8_STAGE(PG8_SA(1, 0), a3, voffA);
	s_add_i32 m0, s64, 0x2000
	s_nop 0
	global_load_lds_dwordx4 v134, s[62:63]

; #define PG8_STAGE(bufoff, gbase, voff) do { _Pragma("unroll") for (int _i = 0; _i < 2; ++_i) \
;         __builtin_amdgcn_global_load_lds((const unsigned*)((const char*)(gbase) + (voff)[_i]), (PG8_LAS unsigned*)(lds + (bufoff) + ldsw + _i * 8192), 16, 0, 0); } while (0)
; #define PG8_LDA(dst, b, h) do { _Pragma("unroll") for (int m = 0; m < 4; ++m) _Pragma("unroll") for (int k = 0; k < 2; ++k) dst[m][k] = *(const PG8_LAS bf16x8*)(lds + PG8_SA(b, h) + aoff + m * 2048 + k * 1024); } while (0)
; template <class Epi, class Sched, bool ALIGN_EPI = false, bool SP2 = false, bool ATILED = false>
; __device__ __forceinline__ void gemm_phase(PG8_LAS unsigned char* lds, const Gemm g, const Sched& S, const Epi& E) {
;     ...
;             PG8_LDA(At, 1, 1); PG8_STAGE(PG8_SB(1, 0), b3, voffB); PG8_STAGE(PG8_SB(1, 1), b3 + hstep, voffB); PG8_STAGE(PG8_SA(1, 0), a3, voffA);
	s_mov_b32 m0, s76
	s_nop 0
	global_load_lds_dwordx4 v128, s[100:101]

; #define PG8_STAGE(bufoff, gbase, voff) do { _Pragma("unroll") for (int _i = 0; _i < 2; ++_i) \
;         __builtin_amdgcn_global_load_lds((const unsigned*)((const char*)(gbase) + (voff)[_i]), (PG8_LAS unsigned*)(lds + (bufoff) + ldsw + _i * 8192), 16, 0, 0); } while (0)
; #define PG8_LDA(dst, b, h) do { _Pragma("unroll") for (int m = 0; m < 4; ++m) _Pragma("unroll") for (int k = 0; k < 2; ++k) dst[m][k] = *(const PG8_LAS bf16x8*)(lds + PG8_SA(b, h) + aoff + m * 2048 + k * 1024); } while (0)
; #define PG8_MMA(ai, bj, At, Bt) do { __builtin_amdgcn_s_setprio(1); _Pragma("unroll") for (int m = 0; m < 4; ++m) _Pragma("unroll") for (int n = 0; n < 2; ++n) _Pragma("unroll") for (int k = 0; k < 2; ++k) \
;         acc[ai][bj][m][n] = __builtin_amdgcn_mfma_f32_16x16x32_bf16(Bt[n][k], At[m][k], acc[ai][bj][m][n], 0, 0, 0); __builtin_amdgcn_s_setprio(0); } while (0)
; #define PG8_WAIT_V(n) asm volatile("s_waitcnt vmcnt(" #n ")" ::: "memory")
; #define PG8_WAIT_L(n) asm volatile("s_waitcnt lgkmcnt(" #n ")" ::: "memory")
; #define PG8_BAR __builtin_amdgcn_s_barrier()
; #define PG8_SCHED __builtin_amdgcn_sched_barrier(0)
; template <class Epi, class Sched, bool ALIGN_EPI = false, bool SP2 = false, bool ATILED = false>
; __device__ __forceinline__ void gemm_phase(PG8_LAS unsigned char* lds, const Gemm g, const Sched& S, const Epi& E) {
;     ...
;             PG8_LDA(At, 1, 1); PG8_STAGE(PG8_SB(1, 0), b3, voffB); PG8_STAGE(PG8_SB(1, 1), b3 + hstep, voffB); PG8_STAGE(PG8_SA(1, 0), a3, voffA);
;             PG8_WAIT_V(8); PG8_WAIT_L(0); PG8_BAR; PG8_MMA(1, 0, At, B0); PG8_MMA(1, 1, At, B1); PG8_BAR; PG8_SCHED;
	s_mov_b32 m0, s77
	s_nop 0
	global_load_lds_dwordx4 v132, s[100:101]
	s_waitcnt vmcnt(8)
	s_waitcnt lgkmcnt(0)
	s_barrier
	s_setprio 1
	s_waitcnt lgkmcnt(0)
	v_mfma_f32_16x16x32_bf16 v[60:63], v[150:153], v[190:193], v[60:63]
	v_mfma_f32_16x16x32_bf16 v[56:59], v[166:169], v[190:193], v[56:59]
	v_mfma_f32_16x16x32_bf16 v[44:47], v[150:153], v[200:203], v[44:47]
	v_mfma_f32_16x16x32_bf16 v[40:43], v[166:169], v[200:203], v[40:43]
	v_mfma_f32_16x16x32_bf16 v[28:31], v[150:153], v[208:211], v[28:31]
	v_mfma_f32_16x16x32_bf16 v[24:27], v[166:169], v[208:211], v[24:27]
	v_mfma_f32_16x16x32_bf16 v[12:15], v[150:153], v[216:219], v[12:15]
	v_mfma_f32_16x16x32_bf16 v[8:11], v[166:169], v[216:219], v[8:11]
	v_mfma_f32_16x16x32_bf16 v[60:63], v[162:165], v[194:197], v[60:63]
	v_mfma_f32_16x16x32_bf16 v[56:59], v[170:173], v[194:197], v[56:59]
	v_mfma_f32_16x16x32_bf16 v[44:47], v[162:165], v[204:207], v[44:47]
	v_mfma_f32_16x16x32_bf16 v[40:43], v[170:173], v[204:207], v[40:43]
	v_mfma_f32_16x16x32_bf16 v[28:31], v[162:165], v[212:215], v[28:31]
	v_mfma_f32_16x16x32_bf16 v[24:27], v[170:173], v[212:215], v[24:27]
	v_mfma_f32_16x16x32_bf16 v[12:15], v[162:165], v[220:223], v[12:15]
	v_mfma_f32_16x16x32_bf16 v[8:11], v[170:173], v[220:223], v[8:11]
	s_setprio 0
	s_setprio 1
	v_mfma_f32_16x16x32_bf16 v[52:55], v[174:177], v[190:193], v[52:55]
	v_mfma_f32_16x16x32_bf16 v[48:51], v[182:185], v[190:193], v[48:51]
	v_mfma_f32_16x16x32_bf16 v[36:39], v[174:177], v[200:203], v[36:39]
	v_mfma_f32_16x16x32_bf16 v[32:35], v[182:185], v[200:203], v[32:35]
	v_mfma_f32_16x16x32_bf16 v[20:23], v[174:177], v[208:211], v[20:23]
	v_mfma_f32_16x16x32_bf16 v[16:19], v[182:185], v[208:211], v[16:19]
	v_mfma_f32_16x16x32_bf16 v[4:7], v[174:177], v[216:219], v[4:7]
	v_mfma_f32_16x16x32_bf16 v[0:3], v[182:185], v[216:219], v[0:3]
	v_mfma_f32_16x16x32_bf16 v[52:55], v[178:181], v[194:197], v[52:55]
	v_mfma_f32_16x16x32_bf16 v[48:51], v[186:189], v[194:197], v[48:51]
	v_mfma_f32_16x16x32_bf16 v[36:39], v[178:181], v[204:207], v[36:39]
	v_mfma_f32_16x16x32_bf16 v[32:35], v[186:189], v[204:207], v[32:35]
	v_mfma_f32_16x16x32_bf16 v[20:23], v[178:181], v[212:215], v[20:23]
	v_mfma_f32_16x16x32_bf16 v[16:19], v[186:189], v[212:215], v[16:19]
	v_mfma_f32_16x16x32_bf16 v[4:7], v[178:181], v[220:223], v[4:7]
	v_mfma_f32_16x16x32_bf16 v[0:3], v[186:189], v[220:223], v[0:3]
	s_setprio 0
	s_barrier
	s_add_i32 s87, s87, 2
	s_add_u32 s60, s60, 0x100
	s_addc_u32 s61, s61, 0
	s_add_u32 s85, s85, 0x100
	s_addc_u32 s86, s86, 0
	s_cmp_gt_u32 s87, 13

; __device__ __forceinline__ void rows_rstd(const float* ssq, int row0, int fq, float (&rs)[2][4]) {
;     f32x4 p[2][4];
; #pragma unroll
;     for (int ai = 0; ai < 2; ++ai)
; #pragma unroll
;         for (int m = 0; m < 4; ++m) p[ai][m] = *(const f32x4*)(ssq + (size_t)(row0 + ai * HALF + m * 16) * 16 + 4 * fq);
; #pragma unroll
;     for (int ai = 0; ai < 2; ++ai)
; #pragma unroll
;         for (int m = 0; m < 4; ++m) { float s = (p[ai][m][0] + p[ai][m][1]) + (p[ai][m][2] + p[ai][m][3]); s += __shfl_xor(s, 16); s += __shfl_xor(s, 32); rs[ai][m] = __builtin_amdgcn_rsqf(s * (1.0f / (float)DM) + RMS_EPS); }
; }
;     __device__ __forceinline__ void operator()(const f32x4 (&acc)[2][2][4][2], const Unit& u, int wr, int wc, int fr, int fq) const {
;         const int row0 = u.pm * BM + wr * 64 + fr, col0 = u.pn * HALF + wc * 32 + 8 * fq;
;         float rsv[2][4]; rows_rstd(ssq, row0, fq, rsv);
; #pragma unroll
;         for (int ai = 0; ai < 2; ++ai)
; #pragma unroll
;             for (int m = 0; m < 4; ++m) {
;                 const int row = row0 + ai * HALF + m * 16; const float rs = rsv[ai][m], cexp = -1.4426950408889634f * rs, rs2 = rs * rs;
;                 const f32x4 g0 = acc[ai][0][m][0], g1 = acc[ai][0][m][1], u0 = acc[ai][1][m][0], u1 = acc[ai][1][m][1];
;                 const f32x4 t0 = g0 * cexp, t1 = g1 * cexp;
;                 f32x4 d0 = (f32x4){__builtin_amdgcn_exp2f(t0[0]), __builtin_amdgcn_exp2f(t0[1]), __builtin_amdgcn_exp2f(t0[2]), __builtin_amdgcn_exp2f(t0[3])} + 1.0f;
;                 f32x4 d1 = (f32x4){__builtin_amdgcn_exp2f(t1[0]), __builtin_amdgcn_exp2f(t1[1]), __builtin_amdgcn_exp2f(t1[2]), __builtin_amdgcn_exp2f(t1[3])} + 1.0f;
;                 const f32x4 r0 = (f32x4){__builtin_amdgcn_rcpf(d0[0]), __builtin_amdgcn_rcpf(d0[1]), __builtin_amdgcn_rcpf(d0[2]), __builtin_amdgcn_rcpf(d0[3])} * rs2;
;                 const f32x4 r1 = (f32x4){__builtin_amdgcn_rcpf(d1[0]), __builtin_amdgcn_rcpf(d1[1]), __builtin_amdgcn_rcpf(d1[2]), __builtin_amdgcn_rcpf(d1[3])} * rs2;
;                 const f32x4 a0 = (g0 * u0) * r0, a1 = (g1 * u1) * r1;
;                 u32x4 w; w.x = cvt_pk_bf16(a0[0], a0[1]); w.y = cvt_pk_bf16(a0[2], a0[3]); w.z = cvt_pk_bf16(a1[0], a1[1]); w.w = cvt_pk_bf16(a1[2], a1[3]);
;                 *(u32x4*)(O + (((size_t)(row >> 8) * (DFF / BK) + (col0 >> 6)) * BM + (row & 255)) * BK + (col0 & 63)) = w;
.Lalign2_skip0:
	s_waitcnt vmcnt(0)
	v_mov_b32_e32 v194, v163
	v_mov_b32_e32 v195, v164
	v_mov_b32_e32 v163, v165
	v_pk_add_f32 v[162:163], v[194:195], v[162:163]
	v_mov_b32_e32 v164, v167
	v_mov_b32_e32 v165, v168
	v_mov_b32_e32 v167, v169
	v_add_f32_e32 v151, v162, v163
	v_pk_add_f32 v[162:163], v[164:165], v[166:167]
	v_mov_b32_e32 v168, v171
	v_mov_b32_e32 v169, v172
	v_mov_b32_e32 v171, v173
	v_mov_b32_e32 v172, v175
	v_mov_b32_e32 v173, v176
	v_mov_b32_e32 v175, v177
	v_mov_b32_e32 v176, v179
	v_mov_b32_e32 v177, v180
	v_mov_b32_e32 v179, v181
	v_pk_add_f32 v[164:165], v[168:169], v[170:171]
	v_pk_add_f32 v[166:167], v[172:173], v[174:175]
	ds_bpermute_b32 v153, v136, v151
	v_add_f32_e32 v161, v162, v163
	v_pk_add_f32 v[168:169], v[176:177], v[178:179]
	v_add_f32_e32 v162, v164, v165
	v_add_f32_e32 v163, v166, v167
	ds_bpermute_b32 v166, v136, v161
	v_add_f32_e32 v164, v168, v169
	ds_bpermute_b32 v167, v136, v162
	ds_bpermute_b32 v168, v136, v163
	ds_bpermute_b32 v169, v136, v164
	s_waitcnt lgkmcnt(4)
	v_add_f32_e32 v151, v151, v153
	ds_bpermute_b32 v153, v149, v151
	s_waitcnt lgkmcnt(4)
	v_add_f32_e32 v161, v161, v166
	s_waitcnt lgkmcnt(3)
	v_add_f32_e32 v162, v162, v167
	s_waitcnt lgkmcnt(2)
	v_add_f32_e32 v163, v163, v168
	ds_bpermute_b32 v166, v149, v161
	v_mov_b32_e32 v180, v183
	v_mov_b32_e32 v181, v184
	v_mov_b32_e32 v183, v185
	s_waitcnt lgkmcnt(2)
	v_add_f32_e32 v164, v164, v169
	ds_bpermute_b32 v167, v149, v162
	ds_bpermute_b32 v168, v149, v163
	v_pk_add_f32 v[170:171], v[180:181], v[182:183]
	ds_bpermute_b32 v169, v149, v164
	v_add_f32_e32 v165, v170, v171
	ds_bpermute_b32 v170, v136, v165
	s_waitcnt lgkmcnt(5)
	v_add_f32_e32 v151, v151, v153
	v_fmamk_f32 v232, v151, 0x3a800000, v160
	v_mov_b32_e32 v233, v232
	s_waitcnt lgkmcnt(4)
	v_add_f32_e32 v153, v161, v166
	s_waitcnt lgkmcnt(3)
	v_add_f32_e32 v161, v162, v167
	s_waitcnt lgkmcnt(2)
	v_add_f32_e32 v162, v163, v168
	v_rsq_f32_e32 v166, v232
	v_fmamk_f32 v234, v153, 0x3a800000, v160
	v_mov_b32_e32 v235, v234
	v_fmamk_f32 v238, v161, 0x3a800000, v160
	v_mov_b32_e32 v239, v238
	v_fmamk_f32 v240, v162, 0x3a800000, v160
	v_mov_b32_e32 v241, v240
	v_rsq_f32_e32 v172, v234
	s_waitcnt lgkmcnt(1)
	v_add_f32_e32 v151, v164, v169
	v_mov_b32_e32 v162, v187
	v_mov_b32_e32 v163, v188
	v_mov_b32_e32 v187, v189
	v_fmamk_f32 v236, v151, 0x3a800000, v160
	v_mov_b32_e32 v237, v236
	v_pk_add_f32 v[162:163], v[162:163], v[186:187]
	v_rsq_f32_e32 v173, v236
	s_waitcnt lgkmcnt(0)
	v_add_f32_e32 v151, v165, v170
	v_add_f32_e32 v165, v162, v163
	v_mov_b32_e32 v162, v191
	v_mov_b32_e32 v163, v192
	v_mov_b32_e32 v191, v193
	v_pk_add_f32 v[162:163], v[162:163], v[190:191]
	ds_bpermute_b32 v167, v136, v165
	v_add_f32_e32 v162, v162, v163
	ds_bpermute_b32 v136, v136, v162
	ds_bpermute_b32 v164, v149, v151
	v_rsq_f32_e32 v153, v238
	s_waitcnt lgkmcnt(2)
	v_add_f32_e32 v163, v165, v167
	v_rsq_f32_e32 v161, v240
	s_waitcnt lgkmcnt(1)
	v_add_f32_e32 v136, v162, v136
	s_waitcnt lgkmcnt(0)
	v_add_f32_e32 v151, v151, v164
	ds_bpermute_b32 v164, v149, v163
	ds_bpermute_b32 v149, v149, v136
	v_fmamk_f32 v242, v151, 0x3a800000, v160
	v_mov_b32_e32 v243, v242
	v_rsq_f32_e32 v174, v242
	s_waitcnt lgkmcnt(1)
	v_add_f32_e32 v151, v163, v164
	s_waitcnt lgkmcnt(0)
	v_add_f32_e32 v136, v136, v149
	v_fmamk_f32 v244, v151, 0x3a800000, v160
	v_mov_b32_e32 v245, v244
	v_fmamk_f32 v246, v136, 0x3a800000, v160
	v_mov_b32_e32 v247, v246
	v_rsq_f32_e32 v175, v244
	v_rsq_f32_e32 v151, v246
	v_mul_f32_e32 v136, 0xbfb8aa3b, v166
	v_pk_mul_f32 v[166:167], v[124:125], v[136:137] op_sel_hi:[1,0]
	v_pk_mul_f32 v[164:165], v[126:127], v[136:137] op_sel_hi:[1,0]
	v_pk_mul_f32 v[168:169], v[122:123], v[136:137] op_sel_hi:[1,0]
	v_pk_mul_f32 v[170:171], v[120:121], v[136:137] op_sel_hi:[1,0]
	v_exp_f32_e32 v166, v166
	v_exp_f32_e32 v167, v167
	v_exp_f32_e32 v164, v164
	v_exp_f32_e32 v165, v165
	v_exp_f32_e32 v170, v170
	v_exp_f32_e32 v168, v168
	v_exp_f32_e32 v169, v169
	v_exp_f32_e32 v171, v171
	v_pk_fma_f32 v[166:167], v[166:167], v[232:233], v[232:233]
	v_pk_fma_f32 v[164:165], v[164:165], v[232:233], v[232:233]
	v_pk_fma_f32 v[168:169], v[168:169], v[232:233], v[232:233]
	v_pk_fma_f32 v[170:171], v[170:171], v[232:233], v[232:233]
	v_rcp_f32_e32 v166, v166
	v_rcp_f32_e32 v167, v167
	v_rcp_f32_e32 v164, v164
	v_rcp_f32_e32 v165, v165
	v_rcp_f32_e32 v170, v170
	v_rcp_f32_e32 v171, v171
	v_rcp_f32_e32 v168, v168
	v_rcp_f32_e32 v169, v169
	s_nop 0
	v_pk_mul_f32 v[116:117], v[116:117], v[166:167]
	v_pk_mul_f32 v[120:121], v[114:115], v[168:169]
	v_pk_mul_f32 v[114:115], v[112:113], v[170:171]
	v_cvt_pk_bf16_f32 v112, v116, v117
	v_lshlrev_b32_e32 v116, 7, v152
	v_and_b32_e32 v136, 0x6780, v116
	v_pk_mul_f32 v[118:119], v[118:119], v[164:165]
	v_lshl_add_u64 v[116:117], s[60:61], 0, v[136:137]
	v_mov_b32_e32 v149, v137
	v_cvt_pk_bf16_f32 v113, v118, v119
	v_cvt_pk_bf16_f32 v114, v114, v115
	v_cvt_pk_bf16_f32 v115, v120, v121
	v_lshl_add_u64 v[116:117], v[116:117], 0, v[148:149]
	global_store_dwordx4 v[116:117], v[112:115], off
	s_nop 1
	v_mul_f32_e32 v112, 0xbfb8aa3b, v172
	v_pk_mul_f32 v[118:119], v[110:111], v[112:113] op_sel_hi:[1,0]
	v_pk_mul_f32 v[120:121], v[108:109], v[112:113] op_sel_hi:[1,0]
	v_pk_mul_f32 v[122:123], v[106:107], v[112:113] op_sel_hi:[1,0]
	v_pk_mul_f32 v[112:113], v[104:105], v[112:113] op_sel_hi:[1,0]
	v_exp_f32_e32 v120, v120
	v_exp_f32_e32 v121, v121
	v_exp_f32_e32 v118, v118
	v_exp_f32_e32 v119, v119
	v_exp_f32_e32 v112, v112
	v_exp_f32_e32 v122, v122
	v_exp_f32_e32 v123, v123
	v_exp_f32_e32 v113, v113
	v_pk_fma_f32 v[118:119], v[118:119], v[234:235], v[234:235]
	v_pk_fma_f32 v[120:121], v[120:121], v[234:235], v[234:235]
; __device__ __forceinline__ unsigned cvt_pk_bf16(float lo, float hi) { typedef float f2 __attribute__((ext_vector_type(2))); const bf16v2 r = __builtin_convertvector((f2){lo, hi}, bf16v2); return __builtin_bit_cast(unsigned, r); }
;     __device__ __forceinline__ void operator()(const f32x4 (&acc)[2][2][4][2], const Unit& u, int wr, int wc, int fr, int fq) const {
;     ...
;                 const int row = row0 + ai * HALF + m * 16; const float rs = rsv[ai][m], cexp = -1.4426950408889634f * rs, rs2 = rs * rs;
;                 const f32x4 g0 = acc[ai][0][m][0], g1 = acc[ai][0][m][1], u0 = acc[ai][1][m][0], u1 = acc[ai][1][m][1];
;                 const f32x4 t0 = g0 * cexp, t1 = g1 * cexp;
;                 f32x4 d0 = (f32x4){__builtin_amdgcn_exp2f(t0[0]), __builtin_amdgcn_exp2f(t0[1]), __builtin_amdgcn_exp2f(t0[2]), __builtin_amdgcn_exp2f(t0[3])} + 1.0f;
;                 f32x4 d1 = (f32x4){__builtin_amdgcn_exp2f(t1[0]), __builtin_amdgcn_exp2f(t1[1]), __builtin_amdgcn_exp2f(t1[2]), __builtin_amdgcn_exp2f(t1[3])} + 1.0f;
;                 const f32x4 r0 = (f32x4){__builtin_amdgcn_rcpf(d0[0]), __builtin_amdgcn_rcpf(d0[1]), __builtin_amdgcn_rcpf(d0[2]), __builtin_amdgcn_rcpf(d0[3])} * rs2;
;                 const f32x4 r1 = (f32x4){__builtin_amdgcn_rcpf(d1[0]), __builtin_amdgcn_rcpf(d1[1]), __builtin_amdgcn_rcpf(d1[2]), __builtin_amdgcn_rcpf(d1[3])} * rs2;
;                 const f32x4 a0 = (g0 * u0) * r0, a1 = (g1 * u1) * r1;
;                 u32x4 w; w.x = cvt_pk_bf16(a0[0], a0[1]); w.y = cvt_pk_bf16(a0[2], a0[3]); w.z = cvt_pk_bf16(a1[0], a1[1]); w.w = cvt_pk_bf16(a1[2], a1[3]);
;                 *(u32x4*)(O + (((size_t)(row >> 8) * (DFF / BK) + (col0 >> 6)) * BM + (row & 255)) * BK + (col0 & 63)) = w;
	v_pk_fma_f32 v[122:123], v[122:123], v[234:235], v[234:235]
	v_pk_fma_f32 v[112:113], v[112:113], v[234:235], v[234:235]
	v_rcp_f32_e32 v120, v120
	v_rcp_f32_e32 v121, v121
	v_rcp_f32_e32 v118, v118
	v_rcp_f32_e32 v119, v119
	v_rcp_f32_e32 v112, v112
	v_rcp_f32_e32 v113, v113
	v_rcp_f32_e32 v122, v122
	v_rcp_f32_e32 v123, v123
	s_nop 0
	v_pk_mul_f32 v[102:103], v[102:103], v[118:119]
	v_pk_mul_f32 v[100:101], v[100:101], v[120:121]
	v_pk_mul_f32 v[104:105], v[98:99], v[122:123]
	v_pk_mul_f32 v[98:99], v[96:97], v[112:113]
	v_cvt_pk_bf16_f32 v96, v100, v101
	v_cvt_pk_bf16_f32 v97, v102, v103
	v_cvt_pk_bf16_f32 v98, v98, v99
	v_cvt_pk_bf16_f32 v99, v104, v105
	global_store_dwordx4 v[116:117], v[96:99], off offset:2048
	s_nop 1
	v_mul_f32_e32 v96, 0xbfb8aa3b, v153
	v_pk_mul_f32 v[102:103], v[92:93], v[96:97] op_sel_hi:[1,0]
	v_pk_mul_f32 v[100:101], v[94:95], v[96:97] op_sel_hi:[1,0]
	v_pk_mul_f32 v[104:105], v[90:91], v[96:97] op_sel_hi:[1,0]
	v_pk_mul_f32 v[96:97], v[88:89], v[96:97] op_sel_hi:[1,0]
	v_exp_f32_e32 v102, v102
	v_exp_f32_e32 v103, v103
	v_exp_f32_e32 v100, v100
	v_exp_f32_e32 v101, v101
	v_exp_f32_e32 v96, v96
	v_exp_f32_e32 v104, v104
	v_exp_f32_e32 v105, v105
	v_exp_f32_e32 v97, v97
	v_pk_fma_f32 v[102:103], v[102:103], v[238:239], v[238:239]
	v_pk_fma_f32 v[100:101], v[100:101], v[238:239], v[238:239]
	v_pk_fma_f32 v[104:105], v[104:105], v[238:239], v[238:239]
	v_pk_fma_f32 v[96:97], v[96:97], v[238:239], v[238:239]
	v_rcp_f32_e32 v102, v102
	v_rcp_f32_e32 v103, v103
	v_rcp_f32_e32 v100, v100
	v_rcp_f32_e32 v101, v101
	v_rcp_f32_e32 v96, v96
	v_rcp_f32_e32 v97, v97
	v_rcp_f32_e32 v104, v104
	v_rcp_f32_e32 v105, v105
	s_nop 0
	v_pk_mul_f32 v[84:85], v[84:85], v[102:103]
	v_pk_mul_f32 v[86:87], v[86:87], v[100:101]
	v_pk_mul_f32 v[88:89], v[82:83], v[104:105]
	v_pk_mul_f32 v[82:83], v[80:81], v[96:97]
	v_cvt_pk_bf16_f32 v80, v84, v85
	v_add_co_u32_e32 v84, vcc, s80, v116
	v_cvt_pk_bf16_f32 v81, v86, v87
	v_cvt_pk_bf16_f32 v82, v82, v83
	v_cvt_pk_bf16_f32 v83, v88, v89
	v_addc_co_u32_e32 v85, vcc, 0, v117, vcc
	global_store_dwordx4 v[84:85], v[80:83], off
	s_nop 1
	v_mul_f32_e32 v80, 0xbfb8aa3b, v161
	v_pk_mul_f32 v[86:87], v[78:79], v[80:81] op_sel_hi:[1,0]
	v_pk_mul_f32 v[88:89], v[76:77], v[80:81] op_sel_hi:[1,0]
	v_pk_mul_f32 v[90:91], v[74:75], v[80:81] op_sel_hi:[1,0]
	v_pk_mul_f32 v[80:81], v[72:73], v[80:81] op_sel_hi:[1,0]
	v_exp_f32_e32 v88, v88
	v_exp_f32_e32 v89, v89
	v_exp_f32_e32 v86, v86
	v_exp_f32_e32 v87, v87
	v_exp_f32_e32 v80, v80
	v_exp_f32_e32 v90, v90
	v_exp_f32_e32 v91, v91
	v_exp_f32_e32 v81, v81
	v_pk_fma_f32 v[86:87], v[86:87], v[240:241], v[240:241]
	v_pk_fma_f32 v[88:89], v[88:89], v[240:241], v[240:241]
	v_pk_fma_f32 v[90:91], v[90:91], v[240:241], v[240:241]
	v_pk_fma_f32 v[80:81], v[80:81], v[240:241], v[240:241]
	v_rcp_f32_e32 v88, v88
	v_rcp_f32_e32 v89, v89
	v_rcp_f32_e32 v86, v86
	v_rcp_f32_e32 v87, v87
	v_rcp_f32_e32 v80, v80
	v_rcp_f32_e32 v81, v81
	v_rcp_f32_e32 v90, v90
	v_rcp_f32_e32 v91, v91
	s_nop 0
	v_pk_mul_f32 v[70:71], v[70:71], v[86:87]
	v_pk_mul_f32 v[68:69], v[68:69], v[88:89]
	v_pk_mul_f32 v[72:73], v[66:67], v[90:91]
	v_pk_mul_f32 v[66:67], v[64:65], v[80:81]
	v_cvt_pk_bf16_f32 v64, v68, v69
	v_cvt_pk_bf16_f32 v65, v70, v71
	v_cvt_pk_bf16_f32 v66, v66, v67
	v_cvt_pk_bf16_f32 v67, v72, v73
	global_store_dwordx4 v[84:85], v[64:67], off offset:2048
	s_nop 1
	v_mul_f32_e32 v66, 0xbfb8aa3b, v173
	v_pk_mul_f32 v[70:71], v[62:63], v[66:67] op_sel_hi:[1,0]
	v_pk_mul_f32 v[72:73], v[60:61], v[66:67] op_sel_hi:[1,0]
	v_pk_mul_f32 v[74:75], v[58:59], v[66:67] op_sel_hi:[1,0]
	v_pk_mul_f32 v[66:67], v[56:57], v[66:67] op_sel_hi:[1,0]
	v_exp_f32_e32 v70, v70
	v_exp_f32_e32 v71, v71
	v_exp_f32_e32 v72, v72
	v_exp_f32_e32 v73, v73
	v_exp_f32_e32 v66, v66
	v_exp_f32_e32 v74, v74
	v_exp_f32_e32 v75, v75
	v_exp_f32_e32 v67, v67
	v_pk_fma_f32 v[70:71], v[70:71], v[236:237], v[236:237]
	v_pk_fma_f32 v[72:73], v[72:73], v[236:237], v[236:237]
	v_pk_fma_f32 v[74:75], v[74:75], v[236:237], v[236:237]
	v_pk_fma_f32 v[66:67], v[66:67], v[236:237], v[236:237]
	v_rcp_f32_e32 v70, v70
	v_rcp_f32_e32 v71, v71
	v_rcp_f32_e32 v72, v72
	v_rcp_f32_e32 v73, v73
	v_rcp_f32_e32 v66, v66
	v_rcp_f32_e32 v67, v67
	v_rcp_f32_e32 v74, v74
	v_rcp_f32_e32 v75, v75
	v_lshrrev_b32_e32 v64, 8, v150
	v_mad_i32_i24 v64, v64, 44, s41
	v_ashrrev_i32_e32 v65, 31, v64
	s_nop 0
	v_pk_mul_f32 v[54:55], v[54:55], v[70:71]
	v_lshlrev_b64 v[64:65], 15, v[64:65]
; #define PG8_BAR __builtin_amdgcn_s_barrier()
;     __device__ __forceinline__ void operator()(const f32x4 (&acc)[2][2][4][2], const Unit& u, int wr, int wc, int fr, int fq) const {
;     ...
;                 const int row = row0 + ai * HALF + m * 16; const float rs = rsv[ai][m], cexp = -1.4426950408889634f * rs, rs2 = rs * rs;
;                 const f32x4 g0 = acc[ai][0][m][0], g1 = acc[ai][0][m][1], u0 = acc[ai][1][m][0], u1 = acc[ai][1][m][1];
;                 const f32x4 t0 = g0 * cexp, t1 = g1 * cexp;
;                 f32x4 d0 = (f32x4){__builtin_amdgcn_exp2f(t0[0]), __builtin_amdgcn_exp2f(t0[1]), __builtin_amdgcn_exp2f(t0[2]), __builtin_amdgcn_exp2f(t0[3])} + 1.0f;
;                 f32x4 d1 = (f32x4){__builtin_amdgcn_exp2f(t1[0]), __builtin_amdgcn_exp2f(t1[1]), __builtin_amdgcn_exp2f(t1[2]), __builtin_amdgcn_exp2f(t1[3])} + 1.0f;
;                 const f32x4 r0 = (f32x4){__builtin_amdgcn_rcpf(d0[0]), __builtin_amdgcn_rcpf(d0[1]), __builtin_amdgcn_rcpf(d0[2]), __builtin_amdgcn_rcpf(d0[3])} * rs2;
;                 const f32x4 r1 = (f32x4){__builtin_amdgcn_rcpf(d1[0]), __builtin_amdgcn_rcpf(d1[1]), __builtin_amdgcn_rcpf(d1[2]), __builtin_amdgcn_rcpf(d1[3])} * rs2;
;                 const f32x4 a0 = (g0 * u0) * r0, a1 = (g1 * u1) * r1;
;                 u32x4 w; w.x = cvt_pk_bf16(a0[0], a0[1]); w.y = cvt_pk_bf16(a0[2], a0[3]); w.z = cvt_pk_bf16(a1[0], a1[1]); w.w = cvt_pk_bf16(a1[2], a1[3]);
;                 *(u32x4*)(O + (((size_t)(row >> 8) * (DFF / BK) + (col0 >> 6)) * BM + (row & 255)) * BK + (col0 & 63)) = w;
; template <class Epi, class Sched, bool ALIGN_EPI = false, bool SP2 = false, bool ATILED = false>
; __device__ __forceinline__ void gemm_phase(PG8_LAS unsigned char* lds, const Gemm g, const Sched& S, const Epi& E) {
;     ...
;         if constexpr (ALIGN_EPI) { if (wr == 0) PG8_BAR; }
;         if constexpr (!Epi::AFTER_DRAIN) { E(acc, cur, wr, wc, fr, fq); S.done(cur); }
;         if (!has_next) break;
; #pragma unroll
;         for (int a = 0; a < 2; ++a)
; #pragma unroll
;             for (int b = 0; b < 2; ++b)
; #pragma unroll
;                 for (int m = 0; m < 4; ++m)
; #pragma unroll
;                     for (int n = 0; n < 2; ++n) acc[a][b][m][n] = (f32x4){0.f, 0.f, 0.f, 0.f};
;         cur = nxt; cA = nA; cB = nB; ++ui;
;         if constexpr (ALIGN_EPI) { if (wr == 1) PG8_BAR; }
	v_pk_mul_f32 v[52:53], v[52:53], v[72:73]
	v_pk_mul_f32 v[56:57], v[50:51], v[74:75]
	v_pk_mul_f32 v[50:51], v[48:49], v[66:67]
	v_cvt_pk_bf16_f32 v49, v54, v55
	v_lshlrev_b32_e32 v54, 7, v150
	v_cvt_pk_bf16_f32 v48, v52, v53
	v_lshl_add_u64 v[52:53], s[36:37], 0, v[64:65]
	v_and_b32_e32 v136, 0x6780, v54
	v_lshl_add_u64 v[52:53], v[52:53], 0, v[136:137]
	v_cvt_pk_bf16_f32 v50, v50, v51
	v_cvt_pk_bf16_f32 v51, v56, v57
	v_lshl_add_u64 v[52:53], v[52:53], 0, v[148:149]
	global_store_dwordx4 v[52:53], v[48:51], off
	s_nop 1
	v_mul_f32_e32 v48, 0xbfb8aa3b, v174
	v_pk_mul_f32 v[54:55], v[46:47], v[48:49] op_sel_hi:[1,0]
	v_pk_mul_f32 v[56:57], v[44:45], v[48:49] op_sel_hi:[1,0]
	v_pk_mul_f32 v[58:59], v[42:43], v[48:49] op_sel_hi:[1,0]
	v_pk_mul_f32 v[48:49], v[40:41], v[48:49] op_sel_hi:[1,0]
	v_exp_f32_e32 v56, v56
	v_exp_f32_e32 v57, v57
	v_exp_f32_e32 v54, v54
	v_exp_f32_e32 v55, v55
	v_exp_f32_e32 v48, v48
	v_exp_f32_e32 v58, v58
	v_exp_f32_e32 v59, v59
	v_exp_f32_e32 v49, v49
	v_pk_fma_f32 v[54:55], v[54:55], v[242:243], v[242:243]
	v_pk_fma_f32 v[56:57], v[56:57], v[242:243], v[242:243]
	v_pk_fma_f32 v[58:59], v[58:59], v[242:243], v[242:243]
	v_pk_fma_f32 v[48:49], v[48:49], v[242:243], v[242:243]
	v_rcp_f32_e32 v56, v56
	v_rcp_f32_e32 v57, v57
	v_rcp_f32_e32 v54, v54
	v_rcp_f32_e32 v55, v55
	v_rcp_f32_e32 v48, v48
	v_rcp_f32_e32 v49, v49
	v_rcp_f32_e32 v58, v58
	v_rcp_f32_e32 v59, v59
	s_nop 0
	v_pk_mul_f32 v[38:39], v[38:39], v[54:55]
	v_pk_mul_f32 v[36:37], v[36:37], v[56:57]
	v_pk_mul_f32 v[40:41], v[34:35], v[58:59]
	v_pk_mul_f32 v[34:35], v[32:33], v[48:49]
	v_cvt_pk_bf16_f32 v32, v36, v37
	v_cvt_pk_bf16_f32 v33, v38, v39
	v_cvt_pk_bf16_f32 v34, v34, v35
	v_cvt_pk_bf16_f32 v35, v40, v41
	global_store_dwordx4 v[52:53], v[32:35], off offset:2048
	s_nop 1
	v_mul_f32_e32 v32, 0xbfb8aa3b, v175
	v_pk_mul_f32 v[38:39], v[28:29], v[32:33] op_sel_hi:[1,0]
	v_pk_mul_f32 v[36:37], v[30:31], v[32:33] op_sel_hi:[1,0]
	v_pk_mul_f32 v[40:41], v[26:27], v[32:33] op_sel_hi:[1,0]
	v_pk_mul_f32 v[32:33], v[24:25], v[32:33] op_sel_hi:[1,0]
	v_exp_f32_e32 v38, v38
	v_exp_f32_e32 v39, v39
	v_exp_f32_e32 v36, v36
	v_exp_f32_e32 v37, v37
	v_exp_f32_e32 v32, v32
	v_exp_f32_e32 v40, v40
	v_exp_f32_e32 v41, v41
	v_exp_f32_e32 v33, v33
	v_pk_fma_f32 v[38:39], v[38:39], v[244:245], v[244:245]
	v_pk_fma_f32 v[36:37], v[36:37], v[244:245], v[244:245]
	v_pk_fma_f32 v[40:41], v[40:41], v[244:245], v[244:245]
	v_pk_fma_f32 v[32:33], v[32:33], v[244:245], v[244:245]
	v_rcp_f32_e32 v38, v38
	v_rcp_f32_e32 v39, v39
	v_rcp_f32_e32 v36, v36
	v_rcp_f32_e32 v37, v37
	v_rcp_f32_e32 v32, v32
	v_rcp_f32_e32 v33, v33
	v_rcp_f32_e32 v40, v40
	v_rcp_f32_e32 v41, v41
	s_nop 0
	v_pk_mul_f32 v[20:21], v[20:21], v[38:39]
	v_pk_mul_f32 v[22:23], v[22:23], v[36:37]
	v_pk_mul_f32 v[24:25], v[18:19], v[40:41]
	v_pk_mul_f32 v[18:19], v[16:17], v[32:33]
	v_cvt_pk_bf16_f32 v16, v20, v21
	v_add_co_u32_e32 v20, vcc, s80, v52
	v_cvt_pk_bf16_f32 v17, v22, v23
	v_cvt_pk_bf16_f32 v18, v18, v19
	v_cvt_pk_bf16_f32 v19, v24, v25
	v_addc_co_u32_e32 v21, vcc, 0, v53, vcc
	global_store_dwordx4 v[20:21], v[16:19], off
	s_andn2_b64 vcc, exec, s[0:1]
	s_mov_b64 s[0:1], -1
	v_mul_f32_e32 v16, 0xbfb8aa3b, v151
	v_pk_mul_f32 v[22:23], v[14:15], v[16:17] op_sel_hi:[1,0]
	v_pk_mul_f32 v[24:25], v[12:13], v[16:17] op_sel_hi:[1,0]
	v_pk_mul_f32 v[26:27], v[10:11], v[16:17] op_sel_hi:[1,0]
	v_pk_mul_f32 v[16:17], v[8:9], v[16:17] op_sel_hi:[1,0]
	v_exp_f32_e32 v24, v24
	v_exp_f32_e32 v25, v25
	v_exp_f32_e32 v22, v22
	v_exp_f32_e32 v23, v23
	v_exp_f32_e32 v16, v16
	v_exp_f32_e32 v26, v26
	v_exp_f32_e32 v27, v27
	v_exp_f32_e32 v17, v17
	v_pk_fma_f32 v[22:23], v[22:23], v[246:247], v[246:247]
	v_pk_fma_f32 v[24:25], v[24:25], v[246:247], v[246:247]
	v_pk_fma_f32 v[26:27], v[26:27], v[246:247], v[246:247]
	v_pk_fma_f32 v[16:17], v[16:17], v[246:247], v[246:247]
	v_rcp_f32_e32 v24, v24
	v_rcp_f32_e32 v25, v25
	v_rcp_f32_e32 v22, v22
	v_rcp_f32_e32 v23, v23
	v_rcp_f32_e32 v16, v16
	v_rcp_f32_e32 v17, v17
	v_rcp_f32_e32 v26, v26
	v_rcp_f32_e32 v27, v27
	s_nop 0
	v_pk_mul_f32 v[6:7], v[6:7], v[22:23]
	v_pk_mul_f32 v[4:5], v[4:5], v[24:25]
	v_pk_mul_f32 v[8:9], v[2:3], v[26:27]
	v_pk_mul_f32 v[2:3], v[0:1], v[16:17]
	v_cvt_pk_bf16_f32 v0, v4, v5
	v_cvt_pk_bf16_f32 v1, v6, v7
	v_cvt_pk_bf16_f32 v2, v2, v3
	v_cvt_pk_bf16_f32 v3, v8, v9
	global_store_dwordx4 v[20:21], v[0:3], off offset:2048
	s_cbranch_vccnz .LBB0_129
	s_branch .LBB0_128

; #define PG8_WAIT_V(n) asm volatile("s_waitcnt vmcnt(" #n ")" ::: "memory")
; #define PG8_BAR __builtin_amdgcn_s_barrier()
; template <class Epi, class Sched, bool ALIGN_EPI = false, bool SP2 = false, bool ATILED = false>
; __device__ __forceinline__ void gemm_phase(PG8_LAS unsigned char* lds, const Gemm g, const Sched& S, const Epi& E) {
;     const int tid = threadIdx.x, wid = __builtin_amdgcn_readfirstlane(tid >> 6), lane = tid & 63, wr = wid >> 2, wc = wid & 3, fr = lane & 15, fq = lane >> 4;
;     const int K = g.K, nt = K / BK;
;     unsigned voffA[2], voffB[2];
; #pragma unroll
;     for (int i = 0; i < 2; ++i) { int R, C; stage_rc(tid * 16 + i * 8192, R, C); const int Rb = Epi::PERM ? ((R & ~31) + perm32(R & 31)) : R;
;         voffA[i] = (unsigned)(R * (ATILED ? BK : K) + C) * 2u; voffB[i] = (unsigned)(Rb * K + C) * 2u; }
;     const size_t kstep = (size_t)(BK * 2);
;     const size_t hstep = (size_t)HALF * K * 2;
;     const size_t tstep = 2 * hstep;
;     const size_t kstepA = ATILED ? (size_t)(BM * BK * 2) : kstep, hstepA = ATILED ? (size_t)(HALF * BK * 2) : hstep, tstepA = ATILED ? (size_t)nt * (BM * BK * 2) : tstep;
;     const unsigned ldsw = (unsigned)wid * 1024u;
;     const int aoff = lds_byte(wr * 64 + fr, fq * 8), boff = lds_byte(wc * 32 + fr, fq * 8);
;     ...
;     Unit cur, nxt; int ui = 0;
;     if (!S.next(0, cur)) return;
;     f32x4 acc[2][2][4][2];
; #pragma unroll
;     for (int a = 0; a < 2; ++a)
; #pragma unroll
;         for (int b = 0; b < 2; ++b)
; #pragma unroll
;             for (int m = 0; m < 4; ++m)
; #pragma unroll
;                 for (int n = 0; n < 2; ++n) acc[a][b][m][n] = (f32x4){0.f, 0.f, 0.f, 0.f};
;     bf16x8 At[4][2], B0[2][2], B1[2][2];
;     const char* cA = (const char*)g.A + (size_t)cur.pm * tstepA; const char* cB = (const char*)g.Bt + (size_t)cur.pn * tstep;
;     S.a_ready(cur);
;     if constexpr (SP2) {
;         PG8_STAGE(PG8_SB(0, 0), cB, voffB); PG8_STAGE(PG8_SB(0, 1), cB + hstep, voffB); PG8_STAGE(PG8_SA(0, 0), cA, voffA); PG8_STAGE(PG8_SA(0, 1), cA + hstepA, voffA);
;         if (wr == 1) PG8_BAR;
;         PG8_WAIT_V(2); PG8_BAR;
;         PG8_STAGE(PG8_SB(1, 0), cB + kstep, voffB); PG8_STAGE(PG8_SA(1, 0), cA + kstepA, voffA); PG8_STAGE(PG8_SB(1, 1), cB + hstep + kstep, voffB);
;         PG8_WAIT_V(6); PG8_BAR;
.LBB0_195:
	v_lshrrev_b32_e32 v1, 1, v198
	v_lshrrev_b32_e32 v2, 5, v198
	v_and_b32_e32 v1, 24, v1
	v_and_b32_e32 v2, 4, v2
	v_bfe_u32 v3, v198, 2, 2
	v_bfe_u32 v7, v198, 2, 4
	v_or3_b32 v1, v2, v3, v1
	v_lshrrev_b32_e32 v2, 3, v198
	s_movk_i32 s0, 0x70
	v_lshlrev_b32_e32 v6, 4, v198
	v_and_b32_e32 v0, 32, v198
	v_and_or_b32 v3, v2, s0, v7
	s_movk_i32 s0, 0x60
	v_bitop3_b32 v4, v6, v0, 48 bitop3:0x6c
	v_and_b32_e32 v5, 64, v198
	v_and_or_b32 v2, v2, s0, v1
	v_or_b32_e32 v0, v4, v5
	v_mul_u32_u24_e32 v2, 0x1600, v2
	v_add_u32_e32 v8, 0x2000, v6
	v_or_b32_e32 v154, v2, v0
	v_lshrrev_b32_e32 v2, 7, v8
	s_movk_i32 s0, 0xf0
	v_lshl_or_b32 v152, v3, 7, v0
	v_and_or_b32 v3, v2, s0, v7
	s_movk_i32 s0, 0xe0
	v_and_or_b32 v1, v2, s0, v1
	s_lshr_b32 s0, s4, 6
	s_lshr_b32 s5, s4, 8
	s_lshl_b32 s64, s0, 10
	s_mul_i32 s7, s8, 0x160000
	s_mul_hi_i32 s6, s8, 0x160000
	s_add_u32 s46, s58, s7
	s_addc_u32 s47, s59, s6
	s_add_i32 s65, s64, 0
	s_add_i32 m0, s65, 0x10000
	v_mul_u32_u24_e32 v1, 0x1600, v1
	global_load_lds_dwordx4 v154, s[46:47]
	s_add_i32 m0, s65, 0x12000
	v_or_b32_e32 v158, v1, v0
	s_add_u32 s6, s46, 0xb0000
	global_load_lds_dwordx4 v158, s[46:47]
	s_addc_u32 s7, s47, 0
	s_add_i32 m0, s65, 0x14000
	s_mul_i32 s9, s78, 0x160000
	global_load_lds_dwordx4 v154, s[6:7]
	s_add_i32 m0, s65, 0x16000
	s_mul_hi_i32 s1, s78, 0x160000
	s_add_u32 s48, s36, s9
	s_addc_u32 s49, s37, s1
	s_add_i32 s66, s65, 0x2000
	global_load_lds_dwordx4 v158, s[6:7]
	s_mov_b32 m0, s65
	s_add_u32 s6, s48, 0x4000
	v_lshl_or_b32 v156, v3, 7, v0
	global_load_lds_dwordx4 v152, s[48:49]
	s_mov_b32 m0, s66
	s_addc_u32 s7, s49, 0
	s_add_i32 s67, s65, 0x4000
	global_load_lds_dwordx4 v156, s[48:49]
	s_mov_b32 m0, s67
	s_add_i32 s68, s65, 0x6000
	global_load_lds_dwordx4 v152, s[6:7]
	s_mov_b32 m0, s68
	v_mov_b32_e32 v155, 0
	global_load_lds_dwordx4 v156, s[6:7]
	v_mov_b32_e32 v159, v155
	s_cmp_eq_u32 s5, 1
	v_mov_b32_e32 v153, v155
	v_mov_b32_e32 v157, v155
	s_mov_b32 s9, 0
	v_lshl_add_u64 v[0:1], s[46:47], 0, v[154:155]
	s_cselect_b64 s[38:39], -1, 0
	s_cmp_lg_u32 s5, 1
	v_lshl_add_u64 v[2:3], s[46:47], 0, v[158:159]
.LBB0_197:
	s_mov_b64 s[40:41], 0x80
	s_and_b32 s70, s0, 3
	s_add_i32 m0, s65, 0x18000
	v_lshl_add_u64 v[0:1], v[0:1], 0, s[40:41]
	s_ashr_i32 s69, s28, 31
	s_lshl_b32 s6, s5, 13
	s_lshl_b32 s7, s70, 12
	s_waitcnt vmcnt(2)
	s_barrier
	global_load_lds_dwordx4 v[0:1], off
	s_add_i32 m0, s65, 0x1a000
	s_add_u32 s0, s48, 0x8000
	v_lshl_add_u64 v[0:1], v[2:3], 0, s[40:41]
	s_addc_u32 s1, s49, 0
	s_add_i32 s71, s65, 0x8000
	global_load_lds_dwordx4 v[0:1], off
	v_lshl_add_u64 v[0:1], s[0:1], 0, v[152:153]
	s_mov_b32 m0, s71
	s_add_i32 s72, s65, 0xa000
	global_load_lds_dwordx4 v[0:1], off
	v_lshl_add_u64 v[0:1], s[0:1], 0, v[156:157]
	s_add_u32 s0, s46, 0xb0080
	s_mov_b32 m0, s72
	s_addc_u32 s1, s47, 0
	global_load_lds_dwordx4 v[0:1], off
	s_add_i32 m0, s65, 0x1c000
	v_lshl_add_u64 v[0:1], s[0:1], 0, v[154:155]
	global_load_lds_dwordx4 v[0:1], off
	v_lshl_add_u64 v[0:1], s[0:1], 0, v[158:159]
	s_add_i32 m0, s65, 0x1e000
	v_lshlrev_b32_e32 v9, 6, v198
	global_load_lds_dwordx4 v[0:1], off
	v_bfe_u32 v1, v198, 4, 2
	v_lshlrev_b32_e32 v2, 3, v1
	v_lshlrev_b32_e32 v3, 4, v1
	s_movk_i32 s0, 0x3c0
	v_and_b32_e32 v0, 15, v198
	v_and_or_b32 v9, v9, s0, v3
	v_lshlrev_b32_e32 v10, 2, v198
	v_cmp_eq_u32_e64 s[0:1], 0, v1
	v_lshl_or_b32 v188, s70, 5, v2
	v_and_b32_e32 v1, 0x3800, v6
	v_lshlrev_b32_e32 v2, 7, v7
	v_and_b32_e32 v10, 32, v10
	v_lshl_or_b32 v186, s5, 6, v0
	v_lshl_or_b32 v0, v0, 6, v3
	v_or3_b32 v1, v4, v1, v2
	v_bitop3_b32 v0, v0, s6, v10 bitop3:0xde
	s_waitcnt vmcnt(6)
	s_cmpk_lt_u32 s4, 0x100
	v_add_u32_e32 v160, v1, v5
	v_and_b32_e32 v1, 0x7800, v8
	v_bitop3_b32 v187, s7, v9, v10 bitop3:0xf6
	s_cselect_b64 s[42:43], -1, 0
	v_or3_b32 v1, v4, v1, v2
	s_add_i32 s73, 0, 0x10000
	s_add_i32 s74, 0, 0x14000
	v_add_u32_e32 v191, 0, v0
	v_mbcnt_lo_u32_b32 v0, -1, 0
	v_mov_b32_e32 v161, v155
	v_add_u32_e32 v162, v1, v5
	v_mov_b32_e32 v163, v155
	v_mov_b64_e32 v[164:165], 0x400
	v_mov_b64_e32 v[166:167], 0x3ff
	v_add_u32_e32 v189, s73, v187
	v_add_u32_e32 v190, s74, v187
	v_mbcnt_hi_u32_b32 v192, -1, v0
	s_mov_b32 s75, 0
	s_barrier
	s_branch .LBB0_200

; #define PG8_STAGE(bufoff, gbase, voff) do { _Pragma("unroll") for (int _i = 0; _i < 2; ++_i) \
;         __builtin_amdgcn_global_load_lds((const unsigned*)((const char*)(gbase) + (voff)[_i]), (PG8_LAS unsigned*)(lds + (bufoff) + ldsw + _i * 8192), 16, 0, 0); } while (0)
; #define PG8_LDA(dst, b, h) do { _Pragma("unroll") for (int m = 0; m < 4; ++m) _Pragma("unroll") for (int k = 0; k < 2; ++k) dst[m][k] = *(const PG8_LAS bf16x8*)(lds + PG8_SA(b, h) + aoff + m * 2048 + k * 1024); } while (0)
; #define PG8_LDB(dst, b, h) do { _Pragma("unroll") for (int n = 0; n < 2; ++n) _Pragma("unroll") for (int k = 0; k < 2; ++k) dst[n][k] = *(const PG8_LAS bf16x8*)(lds + PG8_SB(b, h) + boff + n * 2048 + k * 1024); } while (0)
; #define PG8_SCHED __builtin_amdgcn_sched_barrier(0)
; template <class Epi, class Sched, bool ALIGN_EPI = false, bool SP2 = false, bool ATILED = false>
; __device__ __forceinline__ void gemm_phase(PG8_LAS unsigned char* lds, const Gemm g, const Sched& S, const Epi& E) {
;     ...
;         const char* nA = has_next ? (const char*)g.A + (size_t)nxt.pm * tstepA : cA; const char* nB = has_next ? (const char*)g.Bt + (size_t)nxt.pn * tstep : cB;
;         for (int t = 0; t < nt; t += 2) {
;             const bool last = (t == nt - 2);
;             const char* a1 = cA + (size_t)(t + 1) * kstepA;
;             const char* a2 = last ? nA : cA + (size_t)(t + 2) * kstepA; const char* b2 = last ? nB : cB + (size_t)(t + 2) * kstep;
;             const char* a3 = a2 + kstepA; const char* b3 = b2 + kstep;
;             if (last && has_next) S.a_ready(nxt);
;             if constexpr (SP2) {
;             PG8_LDB(B0, 0, 0); PG8_LDB(B1, 0, 1); PG8_SCHED; PG8_LDA(At, 0, 0); PG8_STAGE(PG8_SA(1, 1), a1 + hstepA, voffA);
.LBB0_210:
	s_add_u32 s79, s46, 0x100
	s_addc_u32 s80, s47, 0
	s_add_u32 s46, s48, 0xc000
	s_addc_u32 s47, s49, 0
	s_mov_b32 s81, -2
	s_waitcnt lgkmcnt(0)
	s_cmp_lg_u64 s[38:39], 0
	s_cbranch_scc0 .Ltbar_skip1
	s_barrier
.Ltbar_skip1:
	ds_read_b128 v[128:131], v189
	ds_read_b128 v[132:135], v189 offset:1024
	ds_read_b128 v[136:139], v189 offset:2048
	ds_read_b128 v[140:143], v189 offset:3072
	ds_read_b128 v[144:147], v190
	ds_read_b128 v[148:151], v190 offset:1024
	ds_read_b128 v[168:171], v190 offset:2048
	ds_read_b128 v[172:175], v190 offset:3072
	s_add_u32 s48, s46, 0x4000
	s_addc_u32 s49, s47, 0
	s_cmp_eq_u32 s81, 40
	s_cselect_b32 s62, s4, s48
	s_cselect_b32 s63, s5, s49
	s_cselect_b32 s60, s44, s79
	s_cselect_b32 s61, s45, s80
	s_add_u32 s48, s62, 0x8000
	s_addc_u32 s49, s63, 0

; #define PG8_STAGE(bufoff, gbase, voff) do { _Pragma("unroll") for (int _i = 0; _i < 2; ++_i) \
;         __builtin_amdgcn_global_load_lds((const unsigned*)((const char*)(gbase) + (voff)[_i]), (PG8_LAS unsigned*)(lds + (bufoff) + ldsw + _i * 8192), 16, 0, 0); } while (0)
; #define PG8_LDA(dst, b, h) do { _Pragma("unroll") for (int m = 0; m < 4; ++m) _Pragma("unroll") for (int k = 0; k < 2; ++k) dst[m][k] = *(const PG8_LAS bf16x8*)(lds + PG8_SA(b, h) + aoff + m * 2048 + k * 1024); } while (0)
; #define PG8_LDB(dst, b, h) do { _Pragma("unroll") for (int n = 0; n < 2; ++n) _Pragma("unroll") for (int k = 0; k < 2; ++k) dst[n][k] = *(const PG8_LAS bf16x8*)(lds + PG8_SB(b, h) + boff + n * 2048 + k * 1024); } while (0)
; #define PG8_SCHED __builtin_amdgcn_sched_barrier(0)
; template <class Epi, class Sched, bool ALIGN_EPI = false, bool SP2 = false, bool ATILED = false>
; __device__ __forceinline__ void gemm_phase(PG8_LAS unsigned char* lds, const Gemm g, const Sched& S, const Epi& E) {
;     ...
;             PG8_LDB(B0, 0, 0); PG8_LDB(B1, 0, 1); PG8_SCHED; PG8_LDA(At, 0, 0); PG8_STAGE(PG8_SA(1, 1), a1 + hstepA, voffA);
	s_add_i32 m0, s65, 0xc000
	ds_read_b128 v[176:179], v191
	ds_read_b128 v[180:183], v191 offset:1024
	ds_read_b128 v[194:197], v191 offset:2048
	ds_read_b128 v[200:203], v191 offset:3072
	ds_read_b128 v[204:207], v191 offset:4096
	ds_read_b128 v[208:211], v191 offset:5120
	ds_read_b128 v[212:215], v191 offset:6144
	ds_read_b128 v[216:219], v191 offset:7168
	global_load_lds_dwordx4 v160, s[46:47]

; #define PG8_STAGE(bufoff, gbase, voff) do { _Pragma("unroll") for (int _i = 0; _i < 2; ++_i) \
;         __builtin_amdgcn_global_load_lds((const unsigned*)((const char*)(gbase) + (voff)[_i]), (PG8_LAS unsigned*)(lds + (bufoff) + ldsw + _i * 8192), 16, 0, 0); } while (0)
; #define PG8_LDA(dst, b, h) do { _Pragma("unroll") for (int m = 0; m < 4; ++m) _Pragma("unroll") for (int k = 0; k < 2; ++k) dst[m][k] = *(const PG8_LAS bf16x8*)(lds + PG8_SA(b, h) + aoff + m * 2048 + k * 1024); } while (0)
; #define PG8_LDB(dst, b, h) do { _Pragma("unroll") for (int n = 0; n < 2; ++n) _Pragma("unroll") for (int k = 0; k < 2; ++k) dst[n][k] = *(const PG8_LAS bf16x8*)(lds + PG8_SB(b, h) + boff + n * 2048 + k * 1024); } while (0)
; #define PG8_MMA(ai, bj, At, Bt) do { __builtin_amdgcn_s_setprio(1); _Pragma("unroll") for (int m = 0; m < 4; ++m) _Pragma("unroll") for (int n = 0; n < 2; ++n) _Pragma("unroll") for (int k = 0; k < 2; ++k) \
;         acc[ai][bj][m][n] = __builtin_amdgcn_mfma_f32_16x16x32_bf16(Bt[n][k], At[m][k], acc[ai][bj][m][n], 0, 0, 0); __builtin_amdgcn_s_setprio(0); } while (0)
; #define PG8_WAIT_V(n) asm volatile("s_waitcnt vmcnt(" #n ")" ::: "memory")
; #define PG8_WAIT_L(n) asm volatile("s_waitcnt lgkmcnt(" #n ")" ::: "memory")
; #define PG8_BAR __builtin_amdgcn_s_barrier()
; #define PG8_SCHED __builtin_amdgcn_sched_barrier(0)
; template <class Epi, class Sched, bool ALIGN_EPI = false, bool SP2 = false, bool ATILED = false>
; __device__ __forceinline__ void gemm_phase(PG8_LAS unsigned char* lds, const Gemm g, const Sched& S, const Epi& E) {
;     ...
;             PG8_LDB(B0, 0, 0); PG8_LDB(B1, 0, 1); PG8_SCHED; PG8_LDA(At, 0, 0); PG8_STAGE(PG8_SA(1, 1), a1 + hstepA, voffA);
;             PG8_WAIT_V(8); PG8_WAIT_L(0); PG8_BAR; PG8_MMA(0, 0, At, B0); PG8_MMA(0, 1, At, B1); PG8_BAR; PG8_SCHED;
	s_add_i32 m0, s65, 0xe000
	s_nop 0
	global_load_lds_dwordx4 v162, s[46:47]
	s_waitcnt vmcnt(8)
	s_waitcnt lgkmcnt(0)
	s_barrier
	s_setprio 1
	s_waitcnt lgkmcnt(0)
	v_mfma_f32_16x16x32_bf16 v[124:127], v[128:131], v[176:179], 0
	v_mfma_f32_16x16x32_bf16 v[120:123], v[136:139], v[176:179], 0
	v_mfma_f32_16x16x32_bf16 v[108:111], v[128:131], v[194:197], 0
	v_mfma_f32_16x16x32_bf16 v[104:107], v[136:139], v[194:197], 0
	v_mfma_f32_16x16x32_bf16 v[92:95], v[128:131], v[204:207], 0
	v_mfma_f32_16x16x32_bf16 v[88:91], v[136:139], v[204:207], 0
	v_mfma_f32_16x16x32_bf16 v[76:79], v[128:131], v[212:215], 0
	v_mfma_f32_16x16x32_bf16 v[72:75], v[136:139], v[212:215], 0
	v_mfma_f32_16x16x32_bf16 v[124:127], v[132:135], v[180:183], v[124:127]
	v_mfma_f32_16x16x32_bf16 v[120:123], v[140:143], v[180:183], v[120:123]
	v_mfma_f32_16x16x32_bf16 v[108:111], v[132:135], v[200:203], v[108:111]
	v_mfma_f32_16x16x32_bf16 v[104:107], v[140:143], v[200:203], v[104:107]
	v_mfma_f32_16x16x32_bf16 v[92:95], v[132:135], v[208:211], v[92:95]
	v_mfma_f32_16x16x32_bf16 v[88:91], v[140:143], v[208:211], v[88:91]
	v_mfma_f32_16x16x32_bf16 v[76:79], v[132:135], v[216:219], v[76:79]
	v_mfma_f32_16x16x32_bf16 v[72:75], v[140:143], v[216:219], v[72:75]
	s_setprio 0
	s_setprio 1
	v_mfma_f32_16x16x32_bf16 v[116:119], v[144:147], v[176:179], 0
	v_mfma_f32_16x16x32_bf16 v[112:115], v[168:171], v[176:179], 0
	v_mfma_f32_16x16x32_bf16 v[100:103], v[144:147], v[194:197], 0
	v_mfma_f32_16x16x32_bf16 v[96:99], v[168:171], v[194:197], 0
	v_mfma_f32_16x16x32_bf16 v[84:87], v[144:147], v[204:207], 0
	v_mfma_f32_16x16x32_bf16 v[80:83], v[168:171], v[204:207], 0
	v_mfma_f32_16x16x32_bf16 v[68:71], v[144:147], v[212:215], 0
	v_mfma_f32_16x16x32_bf16 v[64:67], v[168:171], v[212:215], 0
	v_mfma_f32_16x16x32_bf16 v[116:119], v[148:151], v[180:183], v[116:119]
	v_mfma_f32_16x16x32_bf16 v[112:115], v[172:175], v[180:183], v[112:115]
	v_mfma_f32_16x16x32_bf16 v[100:103], v[148:151], v[200:203], v[100:103]
	v_mfma_f32_16x16x32_bf16 v[96:99], v[172:175], v[200:203], v[96:99]
	v_mfma_f32_16x16x32_bf16 v[84:87], v[148:151], v[208:211], v[84:87]
	v_mfma_f32_16x16x32_bf16 v[80:83], v[172:175], v[208:211], v[80:83]
	v_mfma_f32_16x16x32_bf16 v[68:71], v[148:151], v[216:219], v[68:71]
	v_mfma_f32_16x16x32_bf16 v[64:67], v[172:175], v[216:219], v[64:67]
	s_setprio 0
	s_barrier
	s_add_u32 s98, s60, s40
	s_addc_u32 s99, s61, s41
	s_add_i32 s83, s73, s64

; #define PG8_STAGE(bufoff, gbase, voff) do { _Pragma("unroll") for (int _i = 0; _i < 2; ++_i) \
;         __builtin_amdgcn_global_load_lds((const unsigned*)((const char*)(gbase) + (voff)[_i]), (PG8_LAS unsigned*)(lds + (bufoff) + ldsw + _i * 8192), 16, 0, 0); } while (0)
; #define PG8_LDA(dst, b, h) do { _Pragma("unroll") for (int m = 0; m < 4; ++m) _Pragma("unroll") for (int k = 0; k < 2; ++k) dst[m][k] = *(const PG8_LAS bf16x8*)(lds + PG8_SA(b, h) + aoff + m * 2048 + k * 1024); } while (0)
; template <class Epi, class Sched, bool ALIGN_EPI = false, bool SP2 = false, bool ATILED = false>
; __device__ __forceinline__ void gemm_phase(PG8_LAS unsigned char* lds, const Gemm g, const Sched& S, const Epi& E) {
;     ...
;             PG8_LDA(At, 0, 1); PG8_STAGE(PG8_SB(0, 0), b2, voffB); PG8_STAGE(PG8_SB(0, 1), b2 + hstep, voffB); PG8_STAGE(PG8_SA(0, 0), a2, voffA);
	s_mov_b32 m0, s83
	ds_read_b128 v[176:179], v191 offset:16384
	ds_read_b128 v[180:183], v191 offset:17408
	ds_read_b128 v[194:197], v191 offset:18432
	ds_read_b128 v[200:203], v191 offset:19456
	ds_read_b128 v[204:207], v191 offset:20480
	ds_read_b128 v[208:211], v191 offset:21504
	ds_read_b128 v[212:215], v191 offset:22528
	ds_read_b128 v[216:219], v191 offset:23552
	global_load_lds_dwordx4 v154, s[60:61]
	s_add_i32 m0, s83, 0x2000
	s_add_u32 s84, s60, 0xb0000

; #define PG8_STAGE(bufoff, gbase, voff) do { _Pragma("unroll") for (int _i = 0; _i < 2; ++_i) \
;         __builtin_amdgcn_global_load_lds((const unsigned*)((const char*)(gbase) + (voff)[_i]), (PG8_LAS unsigned*)(lds + (bufoff) + ldsw + _i * 8192), 16, 0, 0); } while (0)
; #define PG8_LDA(dst, b, h) do { _Pragma("unroll") for (int m = 0; m < 4; ++m) _Pragma("unroll") for (int k = 0; k < 2; ++k) dst[m][k] = *(const PG8_LAS bf16x8*)(lds + PG8_SA(b, h) + aoff + m * 2048 + k * 1024); } while (0)
; template <class Epi, class Sched, bool ALIGN_EPI = false, bool SP2 = false, bool ATILED = false>
; __device__ __forceinline__ void gemm_phase(PG8_LAS unsigned char* lds, const Gemm g, const Sched& S, const Epi& E) {
;     ...
;             PG8_LDA(At, 0, 1); PG8_STAGE(PG8_SB(0, 0), b2, voffB); PG8_STAGE(PG8_SB(0, 1), b2 + hstep, voffB); PG8_STAGE(PG8_SA(0, 0), a2, voffA);
	s_addc_u32 s85, s61, 0
	s_add_i32 s83, s74, s64
	global_load_lds_dwordx4 v158, s[60:61]

; #define PG8_STAGE(bufoff, gbase, voff) do { _Pragma("unroll") for (int _i = 0; _i < 2; ++_i) \
;         __builtin_amdgcn_global_load_lds((const unsigned*)((const char*)(gbase) + (voff)[_i]), (PG8_LAS unsigned*)(lds + (bufoff) + ldsw + _i * 8192), 16, 0, 0); } while (0)
; #define PG8_LDA(dst, b, h) do { _Pragma("unroll") for (int m = 0; m < 4; ++m) _Pragma("unroll") for (int k = 0; k < 2; ++k) dst[m][k] = *(const PG8_LAS bf16x8*)(lds + PG8_SA(b, h) + aoff + m * 2048 + k * 1024); } while (0)
; template <class Epi, class Sched, bool ALIGN_EPI = false, bool SP2 = false, bool ATILED = false>
; __device__ __forceinline__ void gemm_phase(PG8_LAS unsigned char* lds, const Gemm g, const Sched& S, const Epi& E) {
;     ...
;             PG8_LDA(At, 0, 1); PG8_STAGE(PG8_SB(0, 0), b2, voffB); PG8_STAGE(PG8_SB(0, 1), b2 + hstep, voffB); PG8_STAGE(PG8_SA(0, 0), a2, voffA);
	s_mov_b32 m0, s83
	s_nop 0
	global_load_lds_dwordx4 v154, s[84:85]

; #define PG8_STAGE(bufoff, gbase, voff) do { _Pragma("unroll") for (int _i = 0; _i < 2; ++_i) \
;         __builtin_amdgcn_global_load_lds((const unsigned*)((const char*)(gbase) + (voff)[_i]), (PG8_LAS unsigned*)(lds + (bufoff) + ldsw + _i * 8192), 16, 0, 0); } while (0)
; #define PG8_LDA(dst, b, h) do { _Pragma("unroll") for (int m = 0; m < 4; ++m) _Pragma("unroll") for (int k = 0; k < 2; ++k) dst[m][k] = *(const PG8_LAS bf16x8*)(lds + PG8_SA(b, h) + aoff + m * 2048 + k * 1024); } while (0)
; template <class Epi, class Sched, bool ALIGN_EPI = false, bool SP2 = false, bool ATILED = false>
; __device__ __forceinline__ void gemm_phase(PG8_LAS unsigned char* lds, const Gemm g, const Sched& S, const Epi& E) {
;     ...
;             PG8_LDA(At, 0, 1); PG8_STAGE(PG8_SB(0, 0), b2, voffB); PG8_STAGE(PG8_SB(0, 1), b2 + hstep, voffB); PG8_STAGE(PG8_SA(0, 0), a2, voffA);
	s_add_i32 m0, s83, 0x2000
	s_nop 0
	global_load_lds_dwordx4 v158, s[84:85]

; #define PG8_STAGE(bufoff, gbase, voff) do { _Pragma("unroll") for (int _i = 0; _i < 2; ++_i) \
;         __builtin_amdgcn_global_load_lds((const unsigned*)((const char*)(gbase) + (voff)[_i]), (PG8_LAS unsigned*)(lds + (bufoff) + ldsw + _i * 8192), 16, 0, 0); } while (0)
; #define PG8_LDA(dst, b, h) do { _Pragma("unroll") for (int m = 0; m < 4; ++m) _Pragma("unroll") for (int k = 0; k < 2; ++k) dst[m][k] = *(const PG8_LAS bf16x8*)(lds + PG8_SA(b, h) + aoff + m * 2048 + k * 1024); } while (0)
; template <class Epi, class Sched, bool ALIGN_EPI = false, bool SP2 = false, bool ATILED = false>
; __device__ __forceinline__ void gemm_phase(PG8_LAS unsigned char* lds, const Gemm g, const Sched& S, const Epi& E) {
;     ...
;             PG8_LDA(At, 0, 1); PG8_STAGE(PG8_SB(0, 0), b2, voffB); PG8_STAGE(PG8_SB(0, 1), b2 + hstep, voffB); PG8_STAGE(PG8_SA(0, 0), a2, voffA);
	s_mov_b32 m0, s65
	s_nop 0
	global_load_lds_dwordx4 v152, s[62:63]

; #define PG8_STAGE(bufoff, gbase, voff) do { _Pragma("unroll") for (int _i = 0; _i < 2; ++_i) \
;         __builtin_amdgcn_global_load_lds((const unsigned*)((const char*)(gbase) + (voff)[_i]), (PG8_LAS unsigned*)(lds + (bufoff) + ldsw + _i * 8192), 16, 0, 0); } while (0)
; #define PG8_LDA(dst, b, h) do { _Pragma("unroll") for (int m = 0; m < 4; ++m) _Pragma("unroll") for (int k = 0; k < 2; ++k) dst[m][k] = *(const PG8_LAS bf16x8*)(lds + PG8_SA(b, h) + aoff + m * 2048 + k * 1024); } while (0)
; #define PG8_LDB(dst, b, h) do { _Pragma("unroll") for (int n = 0; n < 2; ++n) _Pragma("unroll") for (int k = 0; k < 2; ++k) dst[n][k] = *(const PG8_LAS bf16x8*)(lds + PG8_SB(b, h) + boff + n * 2048 + k * 1024); } while (0)
; #define PG8_MMA(ai, bj, At, Bt) do { __builtin_amdgcn_s_setprio(1); _Pragma("unroll") for (int m = 0; m < 4; ++m) _Pragma("unroll") for (int n = 0; n < 2; ++n) _Pragma("unroll") for (int k = 0; k < 2; ++k) \
;         acc[ai][bj][m][n] = __builtin_amdgcn_mfma_f32_16x16x32_bf16(Bt[n][k], At[m][k], acc[ai][bj][m][n], 0, 0, 0); __builtin_amdgcn_s_setprio(0); } while (0)
; #define PG8_WAIT_V(n) asm volatile("s_waitcnt vmcnt(" #n ")" ::: "memory")
; #define PG8_WAIT_L(n) asm volatile("s_waitcnt lgkmcnt(" #n ")" ::: "memory")
; #define PG8_BAR __builtin_amdgcn_s_barrier()
; #define PG8_SCHED __builtin_amdgcn_sched_barrier(0)
; template <class Epi, class Sched, bool ALIGN_EPI = false, bool SP2 = false, bool ATILED = false>
; __device__ __forceinline__ void gemm_phase(PG8_LAS unsigned char* lds, const Gemm g, const Sched& S, const Epi& E) {
;     ...
;             PG8_WAIT_V(8); PG8_WAIT_L(0); PG8_BAR; PG8_MMA(1, 0, At, B0); PG8_MMA(1, 1, At, B1); PG8_BAR; PG8_SCHED;
;             PG8_LDB(B0, 1, 0); PG8_LDB(B1, 1, 1); PG8_SCHED; PG8_LDA(At, 1, 0); PG8_STAGE(PG8_SA(0, 1), a2 + hstepA, voffA);
	s_mov_b32 m0, s66
	s_nop 0
	global_load_lds_dwordx4 v156, s[62:63]
	s_waitcnt vmcnt(8)
	s_waitcnt lgkmcnt(0)
	s_barrier
	s_setprio 1
	s_waitcnt lgkmcnt(0)
	v_mfma_f32_16x16x32_bf16 v[60:63], v[128:131], v[176:179], 0
	v_mfma_f32_16x16x32_bf16 v[56:59], v[136:139], v[176:179], 0
	v_mfma_f32_16x16x32_bf16 v[44:47], v[128:131], v[194:197], 0
	v_mfma_f32_16x16x32_bf16 v[40:43], v[136:139], v[194:197], 0
	v_mfma_f32_16x16x32_bf16 v[28:31], v[128:131], v[204:207], 0
	v_mfma_f32_16x16x32_bf16 v[24:27], v[136:139], v[204:207], 0
	v_mfma_f32_16x16x32_bf16 v[12:15], v[128:131], v[212:215], 0
	v_mfma_f32_16x16x32_bf16 v[8:11], v[136:139], v[212:215], 0
	v_mfma_f32_16x16x32_bf16 v[60:63], v[132:135], v[180:183], v[60:63]
	v_mfma_f32_16x16x32_bf16 v[56:59], v[140:143], v[180:183], v[56:59]
	v_mfma_f32_16x16x32_bf16 v[44:47], v[132:135], v[200:203], v[44:47]
	v_mfma_f32_16x16x32_bf16 v[40:43], v[140:143], v[200:203], v[40:43]
	v_mfma_f32_16x16x32_bf16 v[28:31], v[132:135], v[208:211], v[28:31]
	v_mfma_f32_16x16x32_bf16 v[24:27], v[140:143], v[208:211], v[24:27]
	v_mfma_f32_16x16x32_bf16 v[12:15], v[132:135], v[216:219], v[12:15]
	v_mfma_f32_16x16x32_bf16 v[8:11], v[140:143], v[216:219], v[8:11]
	s_setprio 0
	s_setprio 1
	v_mfma_f32_16x16x32_bf16 v[52:55], v[144:147], v[176:179], 0
	v_mfma_f32_16x16x32_bf16 v[48:51], v[168:171], v[176:179], 0
	v_mfma_f32_16x16x32_bf16 v[36:39], v[144:147], v[194:197], 0
	v_mfma_f32_16x16x32_bf16 v[32:35], v[168:171], v[194:197], 0
	v_mfma_f32_16x16x32_bf16 v[20:23], v[144:147], v[204:207], 0
	v_mfma_f32_16x16x32_bf16 v[16:19], v[168:171], v[204:207], 0
	v_mfma_f32_16x16x32_bf16 v[4:7], v[144:147], v[212:215], 0
	v_mfma_f32_16x16x32_bf16 v[0:3], v[168:171], v[212:215], 0
	v_mfma_f32_16x16x32_bf16 v[52:55], v[148:151], v[180:183], v[52:55]
	v_mfma_f32_16x16x32_bf16 v[48:51], v[172:175], v[180:183], v[48:51]
	v_mfma_f32_16x16x32_bf16 v[36:39], v[148:151], v[200:203], v[36:39]
	v_mfma_f32_16x16x32_bf16 v[32:35], v[172:175], v[200:203], v[32:35]
	v_mfma_f32_16x16x32_bf16 v[20:23], v[148:151], v[208:211], v[20:23]
	v_mfma_f32_16x16x32_bf16 v[16:19], v[172:175], v[208:211], v[16:19]
	v_mfma_f32_16x16x32_bf16 v[4:7], v[148:151], v[216:219], v[4:7]
	v_mfma_f32_16x16x32_bf16 v[0:3], v[172:175], v[216:219], v[0:3]
	s_setprio 0
	s_barrier
	s_add_i32 s83, 0, 0x18000
	s_add_i32 s84, 0, 0x1c000
	v_add_u32_e32 v140, s83, v187
	v_add_u32_e32 v172, s84, v187
	ds_read_b128 v[128:131], v140
	ds_read_b128 v[132:135], v140 offset:1024
	ds_read_b128 v[136:139], v140 offset:2048
	ds_read_b128 v[140:143], v140 offset:3072
	ds_read_b128 v[144:147], v172
	ds_read_b128 v[148:151], v172 offset:1024
	ds_read_b128 v[168:171], v172 offset:2048
	ds_read_b128 v[172:175], v172 offset:3072
	s_add_u32 s62, s62, 0x4000
	s_addc_u32 s63, s63, 0
	s_mov_b32 m0, s67

; #define PG8_STAGE(bufoff, gbase, voff) do { _Pragma("unroll") for (int _i = 0; _i < 2; ++_i) \
;         __builtin_amdgcn_global_load_lds((const unsigned*)((const char*)(gbase) + (voff)[_i]), (PG8_LAS unsigned*)(lds + (bufoff) + ldsw + _i * 8192), 16, 0, 0); } while (0)
; #define PG8_LDA(dst, b, h) do { _Pragma("unroll") for (int m = 0; m < 4; ++m) _Pragma("unroll") for (int k = 0; k < 2; ++k) dst[m][k] = *(const PG8_LAS bf16x8*)(lds + PG8_SA(b, h) + aoff + m * 2048 + k * 1024); } while (0)
; #define PG8_LDB(dst, b, h) do { _Pragma("unroll") for (int n = 0; n < 2; ++n) _Pragma("unroll") for (int k = 0; k < 2; ++k) dst[n][k] = *(const PG8_LAS bf16x8*)(lds + PG8_SB(b, h) + boff + n * 2048 + k * 1024); } while (0)
; #define PG8_SCHED __builtin_amdgcn_sched_barrier(0)
; template <class Epi, class Sched, bool ALIGN_EPI = false, bool SP2 = false, bool ATILED = false>
; __device__ __forceinline__ void gemm_phase(PG8_LAS unsigned char* lds, const Gemm g, const Sched& S, const Epi& E) {
;     ...
;             PG8_LDB(B0, 1, 0); PG8_LDB(B1, 1, 1); PG8_SCHED; PG8_LDA(At, 1, 0); PG8_STAGE(PG8_SA(0, 1), a2 + hstepA, voffA);
	ds_read_b128 v[176:179], v191 offset:32768
	ds_read_b128 v[180:183], v191 offset:33792
	ds_read_b128 v[194:197], v191 offset:34816
	ds_read_b128 v[200:203], v191 offset:35840
	ds_read_b128 v[204:207], v191 offset:36864
	ds_read_b128 v[208:211], v191 offset:37888
	ds_read_b128 v[212:215], v191 offset:38912
	ds_read_b128 v[216:219], v191 offset:39936
	global_load_lds_dwordx4 v152, s[62:63]

; #define PG8_STAGE(bufoff, gbase, voff) do { _Pragma("unroll") for (int _i = 0; _i < 2; ++_i) \
;         __builtin_amdgcn_global_load_lds((const unsigned*)((const char*)(gbase) + (voff)[_i]), (PG8_LAS unsigned*)(lds + (bufoff) + ldsw + _i * 8192), 16, 0, 0); } while (0)
; #define PG8_LDA(dst, b, h) do { _Pragma("unroll") for (int m = 0; m < 4; ++m) _Pragma("unroll") for (int k = 0; k < 2; ++k) dst[m][k] = *(const PG8_LAS bf16x8*)(lds + PG8_SA(b, h) + aoff + m * 2048 + k * 1024); } while (0)
; #define PG8_LDB(dst, b, h) do { _Pragma("unroll") for (int n = 0; n < 2; ++n) _Pragma("unroll") for (int k = 0; k < 2; ++k) dst[n][k] = *(const PG8_LAS bf16x8*)(lds + PG8_SB(b, h) + boff + n * 2048 + k * 1024); } while (0)
; #define PG8_MMA(ai, bj, At, Bt) do { __builtin_amdgcn_s_setprio(1); _Pragma("unroll") for (int m = 0; m < 4; ++m) _Pragma("unroll") for (int n = 0; n < 2; ++n) _Pragma("unroll") for (int k = 0; k < 2; ++k) \
;         acc[ai][bj][m][n] = __builtin_amdgcn_mfma_f32_16x16x32_bf16(Bt[n][k], At[m][k], acc[ai][bj][m][n], 0, 0, 0); __builtin_amdgcn_s_setprio(0); } while (0)
; #define PG8_WAIT_V(n) asm volatile("s_waitcnt vmcnt(" #n ")" ::: "memory")
; #define PG8_WAIT_L(n) asm volatile("s_waitcnt lgkmcnt(" #n ")" ::: "memory")
; #define PG8_BAR __builtin_amdgcn_s_barrier()
; #define PG8_SCHED __builtin_amdgcn_sched_barrier(0)
; template <class Epi, class Sched, bool ALIGN_EPI = false, bool SP2 = false, bool ATILED = false>
; __device__ __forceinline__ void gemm_phase(PG8_LAS unsigned char* lds, const Gemm g, const Sched& S, const Epi& E) {
;     ...
;             PG8_LDB(B0, 1, 0); PG8_LDB(B1, 1, 1); PG8_SCHED; PG8_LDA(At, 1, 0); PG8_STAGE(PG8_SA(0, 1), a2 + hstepA, voffA);
;             PG8_WAIT_V(8); PG8_WAIT_L(0); PG8_BAR; PG8_MMA(0, 0, At, B0); PG8_MMA(0, 1, At, B1); PG8_BAR; PG8_SCHED;
	s_mov_b32 m0, s68
	s_nop 0
	global_load_lds_dwordx4 v156, s[62:63]
	s_waitcnt vmcnt(8)
	s_waitcnt lgkmcnt(0)
	s_barrier
	s_setprio 1
	s_waitcnt lgkmcnt(0)
	v_mfma_f32_16x16x32_bf16 v[124:127], v[128:131], v[176:179], v[124:127]
	v_mfma_f32_16x16x32_bf16 v[120:123], v[136:139], v[176:179], v[120:123]
	v_mfma_f32_16x16x32_bf16 v[108:111], v[128:131], v[194:197], v[108:111]
	v_mfma_f32_16x16x32_bf16 v[104:107], v[136:139], v[194:197], v[104:107]
	v_mfma_f32_16x16x32_bf16 v[92:95], v[128:131], v[204:207], v[92:95]
	v_mfma_f32_16x16x32_bf16 v[88:91], v[136:139], v[204:207], v[88:91]
	v_mfma_f32_16x16x32_bf16 v[76:79], v[128:131], v[212:215], v[76:79]
	v_mfma_f32_16x16x32_bf16 v[72:75], v[136:139], v[212:215], v[72:75]
	v_mfma_f32_16x16x32_bf16 v[124:127], v[132:135], v[180:183], v[124:127]
	v_mfma_f32_16x16x32_bf16 v[120:123], v[140:143], v[180:183], v[120:123]
	v_mfma_f32_16x16x32_bf16 v[108:111], v[132:135], v[200:203], v[108:111]
	v_mfma_f32_16x16x32_bf16 v[104:107], v[140:143], v[200:203], v[104:107]
	v_mfma_f32_16x16x32_bf16 v[92:95], v[132:135], v[208:211], v[92:95]
	v_mfma_f32_16x16x32_bf16 v[88:91], v[140:143], v[208:211], v[88:91]
	v_mfma_f32_16x16x32_bf16 v[76:79], v[132:135], v[216:219], v[76:79]
	v_mfma_f32_16x16x32_bf16 v[72:75], v[140:143], v[216:219], v[72:75]
	s_setprio 0
	s_setprio 1
	v_mfma_f32_16x16x32_bf16 v[116:119], v[144:147], v[176:179], v[116:119]
	v_mfma_f32_16x16x32_bf16 v[112:115], v[168:171], v[176:179], v[112:115]
	v_mfma_f32_16x16x32_bf16 v[100:103], v[144:147], v[194:197], v[100:103]
	v_mfma_f32_16x16x32_bf16 v[96:99], v[168:171], v[194:197], v[96:99]
	v_mfma_f32_16x16x32_bf16 v[84:87], v[144:147], v[204:207], v[84:87]
	v_mfma_f32_16x16x32_bf16 v[80:83], v[168:171], v[204:207], v[80:83]
	v_mfma_f32_16x16x32_bf16 v[68:71], v[144:147], v[212:215], v[68:71]
	v_mfma_f32_16x16x32_bf16 v[64:67], v[168:171], v[212:215], v[64:67]
	v_mfma_f32_16x16x32_bf16 v[116:119], v[148:151], v[180:183], v[116:119]
	v_mfma_f32_16x16x32_bf16 v[112:115], v[172:175], v[180:183], v[112:115]
	v_mfma_f32_16x16x32_bf16 v[100:103], v[148:151], v[200:203], v[100:103]
	v_mfma_f32_16x16x32_bf16 v[96:99], v[172:175], v[200:203], v[96:99]
	v_mfma_f32_16x16x32_bf16 v[84:87], v[148:151], v[208:211], v[84:87]
	v_mfma_f32_16x16x32_bf16 v[80:83], v[172:175], v[208:211], v[80:83]
	v_mfma_f32_16x16x32_bf16 v[68:71], v[148:151], v[216:219], v[68:71]
	v_mfma_f32_16x16x32_bf16 v[64:67], v[172:175], v[216:219], v[64:67]
	s_setprio 0
	s_barrier
	s_add_i32 s62, s83, s64

; #define PG8_STAGE(bufoff, gbase, voff) do { _Pragma("unroll") for (int _i = 0; _i < 2; ++_i) \
;         __builtin_amdgcn_global_load_lds((const unsigned*)((const char*)(gbase) + (voff)[_i]), (PG8_LAS unsigned*)(lds + (bufoff) + ldsw + _i * 8192), 16, 0, 0); } while (0)
; #define PG8_LDA(dst, b, h) do { _Pragma("unroll") for (int m = 0; m < 4; ++m) _Pragma("unroll") for (int k = 0; k < 2; ++k) dst[m][k] = *(const PG8_LAS bf16x8*)(lds + PG8_SA(b, h) + aoff + m * 2048 + k * 1024); } while (0)
; template <class Epi, class Sched, bool ALIGN_EPI = false, bool SP2 = false, bool ATILED = false>
; __device__ __forceinline__ void gemm_phase(PG8_LAS unsigned char* lds, const Gemm g, const Sched& S, const Epi& E) {
;     ...
;             PG8_LDA(At, 1, 1); PG8_STAGE(PG8_SB(1, 0), b3, voffB); PG8_STAGE(PG8_SB(1, 1), b3 + hstep, voffB); PG8_STAGE(PG8_SA(1, 0), a3, voffA);
	s_mov_b32 m0, s62
	ds_read_b128 v[176:179], v191 offset:49152
	ds_read_b128 v[180:183], v191 offset:50176
	ds_read_b128 v[194:197], v191 offset:51200
	ds_read_b128 v[200:203], v191 offset:52224
	ds_read_b128 v[204:207], v191 offset:53248
	ds_read_b128 v[208:211], v191 offset:54272
	ds_read_b128 v[212:215], v191 offset:55296
	ds_read_b128 v[216:219], v191 offset:56320
	global_load_lds_dwordx4 v154, s[98:99]
	s_add_i32 m0, s62, 0x2000
	s_add_u32 s60, s60, 0xb0080

; #define PG8_STAGE(bufoff, gbase, voff) do { _Pragma("unroll") for (int _i = 0; _i < 2; ++_i) \
;         __builtin_amdgcn_global_load_lds((const unsigned*)((const char*)(gbase) + (voff)[_i]), (PG8_LAS unsigned*)(lds + (bufoff) + ldsw + _i * 8192), 16, 0, 0); } while (0)
; #define PG8_LDA(dst, b, h) do { _Pragma("unroll") for (int m = 0; m < 4; ++m) _Pragma("unroll") for (int k = 0; k < 2; ++k) dst[m][k] = *(const PG8_LAS bf16x8*)(lds + PG8_SA(b, h) + aoff + m * 2048 + k * 1024); } while (0)
; template <class Epi, class Sched, bool ALIGN_EPI = false, bool SP2 = false, bool ATILED = false>
; __device__ __forceinline__ void gemm_phase(PG8_LAS unsigned char* lds, const Gemm g, const Sched& S, const Epi& E) {
;     ...
;             PG8_LDA(At, 1, 1); PG8_STAGE(PG8_SB(1, 0), b3, voffB); PG8_STAGE(PG8_SB(1, 1), b3 + hstep, voffB); PG8_STAGE(PG8_SA(1, 0), a3, voffA);
	s_addc_u32 s61, s61, 0
	s_add_i32 s62, s84, s64
	global_load_lds_dwordx4 v158, s[98:99]

; #define PG8_STAGE(bufoff, gbase, voff) do { _Pragma("unroll") for (int _i = 0; _i < 2; ++_i) \
;         __builtin_amdgcn_global_load_lds((const unsigned*)((const char*)(gbase) + (voff)[_i]), (PG8_LAS unsigned*)(lds + (bufoff) + ldsw + _i * 8192), 16, 0, 0); } while (0)
; #define PG8_LDA(dst, b, h) do { _Pragma("unroll") for (int m = 0; m < 4; ++m) _Pragma("unroll") for (int k = 0; k < 2; ++k) dst[m][k] = *(const PG8_LAS bf16x8*)(lds + PG8_SA(b, h) + aoff + m * 2048 + k * 1024); } while (0)
; template <class Epi, class Sched, bool ALIGN_EPI = false, bool SP2 = false, bool ATILED = false>
; __device__ __forceinline__ void gemm_phase(PG8_LAS unsigned char* lds, const Gemm g, const Sched& S, const Epi& E) {
;     ...
;             PG8_LDA(At, 1, 1); PG8_STAGE(PG8_SB(1, 0), b3, voffB); PG8_STAGE(PG8_SB(1, 1), b3 + hstep, voffB); PG8_STAGE(PG8_SA(1, 0), a3, voffA);
	s_mov_b32 m0, s62
	s_nop 0
	global_load_lds_dwordx4 v154, s[60:61]

; #define PG8_STAGE(bufoff, gbase, voff) do { _Pragma("unroll") for (int _i = 0; _i < 2; ++_i) \
;         __builtin_amdgcn_global_load_lds((const unsigned*)((const char*)(gbase) + (voff)[_i]), (PG8_LAS unsigned*)(lds + (bufoff) + ldsw + _i * 8192), 16, 0, 0); } while (0)
; #define PG8_LDA(dst, b, h) do { _Pragma("unroll") for (int m = 0; m < 4; ++m) _Pragma("unroll") for (int k = 0; k < 2; ++k) dst[m][k] = *(const PG8_LAS bf16x8*)(lds + PG8_SA(b, h) + aoff + m * 2048 + k * 1024); } while (0)
; template <class Epi, class Sched, bool ALIGN_EPI = false, bool SP2 = false, bool ATILED = false>
; __device__ __forceinline__ void gemm_phase(PG8_LAS unsigned char* lds, const Gemm g, const Sched& S, const Epi& E) {
;     ...
;             PG8_LDA(At, 1, 1); PG8_STAGE(PG8_SB(1, 0), b3, voffB); PG8_STAGE(PG8_SB(1, 1), b3 + hstep, voffB); PG8_STAGE(PG8_SA(1, 0), a3, voffA);
	s_add_i32 m0, s62, 0x2000
	s_nop 0
	global_load_lds_dwordx4 v158, s[60:61]

; #define PG8_STAGE(bufoff, gbase, voff) do { _Pragma("unroll") for (int _i = 0; _i < 2; ++_i) \
;         __builtin_amdgcn_global_load_lds((const unsigned*)((const char*)(gbase) + (voff)[_i]), (PG8_LAS unsigned*)(lds + (bufoff) + ldsw + _i * 8192), 16, 0, 0); } while (0)
; #define PG8_LDA(dst, b, h) do { _Pragma("unroll") for (int m = 0; m < 4; ++m) _Pragma("unroll") for (int k = 0; k < 2; ++k) dst[m][k] = *(const PG8_LAS bf16x8*)(lds + PG8_SA(b, h) + aoff + m * 2048 + k * 1024); } while (0)
; template <class Epi, class Sched, bool ALIGN_EPI = false, bool SP2 = false, bool ATILED = false>
; __device__ __forceinline__ void gemm_phase(PG8_LAS unsigned char* lds, const Gemm g, const Sched& S, const Epi& E) {
;     ...
;             PG8_LDA(At, 1, 1); PG8_STAGE(PG8_SB(1, 0), b3, voffB); PG8_STAGE(PG8_SB(1, 1), b3 + hstep, voffB); PG8_STAGE(PG8_SA(1, 0), a3, voffA);
	s_mov_b32 m0, s71
	s_nop 0
	global_load_lds_dwordx4 v152, s[48:49]

; #define PG8_STAGE(bufoff, gbase, voff) do { _Pragma("unroll") for (int _i = 0; _i < 2; ++_i) \
;         __builtin_amdgcn_global_load_lds((const unsigned*)((const char*)(gbase) + (voff)[_i]), (PG8_LAS unsigned*)(lds + (bufoff) + ldsw + _i * 8192), 16, 0, 0); } while (0)
; #define PG8_LDA(dst, b, h) do { _Pragma("unroll") for (int m = 0; m < 4; ++m) _Pragma("unroll") for (int k = 0; k < 2; ++k) dst[m][k] = *(const PG8_LAS bf16x8*)(lds + PG8_SA(b, h) + aoff + m * 2048 + k * 1024); } while (0)
; #define PG8_MMA(ai, bj, At, Bt) do { __builtin_amdgcn_s_setprio(1); _Pragma("unroll") for (int m = 0; m < 4; ++m) _Pragma("unroll") for (int n = 0; n < 2; ++n) _Pragma("unroll") for (int k = 0; k < 2; ++k) \
;         acc[ai][bj][m][n] = __builtin_amdgcn_mfma_f32_16x16x32_bf16(Bt[n][k], At[m][k], acc[ai][bj][m][n], 0, 0, 0); __builtin_amdgcn_s_setprio(0); } while (0)
; #define PG8_WAIT_V(n) asm volatile("s_waitcnt vmcnt(" #n ")" ::: "memory")
; #define PG8_WAIT_L(n) asm volatile("s_waitcnt lgkmcnt(" #n ")" ::: "memory")
; #define PG8_BAR __builtin_amdgcn_s_barrier()
; #define PG8_SCHED __builtin_amdgcn_sched_barrier(0)
; template <class Epi, class Sched, bool ALIGN_EPI = false, bool SP2 = false, bool ATILED = false>
; __device__ __forceinline__ void gemm_phase(PG8_LAS unsigned char* lds, const Gemm g, const Sched& S, const Epi& E) {
;     ...
;             PG8_LDA(At, 1, 1); PG8_STAGE(PG8_SB(1, 0), b3, voffB); PG8_STAGE(PG8_SB(1, 1), b3 + hstep, voffB); PG8_STAGE(PG8_SA(1, 0), a3, voffA);
;             PG8_WAIT_V(8); PG8_WAIT_L(0); PG8_BAR; PG8_MMA(1, 0, At, B0); PG8_MMA(1, 1, At, B1); PG8_BAR; PG8_SCHED;
	s_mov_b32 m0, s72
	s_nop 0
	global_load_lds_dwordx4 v156, s[48:49]
	s_waitcnt vmcnt(8)
	s_waitcnt lgkmcnt(0)
	s_barrier
	s_setprio 1
	s_waitcnt lgkmcnt(0)
	v_mfma_f32_16x16x32_bf16 v[60:63], v[128:131], v[176:179], v[60:63]
	v_mfma_f32_16x16x32_bf16 v[56:59], v[136:139], v[176:179], v[56:59]
	v_mfma_f32_16x16x32_bf16 v[44:47], v[128:131], v[194:197], v[44:47]
	v_mfma_f32_16x16x32_bf16 v[40:43], v[136:139], v[194:197], v[40:43]
	v_mfma_f32_16x16x32_bf16 v[28:31], v[128:131], v[204:207], v[28:31]
	v_mfma_f32_16x16x32_bf16 v[24:27], v[136:139], v[204:207], v[24:27]
	v_mfma_f32_16x16x32_bf16 v[12:15], v[128:131], v[212:215], v[12:15]
	v_mfma_f32_16x16x32_bf16 v[8:11], v[136:139], v[212:215], v[8:11]
	v_mfma_f32_16x16x32_bf16 v[60:63], v[132:135], v[180:183], v[60:63]
	v_mfma_f32_16x16x32_bf16 v[56:59], v[140:143], v[180:183], v[56:59]
	v_mfma_f32_16x16x32_bf16 v[44:47], v[132:135], v[200:203], v[44:47]
	v_mfma_f32_16x16x32_bf16 v[40:43], v[140:143], v[200:203], v[40:43]
	v_mfma_f32_16x16x32_bf16 v[28:31], v[132:135], v[208:211], v[28:31]
	v_mfma_f32_16x16x32_bf16 v[24:27], v[140:143], v[208:211], v[24:27]
	v_mfma_f32_16x16x32_bf16 v[12:15], v[132:135], v[216:219], v[12:15]
	v_mfma_f32_16x16x32_bf16 v[8:11], v[140:143], v[216:219], v[8:11]
	s_setprio 0
	s_setprio 1
	v_mfma_f32_16x16x32_bf16 v[52:55], v[144:147], v[176:179], v[52:55]
	v_mfma_f32_16x16x32_bf16 v[48:51], v[168:171], v[176:179], v[48:51]
	v_mfma_f32_16x16x32_bf16 v[36:39], v[144:147], v[194:197], v[36:39]
	v_mfma_f32_16x16x32_bf16 v[32:35], v[168:171], v[194:197], v[32:35]
	v_mfma_f32_16x16x32_bf16 v[20:23], v[144:147], v[204:207], v[20:23]
	v_mfma_f32_16x16x32_bf16 v[16:19], v[168:171], v[204:207], v[16:19]
	v_mfma_f32_16x16x32_bf16 v[4:7], v[144:147], v[212:215], v[4:7]
	v_mfma_f32_16x16x32_bf16 v[0:3], v[168:171], v[212:215], v[0:3]
	v_mfma_f32_16x16x32_bf16 v[52:55], v[148:151], v[180:183], v[52:55]
	v_mfma_f32_16x16x32_bf16 v[48:51], v[172:175], v[180:183], v[48:51]
	v_mfma_f32_16x16x32_bf16 v[36:39], v[148:151], v[200:203], v[36:39]
	v_mfma_f32_16x16x32_bf16 v[32:35], v[172:175], v[200:203], v[32:35]
	v_mfma_f32_16x16x32_bf16 v[20:23], v[148:151], v[208:211], v[20:23]
	v_mfma_f32_16x16x32_bf16 v[16:19], v[172:175], v[208:211], v[16:19]
	v_mfma_f32_16x16x32_bf16 v[4:7], v[148:151], v[216:219], v[4:7]
	v_mfma_f32_16x16x32_bf16 v[0:3], v[172:175], v[216:219], v[0:3]
	s_setprio 0
	s_barrier
	s_add_i32 s81, s81, 2
	s_add_u32 s79, s79, 0x100
	s_addc_u32 s80, s80, 0
	s_add_u32 s46, s46, 0x10000
	s_addc_u32 s47, s47, 0
	s_cmp_gt_u32 s81, 41

; #define PG8_BAR __builtin_amdgcn_s_barrier()
; template <class Epi, class Sched, bool ALIGN_EPI = false, bool SP2 = false, bool ATILED = false>
; __device__ __forceinline__ void gemm_phase(PG8_LAS unsigned char* lds, const Gemm g, const Sched& S, const Epi& E) {
;     ...
;         if constexpr (!Epi::AFTER_DRAIN) { E(acc, cur, wr, wc, fr, fq); S.done(cur); }
;         if (!has_next) break;
; #pragma unroll
;         for (int a = 0; a < 2; ++a)
; #pragma unroll
;             for (int b = 0; b < 2; ++b)
; #pragma unroll
;                 for (int m = 0; m < 4; ++m)
; #pragma unroll
;                     for (int n = 0; n < 2; ++n) acc[a][b][m][n] = (f32x4){0.f, 0.f, 0.f, 0.f};
;         cur = nxt; cA = nA; cB = nB; ++ui;
;         if constexpr (ALIGN_EPI) { if (wr == 1) PG8_BAR; }
;     }
.LBB0_230:
	s_or_b64 exec, exec, s[48:49]
	s_and_b64 vcc, exec, s[6:7]
	s_mov_b64 s[6:7], -1
	s_cbranch_vccnz .LBB0_199
	s_branch .LBB0_198

; template <class Epi, class Sched, bool ALIGN_EPI = false, bool SP2 = false, bool ATILED = false>
; __device__ __forceinline__ void gemm_phase(PG8_LAS unsigned char* lds, const Gemm g, const Sched& S, const Epi& E) {
;     const int tid = threadIdx.x, wid = __builtin_amdgcn_readfirstlane(tid >> 6), lane = tid & 63, wr = wid >> 2, wc = wid & 3, fr = lane & 15, fq = lane >> 4;
;     const int K = g.K, nt = K / BK;
;     unsigned voffA[2], voffB[2];
; #pragma unroll
;     for (int i = 0; i < 2; ++i) { int R, C; stage_rc(tid * 16 + i * 8192, R, C); const int Rb = Epi::PERM ? ((R & ~31) + perm32(R & 31)) : R;
;         voffA[i] = (unsigned)(R * (ATILED ? BK : K) + C) * 2u; voffB[i] = (unsigned)(Rb * K + C) * 2u; }
;     const size_t kstep = (size_t)(BK * 2);
;     const size_t hstep = (size_t)HALF * K * 2;
;     const size_t tstep = 2 * hstep;
;     const size_t kstepA = ATILED ? (size_t)(BM * BK * 2) : kstep, hstepA = ATILED ? (size_t)(HALF * BK * 2) : hstep, tstepA = ATILED ? (size_t)nt * (BM * BK * 2) : tstep;
;     const unsigned ldsw = (unsigned)wid * 1024u;
;     const int aoff = lds_byte(wr * 64 + fr, fq * 8), boff = lds_byte(wc * 32 + fr, fq * 8);
;     ...
;     Unit cur, nxt; int ui = 0;
;     if (!S.next(0, cur)) return;
;     f32x4 acc[2][2][4][2];
; #pragma unroll
;     for (int a = 0; a < 2; ++a)
; #pragma unroll
;         for (int b = 0; b < 2; ++b)
; #pragma unroll
;             for (int m = 0; m < 4; ++m)
; #pragma unroll
;                 for (int n = 0; n < 2; ++n) acc[a][b][m][n] = (f32x4){0.f, 0.f, 0.f, 0.f};
;     bf16x8 At[4][2], B0[2][2], B1[2][2];
;     const char* cA = (const char*)g.A + (size_t)cur.pm * tstepA; const char* cB = (const char*)g.Bt + (size_t)cur.pn * tstep;
;     S.a_ready(cur);
;     if constexpr (SP2) {
;         PG8_STAGE(PG8_SB(0, 0), cB, voffB); PG8_STAGE(PG8_SB(0, 1), cB + hstep, voffB); PG8_STAGE(PG8_SA(0, 0), cA, voffA); PG8_STAGE(PG8_SA(0, 1), cA + hstepA, voffA);
;         if (wr == 1) PG8_BAR;
;         PG8_WAIT_V(2); PG8_BAR;
;         PG8_STAGE(PG8_SB(1, 0), cB + kstep, voffB); PG8_STAGE(PG8_SA(1, 0), cA + kstepA, voffA); PG8_STAGE(PG8_SB(1, 1), cB + hstep + kstep, voffB);
;         PG8_WAIT_V(6); PG8_BAR;
;     } else {
;         PG8_STAGE(PG8_SB(0, 0), cB, voffB); PG8_STAGE(PG8_SA(0, 0), cA, voffA); PG8_STAGE(PG8_SB(0, 1), cB + hstep, voffB); PG8_STAGE(PG8_SA(0, 1), cA + hstepA, voffA);
.LBB0_288:
	v_lshrrev_b32_e32 v2, 1, v198
	v_lshrrev_b32_e32 v3, 5, v198
	v_and_b32_e32 v2, 24, v2
	v_and_b32_e32 v3, 4, v3
	v_bfe_u32 v4, v198, 2, 2
	v_lshlrev_b32_e32 v0, 4, v198
	s_waitcnt lgkmcnt(0)
	v_and_b32_e32 v1, 32, v198
	v_bfe_u32 v10, v198, 2, 4
	v_or3_b32 v2, v3, v4, v2
	v_lshrrev_b32_e32 v3, 3, v198
	s_movk_i32 s0, 0x70
	v_bitop3_b32 v8, v0, v1, 48 bitop3:0x6c
	v_and_b32_e32 v9, 64, v198
	v_and_or_b32 v4, v3, s0, v10
	s_movk_i32 s0, 0x60
	v_add_u32_e32 v11, 0x2000, v0
	v_or_b32_e32 v1, v8, v9
	v_and_or_b32 v3, v3, s0, v2
	v_lshrrev_b32_e32 v0, 7, v11
	s_movk_i32 s0, 0xf0
	v_lshl_or_b32 v130, v3, 11, v1
	v_and_or_b32 v3, v0, s0, v10
	s_movk_i32 s0, 0xe0
	v_and_or_b32 v0, v0, s0, v2
	s_lshr_b32 s0, s6, 6
	s_ashr_i32 s5, s4, 31
	s_ashr_i32 s63, s62, 31
	s_lshr_b32 s1, s6, 8
	s_lshl_b32 s70, s0, 10
	s_lshl_b64 s[8:9], s[4:5], 19
	s_lshl_b64 s[38:39], s[62:63], 19
	s_add_u32 s66, s54, s38
	s_addc_u32 s67, s55, s39
	s_add_i32 s71, s70, 0
	s_add_i32 m0, s71, 0x10000
	v_lshl_or_b32 v134, v0, 11, v1
	global_load_lds_dwordx4 v130, s[66:67]
	s_add_i32 m0, s71, 0x12000
	s_add_u32 s38, s66, 0x40000
	global_load_lds_dwordx4 v134, s[66:67]
	s_addc_u32 s39, s67, 0
	s_add_i32 m0, s71, 0x14000
	v_lshl_or_b32 v128, v4, 11, v1
	global_load_lds_dwordx4 v130, s[38:39]
	s_add_i32 m0, s71, 0x16000
	s_add_u32 s64, s26, s8
	s_addc_u32 s65, s27, s9
	s_add_i32 s72, s71, 0x2000
	global_load_lds_dwordx4 v134, s[38:39]
	s_mov_b32 m0, s71
	s_add_u32 s8, s64, 0x40000
	v_lshl_or_b32 v132, v3, 11, v1
	global_load_lds_dwordx4 v128, s[64:65]
	s_mov_b32 m0, s72
	s_addc_u32 s9, s65, 0
	s_add_i32 s73, s71, 0x4000
	global_load_lds_dwordx4 v132, s[64:65]
	s_mov_b32 m0, s73
	s_add_i32 s74, s71, 0x6000
	global_load_lds_dwordx4 v128, s[8:9]
	s_mov_b32 m0, s74
	v_mov_b32_e32 v137, 0
	global_load_lds_dwordx4 v132, s[8:9]
	v_mov_b32_e32 v131, v137
	v_mov_b32_e32 v135, v137
	v_mov_b32_e32 v129, v137
	v_mov_b32_e32 v133, v137
	s_cmp_eq_u32 s1, 1
	s_mov_b32 s7, 0
	v_lshl_add_u64 v[6:7], s[66:67], 0, v[130:131]
	v_lshl_add_u64 v[4:5], s[66:67], 0, v[134:135]
	v_lshl_add_u64 v[0:1], s[64:65], 0, v[128:129]
	s_cselect_b64 s[8:9], -1, 0
	s_cmp_lg_u32 s1, 1
	v_lshl_add_u64 v[2:3], s[64:65], 0, v[132:133]
.LBB0_290:
	s_mov_b64 s[38:39], 0x80
	s_and_b32 s5, s0, 3
	s_add_i32 m0, s71, 0x18000
	v_lshl_add_u64 v[6:7], v[6:7], 0, s[38:39]
	s_ashr_i32 s75, s28, 31
	s_lshl_b32 s44, s1, 13
	s_lshl_b32 s76, s5, 5
	s_lshl_b32 s5, s5, 12
	s_waitcnt vmcnt(2)
	s_barrier
	global_load_lds_dwordx4 v[6:7], off
	v_lshl_add_u64 v[4:5], v[4:5], 0, s[38:39]
	s_add_i32 m0, s71, 0x1a000
	s_add_i32 s77, s71, 0x8000
	s_add_i32 s78, s71, 0xa000
	global_load_lds_dwordx4 v[4:5], off
	v_lshl_add_u64 v[0:1], v[0:1], 0, s[38:39]
	s_mov_b32 m0, s77
	s_add_u32 s40, s66, 0x40080
	global_load_lds_dwordx4 v[0:1], off
	v_lshl_add_u64 v[0:1], v[2:3], 0, s[38:39]
	s_mov_b32 m0, s78
	s_addc_u32 s41, s67, 0
	global_load_lds_dwordx4 v[0:1], off
	s_add_i32 m0, s71, 0x1c000
	v_lshl_add_u64 v[0:1], s[40:41], 0, v[130:131]
	global_load_lds_dwordx4 v[0:1], off
	v_lshl_add_u64 v[0:1], s[40:41], 0, v[134:135]
	s_add_i32 m0, s71, 0x1e000
	v_lshlrev_b32_e32 v2, 6, v198
	global_load_lds_dwordx4 v[0:1], off
	v_bfe_u32 v1, v198, 4, 2
	v_and_b32_e32 v0, 15, v198
	v_lshlrev_b32_e32 v136, 4, v1
	s_movk_i32 s40, 0x3c0
	v_lshlrev_b32_e32 v3, 2, v198
	s_cmpk_lt_u32 s6, 0x100
	v_lshlrev_b32_e32 v138, 3, v1
	v_and_or_b32 v2, v2, s40, v136
	v_and_b32_e32 v3, 32, v3
	v_lshlrev_b32_e32 v1, 2, v1
	v_lshl_or_b32 v139, s1, 6, v0
	v_lshl_or_b32 v0, v0, 6, v136
	s_cselect_b64 s[40:41], -1, 0
	s_lshl_b32 s0, s0, 4
	v_bitop3_b32 v4, v0, s44, v3 bitop3:0xde
	v_and_or_b32 v0, s0, 16, v1
	v_lshl_add_u64 v[140:141], s[10:11], 0, v[136:137]
	v_lshlrev_b32_e32 v136, 2, v0
	v_bitop3_b32 v200, s5, v2, v3 bitop3:0xf6
	v_lshl_add_u64 v[2:3], s[26:27], 0, v[136:137]
	s_mov_b64 s[0:1], 0x24800000
	v_lshl_add_u64 v[142:143], v[2:3], 0, s[0:1]
	s_mov_b64 s[0:1], 0x24840000
	v_lshlrev_b32_e32 v1, 8, v198
	v_lshl_add_u64 v[144:145], v[2:3], 0, s[0:1]
	v_and_b32_e32 v1, 0x38000, v1
	v_lshlrev_b32_e32 v2, 11, v10
	v_or3_b32 v1, v8, v1, v2
	v_add_u32_e32 v146, v1, v9
	v_lshlrev_b32_e32 v1, 4, v11
	v_and_b32_e32 v1, 0x78000, v1
	s_waitcnt vmcnt(6)
	v_or3_b32 v1, v8, v1, v2
	s_and_b32 s5, s76, 64
	v_add_u32_e32 v148, v1, v9
	s_add_i32 s79, 0, 0x10000
	s_add_i32 s80, 0, 0x14000
	v_mbcnt_lo_u32_b32 v1, -1, 0
	v_mov_b32_e32 v147, v137
	v_mov_b32_e32 v149, v137
	v_mov_b64_e32 v[150:151], 0x800
	v_mov_b64_e32 v[152:153], 0x7ff
	v_add_u32_e32 v201, s79, v200
	v_add_u32_e32 v202, s80, v200
	v_add_u32_e32 v203, 0, v4
	v_mbcnt_hi_u32_b32 v204, -1, v1
	v_mov_b32_e32 v205, 0x358637bd
	s_lshl_b32 s44, s5, 1
	v_lshlrev_b32_e32 v154, 1, v0
	v_mov_b32_e32 v206, 0x3e000000
	v_mov_b32_e32 v207, 0x1000
	s_mov_b32 s81, 0
	s_barrier
	s_branch .LBB0_293

; #define PG8_STAGE(bufoff, gbase, voff) do { _Pragma("unroll") for (int _i = 0; _i < 2; ++_i) \
;         __builtin_amdgcn_global_load_lds((const unsigned*)((const char*)(gbase) + (voff)[_i]), (PG8_LAS unsigned*)(lds + (bufoff) + ldsw + _i * 8192), 16, 0, 0); } while (0)
; #define PG8_LDA(dst, b, h) do { _Pragma("unroll") for (int m = 0; m < 4; ++m) _Pragma("unroll") for (int k = 0; k < 2; ++k) dst[m][k] = *(const PG8_LAS bf16x8*)(lds + PG8_SA(b, h) + aoff + m * 2048 + k * 1024); } while (0)
; #define PG8_LDB(dst, b, h) do { _Pragma("unroll") for (int n = 0; n < 2; ++n) _Pragma("unroll") for (int k = 0; k < 2; ++k) dst[n][k] = *(const PG8_LAS bf16x8*)(lds + PG8_SB(b, h) + boff + n * 2048 + k * 1024); } while (0)
; #define PG8_SCHED __builtin_amdgcn_sched_barrier(0)
; template <class Epi, class Sched, bool ALIGN_EPI = false, bool SP2 = false, bool ATILED = false>
; __device__ __forceinline__ void gemm_phase(PG8_LAS unsigned char* lds, const Gemm g, const Sched& S, const Epi& E) {
;     ...
;         const bool has_next = S.next(ui + 1, nxt);
;         const char* nA = has_next ? (const char*)g.A + (size_t)nxt.pm * tstepA : cA; const char* nB = has_next ? (const char*)g.Bt + (size_t)nxt.pn * tstep : cB;
;         for (int t = 0; t < nt; t += 2) {
;             const bool last = (t == nt - 2);
;             const char* a1 = cA + (size_t)(t + 1) * kstepA;
;             const char* a2 = last ? nA : cA + (size_t)(t + 2) * kstepA; const char* b2 = last ? nB : cB + (size_t)(t + 2) * kstep;
;             const char* a3 = a2 + kstepA; const char* b3 = b2 + kstep;
;             if (last && has_next) S.a_ready(nxt);
;             if constexpr (SP2) {
;             PG8_LDB(B0, 0, 0); PG8_LDB(B1, 0, 1); PG8_SCHED; PG8_LDA(At, 0, 0); PG8_STAGE(PG8_SA(1, 1), a1 + hstepA, voffA);
.LBB0_299:
	s_ashr_i32 s49, s48, 31
	s_lshl_b64 s[58:59], s[48:49], 19
	s_add_u32 s58, s26, s58
	s_addc_u32 s59, s27, s59
	s_and_b64 s[60:61], s[0:1], exec
	s_cselect_b32 s5, s59, s65
	s_cselect_b32 s6, s58, s64
	s_ashr_i32 s47, s46, 31
	s_lshl_b64 s[60:61], s[46:47], 19
	s_add_u32 s60, s54, s60
	s_addc_u32 s61, s55, s61
	s_and_b64 s[68:69], s[0:1], exec
	s_cselect_b32 s45, s61, s67
	s_cselect_b32 s47, s60, s66
	s_add_u32 s64, s64, 0x40080
	s_addc_u32 s65, s65, 0
	s_add_u32 s49, s66, 0x100
	s_addc_u32 s63, s67, 0
	s_mov_b32 s83, -2
	s_cmp_lg_u64 s[8:9], 0
	s_cbranch_scc0 .Ltbar_skip2
	s_barrier
.Ltbar_skip2:
	ds_read_b128 v[156:159], v201
	ds_read_b128 v[160:163], v201 offset:1024
	ds_read_b128 v[164:167], v201 offset:2048
	ds_read_b128 v[168:171], v201 offset:3072
	ds_read_b128 v[172:175], v202
	ds_read_b128 v[176:179], v202 offset:1024
	ds_read_b128 v[180:183], v202 offset:2048
	ds_read_b128 v[184:187], v202 offset:3072
	s_add_u32 s66, s64, 0xfffc0080
	s_addc_u32 s67, s65, -1
	s_cmp_eq_u32 s83, 12
	s_cselect_b32 s69, s5, s67
	s_cselect_b32 s68, s6, s66
	s_cselect_b32 s67, s45, s63
	s_cselect_b32 s66, s47, s49

; #define PG8_STAGE(bufoff, gbase, voff) do { _Pragma("unroll") for (int _i = 0; _i < 2; ++_i) \
;         __builtin_amdgcn_global_load_lds((const unsigned*)((const char*)(gbase) + (voff)[_i]), (PG8_LAS unsigned*)(lds + (bufoff) + ldsw + _i * 8192), 16, 0, 0); } while (0)
; #define PG8_LDA(dst, b, h) do { _Pragma("unroll") for (int m = 0; m < 4; ++m) _Pragma("unroll") for (int k = 0; k < 2; ++k) dst[m][k] = *(const PG8_LAS bf16x8*)(lds + PG8_SA(b, h) + aoff + m * 2048 + k * 1024); } while (0)
; #define PG8_LDB(dst, b, h) do { _Pragma("unroll") for (int n = 0; n < 2; ++n) _Pragma("unroll") for (int k = 0; k < 2; ++k) dst[n][k] = *(const PG8_LAS bf16x8*)(lds + PG8_SB(b, h) + boff + n * 2048 + k * 1024); } while (0)
; #define PG8_SCHED __builtin_amdgcn_sched_barrier(0)
; template <class Epi, class Sched, bool ALIGN_EPI = false, bool SP2 = false, bool ATILED = false>
; __device__ __forceinline__ void gemm_phase(PG8_LAS unsigned char* lds, const Gemm g, const Sched& S, const Epi& E) {
;     ...
;             PG8_LDB(B0, 0, 0); PG8_LDB(B1, 0, 1); PG8_SCHED; PG8_LDA(At, 0, 0); PG8_STAGE(PG8_SA(1, 1), a1 + hstepA, voffA);
	s_add_i32 m0, s71, 0xc000
	ds_read_b128 v[188:191], v203
	ds_read_b128 v[192:195], v203 offset:1024
	ds_read_b128 v[208:211], v203 offset:2048
	ds_read_b128 v[212:215], v203 offset:3072
	ds_read_b128 v[216:219], v203 offset:4096
	ds_read_b128 v[220:223], v203 offset:5120
	ds_read_b128 v[224:227], v203 offset:6144
	ds_read_b128 v[228:231], v203 offset:7168
	global_load_lds_dwordx4 v146, s[64:65]

; #define PG8_STAGE(bufoff, gbase, voff) do { _Pragma("unroll") for (int _i = 0; _i < 2; ++_i) \
;         __builtin_amdgcn_global_load_lds((const unsigned*)((const char*)(gbase) + (voff)[_i]), (PG8_LAS unsigned*)(lds + (bufoff) + ldsw + _i * 8192), 16, 0, 0); } while (0)
; #define PG8_LDA(dst, b, h) do { _Pragma("unroll") for (int m = 0; m < 4; ++m) _Pragma("unroll") for (int k = 0; k < 2; ++k) dst[m][k] = *(const PG8_LAS bf16x8*)(lds + PG8_SA(b, h) + aoff + m * 2048 + k * 1024); } while (0)
; #define PG8_LDB(dst, b, h) do { _Pragma("unroll") for (int n = 0; n < 2; ++n) _Pragma("unroll") for (int k = 0; k < 2; ++k) dst[n][k] = *(const PG8_LAS bf16x8*)(lds + PG8_SB(b, h) + boff + n * 2048 + k * 1024); } while (0)
; #define PG8_MMA(ai, bj, At, Bt) do { __builtin_amdgcn_s_setprio(1); _Pragma("unroll") for (int m = 0; m < 4; ++m) _Pragma("unroll") for (int n = 0; n < 2; ++n) _Pragma("unroll") for (int k = 0; k < 2; ++k) \
;         acc[ai][bj][m][n] = __builtin_amdgcn_mfma_f32_16x16x32_bf16(Bt[n][k], At[m][k], acc[ai][bj][m][n], 0, 0, 0); __builtin_amdgcn_s_setprio(0); } while (0)
; #define PG8_WAIT_V(n) asm volatile("s_waitcnt vmcnt(" #n ")" ::: "memory")
; #define PG8_WAIT_L(n) asm volatile("s_waitcnt lgkmcnt(" #n ")" ::: "memory")
; #define PG8_BAR __builtin_amdgcn_s_barrier()
; #define PG8_SCHED __builtin_amdgcn_sched_barrier(0)
; template <class Epi, class Sched, bool ALIGN_EPI = false, bool SP2 = false, bool ATILED = false>
; __device__ __forceinline__ void gemm_phase(PG8_LAS unsigned char* lds, const Gemm g, const Sched& S, const Epi& E) {
;     ...
;             PG8_LDB(B0, 0, 0); PG8_LDB(B1, 0, 1); PG8_SCHED; PG8_LDA(At, 0, 0); PG8_STAGE(PG8_SA(1, 1), a1 + hstepA, voffA);
;             PG8_WAIT_V(8); PG8_WAIT_L(0); PG8_BAR; PG8_MMA(0, 0, At, B0); PG8_MMA(0, 1, At, B1); PG8_BAR; PG8_SCHED;
	s_add_i32 m0, s71, 0xe000
	s_nop 0
	global_load_lds_dwordx4 v148, s[64:65]
	s_waitcnt vmcnt(8)
	s_waitcnt lgkmcnt(0)
	s_barrier
	s_setprio 1
	s_waitcnt lgkmcnt(0)
	v_mfma_f32_16x16x32_bf16 v[124:127], v[156:159], v[188:191], 0
	v_mfma_f32_16x16x32_bf16 v[120:123], v[164:167], v[188:191], 0
	v_mfma_f32_16x16x32_bf16 v[116:119], v[156:159], v[208:211], 0
	v_mfma_f32_16x16x32_bf16 v[112:115], v[164:167], v[208:211], 0
	v_mfma_f32_16x16x32_bf16 v[96:99], v[156:159], v[216:219], 0
	v_mfma_f32_16x16x32_bf16 v[88:91], v[164:167], v[216:219], 0
	v_mfma_f32_16x16x32_bf16 v[80:83], v[156:159], v[224:227], 0
	v_mfma_f32_16x16x32_bf16 v[72:75], v[164:167], v[224:227], 0
	v_mfma_f32_16x16x32_bf16 v[124:127], v[160:163], v[192:195], v[124:127]
	v_mfma_f32_16x16x32_bf16 v[120:123], v[168:171], v[192:195], v[120:123]
	v_mfma_f32_16x16x32_bf16 v[116:119], v[160:163], v[212:215], v[116:119]
	v_mfma_f32_16x16x32_bf16 v[112:115], v[168:171], v[212:215], v[112:115]
	v_mfma_f32_16x16x32_bf16 v[96:99], v[160:163], v[220:223], v[96:99]
	v_mfma_f32_16x16x32_bf16 v[88:91], v[168:171], v[220:223], v[88:91]
	v_mfma_f32_16x16x32_bf16 v[80:83], v[160:163], v[228:231], v[80:83]
	v_mfma_f32_16x16x32_bf16 v[72:75], v[168:171], v[228:231], v[72:75]
	s_setprio 0
	s_setprio 1
	v_mfma_f32_16x16x32_bf16 v[108:111], v[172:175], v[188:191], 0
	v_mfma_f32_16x16x32_bf16 v[104:107], v[180:183], v[188:191], 0
	v_mfma_f32_16x16x32_bf16 v[100:103], v[172:175], v[208:211], 0
	v_mfma_f32_16x16x32_bf16 v[92:95], v[180:183], v[208:211], 0
	v_mfma_f32_16x16x32_bf16 v[84:87], v[172:175], v[216:219], 0
	v_mfma_f32_16x16x32_bf16 v[76:79], v[180:183], v[216:219], 0
	v_mfma_f32_16x16x32_bf16 v[68:71], v[172:175], v[224:227], 0
	v_mfma_f32_16x16x32_bf16 v[64:67], v[180:183], v[224:227], 0
	v_mfma_f32_16x16x32_bf16 v[108:111], v[176:179], v[192:195], v[108:111]
	v_mfma_f32_16x16x32_bf16 v[104:107], v[184:187], v[192:195], v[104:107]
	v_mfma_f32_16x16x32_bf16 v[100:103], v[176:179], v[212:215], v[100:103]
	v_mfma_f32_16x16x32_bf16 v[92:95], v[184:187], v[212:215], v[92:95]
	v_mfma_f32_16x16x32_bf16 v[84:87], v[176:179], v[220:223], v[84:87]
	v_mfma_f32_16x16x32_bf16 v[76:79], v[184:187], v[220:223], v[76:79]
	v_mfma_f32_16x16x32_bf16 v[68:71], v[176:179], v[228:231], v[68:71]
	v_mfma_f32_16x16x32_bf16 v[64:67], v[184:187], v[228:231], v[64:67]
	s_setprio 0
	s_barrier
	s_add_u32 s98, s66, s38
	s_addc_u32 s99, s67, s39
	s_add_u32 s100, s68, s38
	s_addc_u32 s101, s69, s39
	s_add_i32 s84, s79, s70

; #define PG8_STAGE(bufoff, gbase, voff) do { _Pragma("unroll") for (int _i = 0; _i < 2; ++_i) \
;         __builtin_amdgcn_global_load_lds((const unsigned*)((const char*)(gbase) + (voff)[_i]), (PG8_LAS unsigned*)(lds + (bufoff) + ldsw + _i * 8192), 16, 0, 0); } while (0)
; #define PG8_LDA(dst, b, h) do { _Pragma("unroll") for (int m = 0; m < 4; ++m) _Pragma("unroll") for (int k = 0; k < 2; ++k) dst[m][k] = *(const PG8_LAS bf16x8*)(lds + PG8_SA(b, h) + aoff + m * 2048 + k * 1024); } while (0)
; template <class Epi, class Sched, bool ALIGN_EPI = false, bool SP2 = false, bool ATILED = false>
; __device__ __forceinline__ void gemm_phase(PG8_LAS unsigned char* lds, const Gemm g, const Sched& S, const Epi& E) {
;     ...
;             PG8_LDA(At, 0, 1); PG8_STAGE(PG8_SB(0, 0), b2, voffB); PG8_STAGE(PG8_SB(0, 1), b2 + hstep, voffB); PG8_STAGE(PG8_SA(0, 0), a2, voffA);
	s_mov_b32 m0, s84
	ds_read_b128 v[188:191], v203 offset:16384
	ds_read_b128 v[192:195], v203 offset:17408
	ds_read_b128 v[208:211], v203 offset:18432
	ds_read_b128 v[212:215], v203 offset:19456
	ds_read_b128 v[216:219], v203 offset:20480
	ds_read_b128 v[220:223], v203 offset:21504
	ds_read_b128 v[224:227], v203 offset:22528
	ds_read_b128 v[228:231], v203 offset:23552
	global_load_lds_dwordx4 v130, s[66:67]
	s_add_i32 m0, s84, 0x2000
	s_add_u32 s84, s66, 0x40000

; #define PG8_STAGE(bufoff, gbase, voff) do { _Pragma("unroll") for (int _i = 0; _i < 2; ++_i) \
;         __builtin_amdgcn_global_load_lds((const unsigned*)((const char*)(gbase) + (voff)[_i]), (PG8_LAS unsigned*)(lds + (bufoff) + ldsw + _i * 8192), 16, 0, 0); } while (0)
; #define PG8_LDA(dst, b, h) do { _Pragma("unroll") for (int m = 0; m < 4; ++m) _Pragma("unroll") for (int k = 0; k < 2; ++k) dst[m][k] = *(const PG8_LAS bf16x8*)(lds + PG8_SA(b, h) + aoff + m * 2048 + k * 1024); } while (0)
; template <class Epi, class Sched, bool ALIGN_EPI = false, bool SP2 = false, bool ATILED = false>
; __device__ __forceinline__ void gemm_phase(PG8_LAS unsigned char* lds, const Gemm g, const Sched& S, const Epi& E) {
;     ...
;             PG8_LDA(At, 0, 1); PG8_STAGE(PG8_SB(0, 0), b2, voffB); PG8_STAGE(PG8_SB(0, 1), b2 + hstep, voffB); PG8_STAGE(PG8_SA(0, 0), a2, voffA);
	s_addc_u32 s85, s67, 0
	s_add_i32 s86, s80, s70
	global_load_lds_dwordx4 v134, s[66:67]

; #define PG8_STAGE(bufoff, gbase, voff) do { _Pragma("unroll") for (int _i = 0; _i < 2; ++_i) \
;         __builtin_amdgcn_global_load_lds((const unsigned*)((const char*)(gbase) + (voff)[_i]), (PG8_LAS unsigned*)(lds + (bufoff) + ldsw + _i * 8192), 16, 0, 0); } while (0)
; #define PG8_LDA(dst, b, h) do { _Pragma("unroll") for (int m = 0; m < 4; ++m) _Pragma("unroll") for (int k = 0; k < 2; ++k) dst[m][k] = *(const PG8_LAS bf16x8*)(lds + PG8_SA(b, h) + aoff + m * 2048 + k * 1024); } while (0)
; template <class Epi, class Sched, bool ALIGN_EPI = false, bool SP2 = false, bool ATILED = false>
; __device__ __forceinline__ void gemm_phase(PG8_LAS unsigned char* lds, const Gemm g, const Sched& S, const Epi& E) {
;     ...
;             PG8_LDA(At, 0, 1); PG8_STAGE(PG8_SB(0, 0), b2, voffB); PG8_STAGE(PG8_SB(0, 1), b2 + hstep, voffB); PG8_STAGE(PG8_SA(0, 0), a2, voffA);
	s_mov_b32 m0, s86

; #define PG8_STAGE(bufoff, gbase, voff) do { _Pragma("unroll") for (int _i = 0; _i < 2; ++_i) \
;         __builtin_amdgcn_global_load_lds((const unsigned*)((const char*)(gbase) + (voff)[_i]), (PG8_LAS unsigned*)(lds + (bufoff) + ldsw + _i * 8192), 16, 0, 0); } while (0)
; #define PG8_LDA(dst, b, h) do { _Pragma("unroll") for (int m = 0; m < 4; ++m) _Pragma("unroll") for (int k = 0; k < 2; ++k) dst[m][k] = *(const PG8_LAS bf16x8*)(lds + PG8_SA(b, h) + aoff + m * 2048 + k * 1024); } while (0)
; template <class Epi, class Sched, bool ALIGN_EPI = false, bool SP2 = false, bool ATILED = false>
; __device__ __forceinline__ void gemm_phase(PG8_LAS unsigned char* lds, const Gemm g, const Sched& S, const Epi& E) {
;     ...
;             PG8_LDA(At, 0, 1); PG8_STAGE(PG8_SB(0, 0), b2, voffB); PG8_STAGE(PG8_SB(0, 1), b2 + hstep, voffB); PG8_STAGE(PG8_SA(0, 0), a2, voffA);
	s_nop 0
	global_load_lds_dwordx4 v130, s[84:85]

; #define PG8_STAGE(bufoff, gbase, voff) do { _Pragma("unroll") for (int _i = 0; _i < 2; ++_i) \
;         __builtin_amdgcn_global_load_lds((const unsigned*)((const char*)(gbase) + (voff)[_i]), (PG8_LAS unsigned*)(lds + (bufoff) + ldsw + _i * 8192), 16, 0, 0); } while (0)
; #define PG8_LDA(dst, b, h) do { _Pragma("unroll") for (int m = 0; m < 4; ++m) _Pragma("unroll") for (int k = 0; k < 2; ++k) dst[m][k] = *(const PG8_LAS bf16x8*)(lds + PG8_SA(b, h) + aoff + m * 2048 + k * 1024); } while (0)
; template <class Epi, class Sched, bool ALIGN_EPI = false, bool SP2 = false, bool ATILED = false>
; __device__ __forceinline__ void gemm_phase(PG8_LAS unsigned char* lds, const Gemm g, const Sched& S, const Epi& E) {
;     ...
;             PG8_LDA(At, 0, 1); PG8_STAGE(PG8_SB(0, 0), b2, voffB); PG8_STAGE(PG8_SB(0, 1), b2 + hstep, voffB); PG8_STAGE(PG8_SA(0, 0), a2, voffA);
	s_add_i32 m0, s86, 0x2000
	s_nop 0
	global_load_lds_dwordx4 v134, s[84:85]

; #define PG8_STAGE(bufoff, gbase, voff) do { _Pragma("unroll") for (int _i = 0; _i < 2; ++_i) \
;         __builtin_amdgcn_global_load_lds((const unsigned*)((const char*)(gbase) + (voff)[_i]), (PG8_LAS unsigned*)(lds + (bufoff) + ldsw + _i * 8192), 16, 0, 0); } while (0)
; #define PG8_LDA(dst, b, h) do { _Pragma("unroll") for (int m = 0; m < 4; ++m) _Pragma("unroll") for (int k = 0; k < 2; ++k) dst[m][k] = *(const PG8_LAS bf16x8*)(lds + PG8_SA(b, h) + aoff + m * 2048 + k * 1024); } while (0)
; #define PG8_LDB(dst, b, h) do { _Pragma("unroll") for (int n = 0; n < 2; ++n) _Pragma("unroll") for (int k = 0; k < 2; ++k) dst[n][k] = *(const PG8_LAS bf16x8*)(lds + PG8_SB(b, h) + boff + n * 2048 + k * 1024); } while (0)
; #define PG8_MMA(ai, bj, At, Bt) do { __builtin_amdgcn_s_setprio(1); _Pragma("unroll") for (int m = 0; m < 4; ++m) _Pragma("unroll") for (int n = 0; n < 2; ++n) _Pragma("unroll") for (int k = 0; k < 2; ++k) \
;         acc[ai][bj][m][n] = __builtin_amdgcn_mfma_f32_16x16x32_bf16(Bt[n][k], At[m][k], acc[ai][bj][m][n], 0, 0, 0); __builtin_amdgcn_s_setprio(0); } while (0)
; #define PG8_WAIT_V(n) asm volatile("s_waitcnt vmcnt(" #n ")" ::: "memory")
; #define PG8_WAIT_L(n) asm volatile("s_waitcnt lgkmcnt(" #n ")" ::: "memory")
; #define PG8_BAR __builtin_amdgcn_s_barrier()
; #define PG8_SCHED __builtin_amdgcn_sched_barrier(0)
; template <class Epi, class Sched, bool ALIGN_EPI = false, bool SP2 = false, bool ATILED = false>
; __device__ __forceinline__ void gemm_phase(PG8_LAS unsigned char* lds, const Gemm g, const Sched& S, const Epi& E) {
;     ...
;             PG8_LDA(At, 0, 1); PG8_STAGE(PG8_SB(0, 0), b2, voffB); PG8_STAGE(PG8_SB(0, 1), b2 + hstep, voffB); PG8_STAGE(PG8_SA(0, 0), a2, voffA);
;             PG8_WAIT_V(8); PG8_WAIT_L(0); PG8_BAR; PG8_MMA(1, 0, At, B0); PG8_MMA(1, 1, At, B1); PG8_BAR; PG8_SCHED;
;             PG8_LDB(B0, 1, 0); PG8_LDB(B1, 1, 1); PG8_SCHED; PG8_LDA(At, 1, 0); PG8_STAGE(PG8_SA(0, 1), a2 + hstepA, voffA);
	s_mov_b32 m0, s71
	s_nop 0
	global_load_lds_dwordx4 v128, s[68:69]
	s_mov_b32 m0, s72
	s_nop 0
	global_load_lds_dwordx4 v132, s[68:69]
	s_waitcnt vmcnt(8)
	s_waitcnt lgkmcnt(0)
	s_barrier
	s_setprio 1
	s_waitcnt lgkmcnt(0)
	v_mfma_f32_16x16x32_bf16 v[60:63], v[156:159], v[188:191], 0
	v_mfma_f32_16x16x32_bf16 v[56:59], v[164:167], v[188:191], 0
	v_mfma_f32_16x16x32_bf16 v[48:51], v[156:159], v[208:211], 0
	v_mfma_f32_16x16x32_bf16 v[40:43], v[164:167], v[208:211], 0
	v_mfma_f32_16x16x32_bf16 v[32:35], v[156:159], v[216:219], 0
	v_mfma_f32_16x16x32_bf16 v[24:27], v[164:167], v[216:219], 0
	v_mfma_f32_16x16x32_bf16 v[16:19], v[156:159], v[224:227], 0
	v_mfma_f32_16x16x32_bf16 v[8:11], v[164:167], v[224:227], 0
	v_mfma_f32_16x16x32_bf16 v[60:63], v[160:163], v[192:195], v[60:63]
	v_mfma_f32_16x16x32_bf16 v[56:59], v[168:171], v[192:195], v[56:59]
	v_mfma_f32_16x16x32_bf16 v[48:51], v[160:163], v[212:215], v[48:51]
	v_mfma_f32_16x16x32_bf16 v[40:43], v[168:171], v[212:215], v[40:43]
	v_mfma_f32_16x16x32_bf16 v[32:35], v[160:163], v[220:223], v[32:35]
	v_mfma_f32_16x16x32_bf16 v[24:27], v[168:171], v[220:223], v[24:27]
	v_mfma_f32_16x16x32_bf16 v[16:19], v[160:163], v[228:231], v[16:19]
	v_mfma_f32_16x16x32_bf16 v[8:11], v[168:171], v[228:231], v[8:11]
	s_setprio 0
	s_setprio 1
	v_mfma_f32_16x16x32_bf16 v[52:55], v[172:175], v[188:191], 0
	v_mfma_f32_16x16x32_bf16 v[44:47], v[180:183], v[188:191], 0
	v_mfma_f32_16x16x32_bf16 v[36:39], v[172:175], v[208:211], 0
	v_mfma_f32_16x16x32_bf16 v[28:31], v[180:183], v[208:211], 0
	v_mfma_f32_16x16x32_bf16 v[20:23], v[172:175], v[216:219], 0
	v_mfma_f32_16x16x32_bf16 v[12:15], v[180:183], v[216:219], 0
	v_mfma_f32_16x16x32_bf16 v[4:7], v[172:175], v[224:227], 0
	v_mfma_f32_16x16x32_bf16 v[0:3], v[180:183], v[224:227], 0
	v_mfma_f32_16x16x32_bf16 v[52:55], v[176:179], v[192:195], v[52:55]
	v_mfma_f32_16x16x32_bf16 v[44:47], v[184:187], v[192:195], v[44:47]
	v_mfma_f32_16x16x32_bf16 v[36:39], v[176:179], v[212:215], v[36:39]
	v_mfma_f32_16x16x32_bf16 v[28:31], v[184:187], v[212:215], v[28:31]
	v_mfma_f32_16x16x32_bf16 v[20:23], v[176:179], v[220:223], v[20:23]
	v_mfma_f32_16x16x32_bf16 v[12:15], v[184:187], v[220:223], v[12:15]
	v_mfma_f32_16x16x32_bf16 v[4:7], v[176:179], v[228:231], v[4:7]
	v_mfma_f32_16x16x32_bf16 v[0:3], v[184:187], v[228:231], v[0:3]
	s_setprio 0
	s_barrier
	s_add_i32 s84, 0, 0x18000
	v_add_u32_e32 v136, s84, v200
	s_add_i32 s85, 0, 0x1c000
	ds_read_b128 v[156:159], v136
	ds_read_b128 v[160:163], v136 offset:1024
	ds_read_b128 v[164:167], v136 offset:2048
	ds_read_b128 v[168:171], v136 offset:3072
	v_add_u32_e32 v136, s85, v200
	ds_read_b128 v[172:175], v136
	ds_read_b128 v[176:179], v136 offset:1024
	ds_read_b128 v[180:183], v136 offset:2048
	ds_read_b128 v[184:187], v136 offset:3072
	s_add_u32 s68, s68, 0x40000
	s_addc_u32 s69, s69, 0
	s_mov_b32 m0, s73

; #define PG8_STAGE(bufoff, gbase, voff) do { _Pragma("unroll") for (int _i = 0; _i < 2; ++_i) \
;         __builtin_amdgcn_global_load_lds((const unsigned*)((const char*)(gbase) + (voff)[_i]), (PG8_LAS unsigned*)(lds + (bufoff) + ldsw + _i * 8192), 16, 0, 0); } while (0)
; #define PG8_LDA(dst, b, h) do { _Pragma("unroll") for (int m = 0; m < 4; ++m) _Pragma("unroll") for (int k = 0; k < 2; ++k) dst[m][k] = *(const PG8_LAS bf16x8*)(lds + PG8_SA(b, h) + aoff + m * 2048 + k * 1024); } while (0)
; #define PG8_LDB(dst, b, h) do { _Pragma("unroll") for (int n = 0; n < 2; ++n) _Pragma("unroll") for (int k = 0; k < 2; ++k) dst[n][k] = *(const PG8_LAS bf16x8*)(lds + PG8_SB(b, h) + boff + n * 2048 + k * 1024); } while (0)
; #define PG8_SCHED __builtin_amdgcn_sched_barrier(0)
; template <class Epi, class Sched, bool ALIGN_EPI = false, bool SP2 = false, bool ATILED = false>
; __device__ __forceinline__ void gemm_phase(PG8_LAS unsigned char* lds, const Gemm g, const Sched& S, const Epi& E) {
;     ...
;             PG8_LDB(B0, 1, 0); PG8_LDB(B1, 1, 1); PG8_SCHED; PG8_LDA(At, 1, 0); PG8_STAGE(PG8_SA(0, 1), a2 + hstepA, voffA);
	ds_read_b128 v[188:191], v203 offset:32768
	ds_read_b128 v[192:195], v203 offset:33792
	ds_read_b128 v[208:211], v203 offset:34816
	ds_read_b128 v[212:215], v203 offset:35840
	ds_read_b128 v[216:219], v203 offset:36864
	ds_read_b128 v[220:223], v203 offset:37888
	ds_read_b128 v[224:227], v203 offset:38912
	ds_read_b128 v[228:231], v203 offset:39936
	global_load_lds_dwordx4 v128, s[68:69]

; #define PG8_STAGE(bufoff, gbase, voff) do { _Pragma("unroll") for (int _i = 0; _i < 2; ++_i) \
;         __builtin_amdgcn_global_load_lds((const unsigned*)((const char*)(gbase) + (voff)[_i]), (PG8_LAS unsigned*)(lds + (bufoff) + ldsw + _i * 8192), 16, 0, 0); } while (0)
; #define PG8_LDA(dst, b, h) do { _Pragma("unroll") for (int m = 0; m < 4; ++m) _Pragma("unroll") for (int k = 0; k < 2; ++k) dst[m][k] = *(const PG8_LAS bf16x8*)(lds + PG8_SA(b, h) + aoff + m * 2048 + k * 1024); } while (0)
; #define PG8_LDB(dst, b, h) do { _Pragma("unroll") for (int n = 0; n < 2; ++n) _Pragma("unroll") for (int k = 0; k < 2; ++k) dst[n][k] = *(const PG8_LAS bf16x8*)(lds + PG8_SB(b, h) + boff + n * 2048 + k * 1024); } while (0)
; #define PG8_MMA(ai, bj, At, Bt) do { __builtin_amdgcn_s_setprio(1); _Pragma("unroll") for (int m = 0; m < 4; ++m) _Pragma("unroll") for (int n = 0; n < 2; ++n) _Pragma("unroll") for (int k = 0; k < 2; ++k) \
;         acc[ai][bj][m][n] = __builtin_amdgcn_mfma_f32_16x16x32_bf16(Bt[n][k], At[m][k], acc[ai][bj][m][n], 0, 0, 0); __builtin_amdgcn_s_setprio(0); } while (0)
; #define PG8_WAIT_V(n) asm volatile("s_waitcnt vmcnt(" #n ")" ::: "memory")
; #define PG8_WAIT_L(n) asm volatile("s_waitcnt lgkmcnt(" #n ")" ::: "memory")
; #define PG8_BAR __builtin_amdgcn_s_barrier()
; #define PG8_SCHED __builtin_amdgcn_sched_barrier(0)
; template <class Epi, class Sched, bool ALIGN_EPI = false, bool SP2 = false, bool ATILED = false>
; __device__ __forceinline__ void gemm_phase(PG8_LAS unsigned char* lds, const Gemm g, const Sched& S, const Epi& E) {
;     ...
;             PG8_LDB(B0, 1, 0); PG8_LDB(B1, 1, 1); PG8_SCHED; PG8_LDA(At, 1, 0); PG8_STAGE(PG8_SA(0, 1), a2 + hstepA, voffA);
;             PG8_WAIT_V(8); PG8_WAIT_L(0); PG8_BAR; PG8_MMA(0, 0, At, B0); PG8_MMA(0, 1, At, B1); PG8_BAR; PG8_SCHED;
	s_mov_b32 m0, s74
	s_nop 0
	global_load_lds_dwordx4 v132, s[68:69]
	s_waitcnt vmcnt(8)
	s_waitcnt lgkmcnt(0)
	s_barrier
	s_setprio 1
	s_waitcnt lgkmcnt(0)
	v_mfma_f32_16x16x32_bf16 v[124:127], v[156:159], v[188:191], v[124:127]
	v_mfma_f32_16x16x32_bf16 v[120:123], v[164:167], v[188:191], v[120:123]
	v_mfma_f32_16x16x32_bf16 v[116:119], v[156:159], v[208:211], v[116:119]
	v_mfma_f32_16x16x32_bf16 v[112:115], v[164:167], v[208:211], v[112:115]
	v_mfma_f32_16x16x32_bf16 v[96:99], v[156:159], v[216:219], v[96:99]
	v_mfma_f32_16x16x32_bf16 v[88:91], v[164:167], v[216:219], v[88:91]
	v_mfma_f32_16x16x32_bf16 v[80:83], v[156:159], v[224:227], v[80:83]
	v_mfma_f32_16x16x32_bf16 v[72:75], v[164:167], v[224:227], v[72:75]
	v_mfma_f32_16x16x32_bf16 v[124:127], v[160:163], v[192:195], v[124:127]
	v_mfma_f32_16x16x32_bf16 v[120:123], v[168:171], v[192:195], v[120:123]
	v_mfma_f32_16x16x32_bf16 v[116:119], v[160:163], v[212:215], v[116:119]
	v_mfma_f32_16x16x32_bf16 v[112:115], v[168:171], v[212:215], v[112:115]
	v_mfma_f32_16x16x32_bf16 v[96:99], v[160:163], v[220:223], v[96:99]
	v_mfma_f32_16x16x32_bf16 v[88:91], v[168:171], v[220:223], v[88:91]
	v_mfma_f32_16x16x32_bf16 v[80:83], v[160:163], v[228:231], v[80:83]
	v_mfma_f32_16x16x32_bf16 v[72:75], v[168:171], v[228:231], v[72:75]
	s_setprio 0
	s_setprio 1
	v_mfma_f32_16x16x32_bf16 v[108:111], v[172:175], v[188:191], v[108:111]
	v_mfma_f32_16x16x32_bf16 v[104:107], v[180:183], v[188:191], v[104:107]
	v_mfma_f32_16x16x32_bf16 v[100:103], v[172:175], v[208:211], v[100:103]
	v_mfma_f32_16x16x32_bf16 v[92:95], v[180:183], v[208:211], v[92:95]
	v_mfma_f32_16x16x32_bf16 v[84:87], v[172:175], v[216:219], v[84:87]
	v_mfma_f32_16x16x32_bf16 v[76:79], v[180:183], v[216:219], v[76:79]
	v_mfma_f32_16x16x32_bf16 v[68:71], v[172:175], v[224:227], v[68:71]
	v_mfma_f32_16x16x32_bf16 v[64:67], v[180:183], v[224:227], v[64:67]
	v_mfma_f32_16x16x32_bf16 v[108:111], v[176:179], v[192:195], v[108:111]
	v_mfma_f32_16x16x32_bf16 v[104:107], v[184:187], v[192:195], v[104:107]
	v_mfma_f32_16x16x32_bf16 v[100:103], v[176:179], v[212:215], v[100:103]
	v_mfma_f32_16x16x32_bf16 v[92:95], v[184:187], v[212:215], v[92:95]
	v_mfma_f32_16x16x32_bf16 v[84:87], v[176:179], v[220:223], v[84:87]
	v_mfma_f32_16x16x32_bf16 v[76:79], v[184:187], v[220:223], v[76:79]
	v_mfma_f32_16x16x32_bf16 v[68:71], v[176:179], v[228:231], v[68:71]
	v_mfma_f32_16x16x32_bf16 v[64:67], v[184:187], v[228:231], v[64:67]
	s_setprio 0
	s_barrier
	s_add_i32 s68, s84, s70

; #define PG8_STAGE(bufoff, gbase, voff) do { _Pragma("unroll") for (int _i = 0; _i < 2; ++_i) \
;         __builtin_amdgcn_global_load_lds((const unsigned*)((const char*)(gbase) + (voff)[_i]), (PG8_LAS unsigned*)(lds + (bufoff) + ldsw + _i * 8192), 16, 0, 0); } while (0)
; #define PG8_LDA(dst, b, h) do { _Pragma("unroll") for (int m = 0; m < 4; ++m) _Pragma("unroll") for (int k = 0; k < 2; ++k) dst[m][k] = *(const PG8_LAS bf16x8*)(lds + PG8_SA(b, h) + aoff + m * 2048 + k * 1024); } while (0)
; template <class Epi, class Sched, bool ALIGN_EPI = false, bool SP2 = false, bool ATILED = false>
; __device__ __forceinline__ void gemm_phase(PG8_LAS unsigned char* lds, const Gemm g, const Sched& S, const Epi& E) {
;     ...
;             PG8_LDA(At, 1, 1); PG8_STAGE(PG8_SB(1, 0), b3, voffB); PG8_STAGE(PG8_SB(1, 1), b3 + hstep, voffB); PG8_STAGE(PG8_SA(1, 0), a3, voffA);
	s_mov_b32 m0, s68
	ds_read_b128 v[188:191], v203 offset:49152
	ds_read_b128 v[192:195], v203 offset:50176
	ds_read_b128 v[208:211], v203 offset:51200
	ds_read_b128 v[212:215], v203 offset:52224
	ds_read_b128 v[216:219], v203 offset:53248
	ds_read_b128 v[220:223], v203 offset:54272
	ds_read_b128 v[224:227], v203 offset:55296
	ds_read_b128 v[228:231], v203 offset:56320
	global_load_lds_dwordx4 v130, s[98:99]
	s_add_i32 m0, s68, 0x2000
	s_add_u32 s66, s66, 0x40080

; #define PG8_STAGE(bufoff, gbase, voff) do { _Pragma("unroll") for (int _i = 0; _i < 2; ++_i) \
;         __builtin_amdgcn_global_load_lds((const unsigned*)((const char*)(gbase) + (voff)[_i]), (PG8_LAS unsigned*)(lds + (bufoff) + ldsw + _i * 8192), 16, 0, 0); } while (0)
; #define PG8_LDA(dst, b, h) do { _Pragma("unroll") for (int m = 0; m < 4; ++m) _Pragma("unroll") for (int k = 0; k < 2; ++k) dst[m][k] = *(const PG8_LAS bf16x8*)(lds + PG8_SA(b, h) + aoff + m * 2048 + k * 1024); } while (0)
; template <class Epi, class Sched, bool ALIGN_EPI = false, bool SP2 = false, bool ATILED = false>
; __device__ __forceinline__ void gemm_phase(PG8_LAS unsigned char* lds, const Gemm g, const Sched& S, const Epi& E) {
;     ...
;             PG8_LDA(At, 1, 1); PG8_STAGE(PG8_SB(1, 0), b3, voffB); PG8_STAGE(PG8_SB(1, 1), b3 + hstep, voffB); PG8_STAGE(PG8_SA(1, 0), a3, voffA);
	s_addc_u32 s67, s67, 0
	s_add_i32 s68, s85, s70
	global_load_lds_dwordx4 v134, s[98:99]

; #define PG8_STAGE(bufoff, gbase, voff) do { _Pragma("unroll") for (int _i = 0; _i < 2; ++_i) \
;         __builtin_amdgcn_global_load_lds((const unsigned*)((const char*)(gbase) + (voff)[_i]), (PG8_LAS unsigned*)(lds + (bufoff) + ldsw + _i * 8192), 16, 0, 0); } while (0)
; #define PG8_LDA(dst, b, h) do { _Pragma("unroll") for (int m = 0; m < 4; ++m) _Pragma("unroll") for (int k = 0; k < 2; ++k) dst[m][k] = *(const PG8_LAS bf16x8*)(lds + PG8_SA(b, h) + aoff + m * 2048 + k * 1024); } while (0)
; template <class Epi, class Sched, bool ALIGN_EPI = false, bool SP2 = false, bool ATILED = false>
; __device__ __forceinline__ void gemm_phase(PG8_LAS unsigned char* lds, const Gemm g, const Sched& S, const Epi& E) {
;     ...
;             PG8_LDA(At, 1, 1); PG8_STAGE(PG8_SB(1, 0), b3, voffB); PG8_STAGE(PG8_SB(1, 1), b3 + hstep, voffB); PG8_STAGE(PG8_SA(1, 0), a3, voffA);
	s_mov_b32 m0, s68
	s_nop 0
	global_load_lds_dwordx4 v130, s[66:67]

; #define PG8_STAGE(bufoff, gbase, voff) do { _Pragma("unroll") for (int _i = 0; _i < 2; ++_i) \
;         __builtin_amdgcn_global_load_lds((const unsigned*)((const char*)(gbase) + (voff)[_i]), (PG8_LAS unsigned*)(lds + (bufoff) + ldsw + _i * 8192), 16, 0, 0); } while (0)
; #define PG8_LDA(dst, b, h) do { _Pragma("unroll") for (int m = 0; m < 4; ++m) _Pragma("unroll") for (int k = 0; k < 2; ++k) dst[m][k] = *(const PG8_LAS bf16x8*)(lds + PG8_SA(b, h) + aoff + m * 2048 + k * 1024); } while (0)
; template <class Epi, class Sched, bool ALIGN_EPI = false, bool SP2 = false, bool ATILED = false>
; __device__ __forceinline__ void gemm_phase(PG8_LAS unsigned char* lds, const Gemm g, const Sched& S, const Epi& E) {
;     ...
;             PG8_LDA(At, 1, 1); PG8_STAGE(PG8_SB(1, 0), b3, voffB); PG8_STAGE(PG8_SB(1, 1), b3 + hstep, voffB); PG8_STAGE(PG8_SA(1, 0), a3, voffA);
	s_add_i32 m0, s68, 0x2000
	s_nop 0
	global_load_lds_dwordx4 v134, s[66:67]

; #define PG8_STAGE(bufoff, gbase, voff) do { _Pragma("unroll") for (int _i = 0; _i < 2; ++_i) \
;         __builtin_amdgcn_global_load_lds((const unsigned*)((const char*)(gbase) + (voff)[_i]), (PG8_LAS unsigned*)(lds + (bufoff) + ldsw + _i * 8192), 16, 0, 0); } while (0)
; #define PG8_LDA(dst, b, h) do { _Pragma("unroll") for (int m = 0; m < 4; ++m) _Pragma("unroll") for (int k = 0; k < 2; ++k) dst[m][k] = *(const PG8_LAS bf16x8*)(lds + PG8_SA(b, h) + aoff + m * 2048 + k * 1024); } while (0)
; template <class Epi, class Sched, bool ALIGN_EPI = false, bool SP2 = false, bool ATILED = false>
; __device__ __forceinline__ void gemm_phase(PG8_LAS unsigned char* lds, const Gemm g, const Sched& S, const Epi& E) {
;     ...
;             PG8_LDA(At, 1, 1); PG8_STAGE(PG8_SB(1, 0), b3, voffB); PG8_STAGE(PG8_SB(1, 1), b3 + hstep, voffB); PG8_STAGE(PG8_SA(1, 0), a3, voffA);
	s_mov_b32 m0, s77
	s_nop 0
	global_load_lds_dwordx4 v128, s[100:101]

; #define PG8_STAGE(bufoff, gbase, voff) do { _Pragma("unroll") for (int _i = 0; _i < 2; ++_i) \
;         __builtin_amdgcn_global_load_lds((const unsigned*)((const char*)(gbase) + (voff)[_i]), (PG8_LAS unsigned*)(lds + (bufoff) + ldsw + _i * 8192), 16, 0, 0); } while (0)
; #define PG8_LDA(dst, b, h) do { _Pragma("unroll") for (int m = 0; m < 4; ++m) _Pragma("unroll") for (int k = 0; k < 2; ++k) dst[m][k] = *(const PG8_LAS bf16x8*)(lds + PG8_SA(b, h) + aoff + m * 2048 + k * 1024); } while (0)
; #define PG8_MMA(ai, bj, At, Bt) do { __builtin_amdgcn_s_setprio(1); _Pragma("unroll") for (int m = 0; m < 4; ++m) _Pragma("unroll") for (int n = 0; n < 2; ++n) _Pragma("unroll") for (int k = 0; k < 2; ++k) \
;         acc[ai][bj][m][n] = __builtin_amdgcn_mfma_f32_16x16x32_bf16(Bt[n][k], At[m][k], acc[ai][bj][m][n], 0, 0, 0); __builtin_amdgcn_s_setprio(0); } while (0)
; #define PG8_WAIT_V(n) asm volatile("s_waitcnt vmcnt(" #n ")" ::: "memory")
; #define PG8_WAIT_L(n) asm volatile("s_waitcnt lgkmcnt(" #n ")" ::: "memory")
; #define PG8_BAR __builtin_amdgcn_s_barrier()
; #define PG8_SCHED __builtin_amdgcn_sched_barrier(0)
; template <class Epi, class Sched, bool ALIGN_EPI = false, bool SP2 = false, bool ATILED = false>
; __device__ __forceinline__ void gemm_phase(PG8_LAS unsigned char* lds, const Gemm g, const Sched& S, const Epi& E) {
;     ...
;             PG8_LDA(At, 1, 1); PG8_STAGE(PG8_SB(1, 0), b3, voffB); PG8_STAGE(PG8_SB(1, 1), b3 + hstep, voffB); PG8_STAGE(PG8_SA(1, 0), a3, voffA);
;             PG8_WAIT_V(8); PG8_WAIT_L(0); PG8_BAR; PG8_MMA(1, 0, At, B0); PG8_MMA(1, 1, At, B1); PG8_BAR; PG8_SCHED;
	s_mov_b32 m0, s78
	s_nop 0
	global_load_lds_dwordx4 v132, s[100:101]
	s_waitcnt vmcnt(8)
	s_waitcnt lgkmcnt(0)
	s_barrier
	s_setprio 1
	s_waitcnt lgkmcnt(0)
	v_mfma_f32_16x16x32_bf16 v[60:63], v[156:159], v[188:191], v[60:63]
	v_mfma_f32_16x16x32_bf16 v[56:59], v[164:167], v[188:191], v[56:59]
	v_mfma_f32_16x16x32_bf16 v[48:51], v[156:159], v[208:211], v[48:51]
	v_mfma_f32_16x16x32_bf16 v[40:43], v[164:167], v[208:211], v[40:43]
	v_mfma_f32_16x16x32_bf16 v[32:35], v[156:159], v[216:219], v[32:35]
	v_mfma_f32_16x16x32_bf16 v[24:27], v[164:167], v[216:219], v[24:27]
	v_mfma_f32_16x16x32_bf16 v[16:19], v[156:159], v[224:227], v[16:19]
	v_mfma_f32_16x16x32_bf16 v[8:11], v[164:167], v[224:227], v[8:11]
	v_mfma_f32_16x16x32_bf16 v[60:63], v[160:163], v[192:195], v[60:63]
	v_mfma_f32_16x16x32_bf16 v[56:59], v[168:171], v[192:195], v[56:59]
	v_mfma_f32_16x16x32_bf16 v[48:51], v[160:163], v[212:215], v[48:51]
	v_mfma_f32_16x16x32_bf16 v[40:43], v[168:171], v[212:215], v[40:43]
	v_mfma_f32_16x16x32_bf16 v[32:35], v[160:163], v[220:223], v[32:35]
	v_mfma_f32_16x16x32_bf16 v[24:27], v[168:171], v[220:223], v[24:27]
	v_mfma_f32_16x16x32_bf16 v[16:19], v[160:163], v[228:231], v[16:19]
	v_mfma_f32_16x16x32_bf16 v[8:11], v[168:171], v[228:231], v[8:11]
	s_setprio 0
	s_setprio 1
	v_mfma_f32_16x16x32_bf16 v[52:55], v[172:175], v[188:191], v[52:55]
	v_mfma_f32_16x16x32_bf16 v[44:47], v[180:183], v[188:191], v[44:47]
	v_mfma_f32_16x16x32_bf16 v[36:39], v[172:175], v[208:211], v[36:39]
	v_mfma_f32_16x16x32_bf16 v[28:31], v[180:183], v[208:211], v[28:31]
	v_mfma_f32_16x16x32_bf16 v[20:23], v[172:175], v[216:219], v[20:23]
	v_mfma_f32_16x16x32_bf16 v[12:15], v[180:183], v[216:219], v[12:15]
	v_mfma_f32_16x16x32_bf16 v[4:7], v[172:175], v[224:227], v[4:7]
	v_mfma_f32_16x16x32_bf16 v[0:3], v[180:183], v[224:227], v[0:3]
	v_mfma_f32_16x16x32_bf16 v[52:55], v[176:179], v[192:195], v[52:55]
	v_mfma_f32_16x16x32_bf16 v[44:47], v[184:187], v[192:195], v[44:47]
	v_mfma_f32_16x16x32_bf16 v[36:39], v[176:179], v[212:215], v[36:39]
	v_mfma_f32_16x16x32_bf16 v[28:31], v[184:187], v[212:215], v[28:31]
	v_mfma_f32_16x16x32_bf16 v[20:23], v[176:179], v[220:223], v[20:23]
	v_mfma_f32_16x16x32_bf16 v[12:15], v[184:187], v[220:223], v[12:15]
	v_mfma_f32_16x16x32_bf16 v[4:7], v[176:179], v[228:231], v[4:7]
	v_mfma_f32_16x16x32_bf16 v[0:3], v[184:187], v[228:231], v[0:3]
	s_setprio 0
	s_barrier
	s_add_i32 s83, s83, 2
	s_add_u32 s64, s64, 0x100
	s_addc_u32 s65, s65, 0
	s_add_u32 s49, s49, 0x100
	s_addc_u32 s63, s63, 0
	s_cmp_gt_u32 s83, 13

; #define PG8_BAR __builtin_amdgcn_s_barrier()
; template <class Epi, class Sched, bool ALIGN_EPI = false, bool SP2 = false, bool ATILED = false>
; __device__ __forceinline__ void gemm_phase(PG8_LAS unsigned char* lds, const Gemm g, const Sched& S, const Epi& E) {
;     ...
;         if constexpr (ALIGN_EPI) { if (wr == 0) PG8_BAR; }
;         if constexpr (!Epi::AFTER_DRAIN) { E(acc, cur, wr, wc, fr, fq); S.done(cur); }
;         if (!has_next) break;
; #pragma unroll
;         for (int a = 0; a < 2; ++a)
; #pragma unroll
;             for (int b = 0; b < 2; ++b)
; #pragma unroll
;                 for (int m = 0; m < 4; ++m)
; #pragma unroll
;                     for (int n = 0; n < 2; ++n) acc[a][b][m][n] = (f32x4){0.f, 0.f, 0.f, 0.f};
;         cur = nxt; cA = nA; cB = nB; ++ui;
;         if constexpr (ALIGN_EPI) { if (wr == 1) PG8_BAR; }
;     }
.LBB0_340:
	s_branch .LBB0_291

; template <class Epi, class Sched, bool ALIGN_EPI = false, bool SP2 = false, bool ATILED = false>
; __device__ __forceinline__ void gemm_phase(PG8_LAS unsigned char* lds, const Gemm g, const Sched& S, const Epi& E) {
;     const int tid = threadIdx.x, wid = __builtin_amdgcn_readfirstlane(tid >> 6), lane = tid & 63, wr = wid >> 2, wc = wid & 3, fr = lane & 15, fq = lane >> 4;
;     const int K = g.K, nt = K / BK;
;     unsigned voffA[2], voffB[2];
; #pragma unroll
;     for (int i = 0; i < 2; ++i) { int R, C; stage_rc(tid * 16 + i * 8192, R, C); const int Rb = Epi::PERM ? ((R & ~31) + perm32(R & 31)) : R;
;         voffA[i] = (unsigned)(R * (ATILED ? BK : K) + C) * 2u; voffB[i] = (unsigned)(Rb * K + C) * 2u; }
;     const size_t kstep = (size_t)(BK * 2);
;     const size_t hstep = (size_t)HALF * K * 2;
;     const size_t tstep = 2 * hstep;
;     const size_t kstepA = ATILED ? (size_t)(BM * BK * 2) : kstep, hstepA = ATILED ? (size_t)(HALF * BK * 2) : hstep, tstepA = ATILED ? (size_t)nt * (BM * BK * 2) : tstep;
;     const unsigned ldsw = (unsigned)wid * 1024u;
;     const int aoff = lds_byte(wr * 64 + fr, fq * 8), boff = lds_byte(wc * 32 + fr, fq * 8);
;     ...
;     Unit cur, nxt; int ui = 0;
;     if (!S.next(0, cur)) return;
;     f32x4 acc[2][2][4][2];
; #pragma unroll
;     for (int a = 0; a < 2; ++a)
; #pragma unroll
;         for (int b = 0; b < 2; ++b)
; #pragma unroll
;             for (int m = 0; m < 4; ++m)
; #pragma unroll
;                 for (int n = 0; n < 2; ++n) acc[a][b][m][n] = (f32x4){0.f, 0.f, 0.f, 0.f};
;     bf16x8 At[4][2], B0[2][2], B1[2][2];
;     const char* cA = (const char*)g.A + (size_t)cur.pm * tstepA; const char* cB = (const char*)g.Bt + (size_t)cur.pn * tstep;
;     S.a_ready(cur);
;     if constexpr (SP2) {
;         PG8_STAGE(PG8_SB(0, 0), cB, voffB); PG8_STAGE(PG8_SB(0, 1), cB + hstep, voffB); PG8_STAGE(PG8_SA(0, 0), cA, voffA); PG8_STAGE(PG8_SA(0, 1), cA + hstepA, voffA);
;         if (wr == 1) PG8_BAR;
;         PG8_WAIT_V(2); PG8_BAR;
;         PG8_STAGE(PG8_SB(1, 0), cB + kstep, voffB); PG8_STAGE(PG8_SA(1, 0), cA + kstepA, voffA); PG8_STAGE(PG8_SB(1, 1), cB + hstep + kstep, voffB);
;         PG8_WAIT_V(6); PG8_BAR;
;     } else {
;         PG8_STAGE(PG8_SB(0, 0), cB, voffB); PG8_STAGE(PG8_SA(0, 0), cA, voffA); PG8_STAGE(PG8_SB(0, 1), cB + hstep, voffB); PG8_STAGE(PG8_SA(0, 1), cA + hstepA, voffA);
.LBB0_723:
	s_waitcnt vmcnt(3)
	v_lshrrev_b32_e32 v2, 1, v198
	v_lshrrev_b32_e32 v3, 5, v198
	v_and_b32_e32 v2, 24, v2
	v_and_b32_e32 v3, 4, v3
	s_waitcnt vmcnt(2)
	v_bfe_u32 v4, v198, 2, 2
	v_lshlrev_b32_e32 v0, 4, v198
	s_waitcnt lgkmcnt(0)
	v_and_b32_e32 v1, 32, v198
	s_waitcnt vmcnt(1)
	v_bfe_u32 v10, v198, 2, 4
	v_or3_b32 v2, v3, v4, v2
	v_lshrrev_b32_e32 v3, 3, v198
	s_movk_i32 s0, 0x70
	v_bitop3_b32 v8, v0, v1, 48 bitop3:0x6c
	v_and_b32_e32 v9, 64, v198
	v_and_or_b32 v4, v3, s0, v10
	s_movk_i32 s0, 0x60
	v_add_u32_e32 v11, 0x2000, v0
	v_or_b32_e32 v1, v8, v9
	v_and_or_b32 v3, v3, s0, v2
	v_lshrrev_b32_e32 v0, 7, v11
	s_movk_i32 s0, 0xf0
	s_lshr_b32 s1, s14, 6
	v_lshl_or_b32 v154, v3, 11, v1
	v_and_or_b32 v3, v0, s0, v10
	s_movk_i32 s0, 0xe0
	s_ashr_i32 s49, s48, 31
	s_ashr_i32 s7, s6, 31
	v_and_or_b32 v0, v0, s0, v2
	s_lshr_b32 s0, s14, 8
	s_lshl_b32 s29, s1, 10
	s_lshl_b64 s[4:5], s[48:49], 19
	s_lshl_b64 s[8:9], s[6:7], 19
	s_add_u32 s54, s46, s8
	s_addc_u32 s55, s47, s9
	s_add_i32 s58, s29, 0
	s_add_i32 m0, s58, 0x10000
	v_lshl_or_b32 v158, v0, 11, v1
	global_load_lds_dwordx4 v154, s[54:55]
	s_add_i32 m0, s58, 0x12000
	s_add_u32 s8, s54, 0x40000
	global_load_lds_dwordx4 v158, s[54:55]
	s_addc_u32 s9, s55, 0
	s_add_i32 m0, s58, 0x14000
	v_lshl_or_b32 v152, v4, 11, v1
	global_load_lds_dwordx4 v154, s[8:9]
	s_add_i32 m0, s58, 0x16000
	s_add_u32 s50, s44, s4
	s_addc_u32 s51, s45, s5
	s_add_i32 s59, s58, 0x2000
	global_load_lds_dwordx4 v158, s[8:9]
	s_mov_b32 m0, s58
	s_add_u32 s4, s50, 0x40000
	v_lshl_or_b32 v156, v3, 11, v1
	global_load_lds_dwordx4 v152, s[50:51]
	s_mov_b32 m0, s59
	s_addc_u32 s5, s51, 0
	s_add_i32 s60, s58, 0x4000
	global_load_lds_dwordx4 v156, s[50:51]
	s_mov_b32 m0, s60
	s_add_i32 s61, s58, 0x6000
	global_load_lds_dwordx4 v152, s[4:5]
	s_mov_b32 m0, s61
	v_mov_b32_e32 v155, 0
	global_load_lds_dwordx4 v156, s[4:5]
	v_mov_b32_e32 v159, v155
	v_mov_b32_e32 v153, v155
	v_mov_b32_e32 v157, v155
	s_cmp_eq_u32 s0, 1
	s_mov_b32 s7, 0
	v_lshl_add_u64 v[6:7], s[54:55], 0, v[154:155]
	v_lshl_add_u64 v[4:5], s[54:55], 0, v[158:159]
	v_lshl_add_u64 v[0:1], s[50:51], 0, v[152:153]
	s_cselect_b64 s[8:9], -1, 0
	s_cmp_lg_u32 s0, 1
	v_lshl_add_u64 v[2:3], s[50:51], 0, v[156:157]
.LBB0_725:
	s_mov_b64 s[12:13], 0x80
	s_and_b32 s62, s1, 3
	s_add_i32 m0, s58, 0x18000
	v_lshl_add_u64 v[6:7], v[6:7], 0, s[12:13]
	s_lshl_b32 s1, s0, 13
	s_lshl_b32 s15, s62, 12
	s_waitcnt vmcnt(2)
	s_barrier
	global_load_lds_dwordx4 v[6:7], off
	v_lshl_add_u64 v[4:5], v[4:5], 0, s[12:13]
	s_add_i32 m0, s58, 0x1a000
	s_add_i32 s63, s58, 0x8000
	s_add_i32 s64, s58, 0xa000
	global_load_lds_dwordx4 v[4:5], off
	v_lshl_add_u64 v[0:1], v[0:1], 0, s[12:13]
	s_mov_b32 m0, s63
	s_add_u32 s4, s54, 0x40080
	global_load_lds_dwordx4 v[0:1], off
	v_lshl_add_u64 v[0:1], v[2:3], 0, s[12:13]
	s_mov_b32 m0, s64
	s_addc_u32 s5, s55, 0
	global_load_lds_dwordx4 v[0:1], off
	s_add_i32 m0, s58, 0x1c000
	v_lshl_add_u64 v[0:1], s[4:5], 0, v[154:155]
	global_load_lds_dwordx4 v[0:1], off
	v_lshl_add_u64 v[0:1], s[4:5], 0, v[158:159]
	s_add_i32 m0, s58, 0x1e000
	v_lshlrev_b32_e32 v4, 2, v198
	global_load_lds_dwordx4 v[0:1], off
	v_bfe_u32 v1, v198, 4, 2
	v_and_b32_e32 v0, 15, v198
	v_lshlrev_b32_e32 v3, 4, v1
	v_lshl_or_b32 v186, s0, 6, v0
	v_lshl_or_b32 v0, v0, 6, v3
	v_and_b32_e32 v4, 32, v4
	v_lshlrev_b32_e32 v5, 6, v198
	s_movk_i32 s0, 0x3c0
	v_lshlrev_b32_e32 v2, 3, v1
	v_bitop3_b32 v0, v0, s1, v4 bitop3:0xde
	v_and_or_b32 v3, v5, s0, v3
	v_cmp_eq_u32_e64 s[0:1], 0, v1
	v_lshlrev_b32_e32 v1, 8, v198
	v_lshl_or_b32 v188, s62, 5, v2
	v_and_b32_e32 v1, 0x38000, v1
	v_lshlrev_b32_e32 v2, 11, v10
	v_or3_b32 v1, v8, v1, v2
	v_add_u32_e32 v160, v1, v9
	v_lshlrev_b32_e32 v1, 4, v11
	s_waitcnt vmcnt(6)
	s_cmpk_lt_u32 s14, 0x100
	v_and_b32_e32 v1, 0x78000, v1
	v_bitop3_b32 v187, s15, v3, v4 bitop3:0xf6
	s_cselect_b64 s[14:15], -1, 0
	v_or3_b32 v1, v8, v1, v2
	s_add_i32 s67, 0, 0x10000
	s_add_i32 s68, 0, 0x14000
	v_add_u32_e32 v191, 0, v0
	v_mbcnt_lo_u32_b32 v0, -1, 0
	s_ashr_i32 s65, s28, 31
	s_ashr_i32 s66, s2, 31
	v_mov_b32_e32 v161, v155
	v_add_u32_e32 v162, v1, v9
	v_mov_b32_e32 v163, v155
	v_mov_b64_e32 v[164:165], 0x400
	v_mov_b64_e32 v[166:167], 0x3ff
	v_add_u32_e32 v189, s67, v187
	v_add_u32_e32 v190, s68, v187
	v_mbcnt_hi_u32_b32 v192, -1, v0
	s_mov_b32 s69, 0
	s_barrier
	s_branch .LBB0_728

; #define PG8_STAGE(bufoff, gbase, voff) do { _Pragma("unroll") for (int _i = 0; _i < 2; ++_i) \
;         __builtin_amdgcn_global_load_lds((const unsigned*)((const char*)(gbase) + (voff)[_i]), (PG8_LAS unsigned*)(lds + (bufoff) + ldsw + _i * 8192), 16, 0, 0); } while (0)
; #define PG8_LDA(dst, b, h) do { _Pragma("unroll") for (int m = 0; m < 4; ++m) _Pragma("unroll") for (int k = 0; k < 2; ++k) dst[m][k] = *(const PG8_LAS bf16x8*)(lds + PG8_SA(b, h) + aoff + m * 2048 + k * 1024); } while (0)
; #define PG8_LDB(dst, b, h) do { _Pragma("unroll") for (int n = 0; n < 2; ++n) _Pragma("unroll") for (int k = 0; k < 2; ++k) dst[n][k] = *(const PG8_LAS bf16x8*)(lds + PG8_SB(b, h) + boff + n * 2048 + k * 1024); } while (0)
; #define PG8_SCHED __builtin_amdgcn_sched_barrier(0)
; template <class Epi, class Sched, bool ALIGN_EPI = false, bool SP2 = false, bool ATILED = false>
; __device__ __forceinline__ void gemm_phase(PG8_LAS unsigned char* lds, const Gemm g, const Sched& S, const Epi& E) {
;     ...
;         const bool has_next = S.next(ui + 1, nxt);
;         const char* nA = has_next ? (const char*)g.A + (size_t)nxt.pm * tstepA : cA; const char* nB = has_next ? (const char*)g.Bt + (size_t)nxt.pn * tstep : cB;
;         for (int t = 0; t < nt; t += 2) {
;             const bool last = (t == nt - 2);
;             const char* a1 = cA + (size_t)(t + 1) * kstepA;
;             const char* a2 = last ? nA : cA + (size_t)(t + 2) * kstepA; const char* b2 = last ? nB : cB + (size_t)(t + 2) * kstep;
;             const char* a3 = a2 + kstepA; const char* b3 = b2 + kstep;
;             if (last && has_next) S.a_ready(nxt);
;             if constexpr (SP2) {
;             PG8_LDB(B0, 0, 0); PG8_LDB(B1, 0, 1); PG8_SCHED; PG8_LDA(At, 0, 0); PG8_STAGE(PG8_SA(1, 1), a1 + hstepA, voffA);
.LBB0_734:
	s_ashr_i32 s19, s18, 31
	s_lshl_b64 s[20:21], s[18:19], 19
	s_add_u32 s20, s44, s20
	s_addc_u32 s21, s45, s21
	s_and_b64 s[42:43], s[4:5], exec
	s_cselect_b32 s19, s21, s51
	s_cselect_b32 s49, s20, s50
	s_ashr_i32 s17, s16, 31
	s_lshl_b64 s[42:43], s[16:17], 19
	s_add_u32 s42, s46, s42
	s_addc_u32 s43, s47, s43
	s_and_b64 s[56:57], s[4:5], exec
	s_cselect_b32 s17, s43, s55
	s_cselect_b32 s70, s42, s54
	s_add_u32 s50, s50, 0x40080
	s_addc_u32 s51, s51, 0
	s_add_u32 s71, s54, 0x100
	s_addc_u32 s72, s55, 0
	s_mov_b32 s73, -2
	s_waitcnt lgkmcnt(0)
	s_waitcnt vmcnt(0)
	s_cmp_lg_u64 s[8:9], 0
	s_cbranch_scc0 .Ltbar_skip3
	s_barrier
.Ltbar_skip3:
	ds_read_b128 v[128:131], v189
	ds_read_b128 v[132:135], v189 offset:1024
	ds_read_b128 v[136:139], v189 offset:2048
	ds_read_b128 v[140:143], v189 offset:3072
	ds_read_b128 v[144:147], v190
	ds_read_b128 v[148:151], v190 offset:1024
	ds_read_b128 v[168:171], v190 offset:2048
	ds_read_b128 v[172:175], v190 offset:3072
	s_add_u32 s54, s50, 0xfffc0080
	s_addc_u32 s55, s51, -1
	s_cmp_eq_u32 s73, 12
	s_cselect_b32 s57, s19, s55
	s_cselect_b32 s56, s49, s54
	s_cselect_b32 s55, s17, s72
	s_cselect_b32 s54, s70, s71

; #define PG8_STAGE(bufoff, gbase, voff) do { _Pragma("unroll") for (int _i = 0; _i < 2; ++_i) \
;         __builtin_amdgcn_global_load_lds((const unsigned*)((const char*)(gbase) + (voff)[_i]), (PG8_LAS unsigned*)(lds + (bufoff) + ldsw + _i * 8192), 16, 0, 0); } while (0)
; #define PG8_LDA(dst, b, h) do { _Pragma("unroll") for (int m = 0; m < 4; ++m) _Pragma("unroll") for (int k = 0; k < 2; ++k) dst[m][k] = *(const PG8_LAS bf16x8*)(lds + PG8_SA(b, h) + aoff + m * 2048 + k * 1024); } while (0)
; #define PG8_LDB(dst, b, h) do { _Pragma("unroll") for (int n = 0; n < 2; ++n) _Pragma("unroll") for (int k = 0; k < 2; ++k) dst[n][k] = *(const PG8_LAS bf16x8*)(lds + PG8_SB(b, h) + boff + n * 2048 + k * 1024); } while (0)
; #define PG8_SCHED __builtin_amdgcn_sched_barrier(0)
; template <class Epi, class Sched, bool ALIGN_EPI = false, bool SP2 = false, bool ATILED = false>
; __device__ __forceinline__ void gemm_phase(PG8_LAS unsigned char* lds, const Gemm g, const Sched& S, const Epi& E) {
;     ...
;             PG8_LDB(B0, 0, 0); PG8_LDB(B1, 0, 1); PG8_SCHED; PG8_LDA(At, 0, 0); PG8_STAGE(PG8_SA(1, 1), a1 + hstepA, voffA);
	s_add_i32 m0, s58, 0xc000
	ds_read_b128 v[176:179], v191
	ds_read_b128 v[180:183], v191 offset:1024
	ds_read_b128 v[194:197], v191 offset:2048
	ds_read_b128 v[200:203], v191 offset:3072
	ds_read_b128 v[204:207], v191 offset:4096
	ds_read_b128 v[208:211], v191 offset:5120
	ds_read_b128 v[212:215], v191 offset:6144
	ds_read_b128 v[216:219], v191 offset:7168
	global_load_lds_dwordx4 v160, s[50:51]

; #define PG8_STAGE(bufoff, gbase, voff) do { _Pragma("unroll") for (int _i = 0; _i < 2; ++_i) \
;         __builtin_amdgcn_global_load_lds((const unsigned*)((const char*)(gbase) + (voff)[_i]), (PG8_LAS unsigned*)(lds + (bufoff) + ldsw + _i * 8192), 16, 0, 0); } while (0)
; #define PG8_LDA(dst, b, h) do { _Pragma("unroll") for (int m = 0; m < 4; ++m) _Pragma("unroll") for (int k = 0; k < 2; ++k) dst[m][k] = *(const PG8_LAS bf16x8*)(lds + PG8_SA(b, h) + aoff + m * 2048 + k * 1024); } while (0)
; #define PG8_LDB(dst, b, h) do { _Pragma("unroll") for (int n = 0; n < 2; ++n) _Pragma("unroll") for (int k = 0; k < 2; ++k) dst[n][k] = *(const PG8_LAS bf16x8*)(lds + PG8_SB(b, h) + boff + n * 2048 + k * 1024); } while (0)
; #define PG8_MMA(ai, bj, At, Bt) do { __builtin_amdgcn_s_setprio(1); _Pragma("unroll") for (int m = 0; m < 4; ++m) _Pragma("unroll") for (int n = 0; n < 2; ++n) _Pragma("unroll") for (int k = 0; k < 2; ++k) \
;         acc[ai][bj][m][n] = __builtin_amdgcn_mfma_f32_16x16x32_bf16(Bt[n][k], At[m][k], acc[ai][bj][m][n], 0, 0, 0); __builtin_amdgcn_s_setprio(0); } while (0)
; #define PG8_WAIT_V(n) asm volatile("s_waitcnt vmcnt(" #n ")" ::: "memory")
; #define PG8_WAIT_L(n) asm volatile("s_waitcnt lgkmcnt(" #n ")" ::: "memory")
; #define PG8_BAR __builtin_amdgcn_s_barrier()
; #define PG8_SCHED __builtin_amdgcn_sched_barrier(0)
; template <class Epi, class Sched, bool ALIGN_EPI = false, bool SP2 = false, bool ATILED = false>
; __device__ __forceinline__ void gemm_phase(PG8_LAS unsigned char* lds, const Gemm g, const Sched& S, const Epi& E) {
;     ...
;             PG8_LDB(B0, 0, 0); PG8_LDB(B1, 0, 1); PG8_SCHED; PG8_LDA(At, 0, 0); PG8_STAGE(PG8_SA(1, 1), a1 + hstepA, voffA);
;             PG8_WAIT_V(8); PG8_WAIT_L(0); PG8_BAR; PG8_MMA(0, 0, At, B0); PG8_MMA(0, 1, At, B1); PG8_BAR; PG8_SCHED;
	s_add_i32 m0, s58, 0xe000
	s_nop 0
	global_load_lds_dwordx4 v162, s[50:51]
	s_waitcnt vmcnt(8)
	s_waitcnt lgkmcnt(0)
	s_barrier
	s_setprio 1
	s_waitcnt lgkmcnt(0)
	v_mfma_f32_16x16x32_bf16 v[124:127], v[128:131], v[176:179], 0
	v_mfma_f32_16x16x32_bf16 v[120:123], v[136:139], v[176:179], 0
	v_mfma_f32_16x16x32_bf16 v[108:111], v[128:131], v[194:197], 0
	v_mfma_f32_16x16x32_bf16 v[104:107], v[136:139], v[194:197], 0
	v_mfma_f32_16x16x32_bf16 v[92:95], v[128:131], v[204:207], 0
	v_mfma_f32_16x16x32_bf16 v[88:91], v[136:139], v[204:207], 0
	v_mfma_f32_16x16x32_bf16 v[76:79], v[128:131], v[212:215], 0
	v_mfma_f32_16x16x32_bf16 v[72:75], v[136:139], v[212:215], 0
	v_mfma_f32_16x16x32_bf16 v[124:127], v[132:135], v[180:183], v[124:127]
	v_mfma_f32_16x16x32_bf16 v[120:123], v[140:143], v[180:183], v[120:123]
	v_mfma_f32_16x16x32_bf16 v[108:111], v[132:135], v[200:203], v[108:111]
	v_mfma_f32_16x16x32_bf16 v[104:107], v[140:143], v[200:203], v[104:107]
	v_mfma_f32_16x16x32_bf16 v[92:95], v[132:135], v[208:211], v[92:95]
	v_mfma_f32_16x16x32_bf16 v[88:91], v[140:143], v[208:211], v[88:91]
	v_mfma_f32_16x16x32_bf16 v[76:79], v[132:135], v[216:219], v[76:79]
	v_mfma_f32_16x16x32_bf16 v[72:75], v[140:143], v[216:219], v[72:75]
	s_setprio 0
	s_setprio 1
	v_mfma_f32_16x16x32_bf16 v[116:119], v[144:147], v[176:179], 0
	v_mfma_f32_16x16x32_bf16 v[112:115], v[168:171], v[176:179], 0
	v_mfma_f32_16x16x32_bf16 v[100:103], v[144:147], v[194:197], 0
	v_mfma_f32_16x16x32_bf16 v[96:99], v[168:171], v[194:197], 0
	v_mfma_f32_16x16x32_bf16 v[84:87], v[144:147], v[204:207], 0
	v_mfma_f32_16x16x32_bf16 v[80:83], v[168:171], v[204:207], 0
	v_mfma_f32_16x16x32_bf16 v[68:71], v[144:147], v[212:215], 0
	v_mfma_f32_16x16x32_bf16 v[64:67], v[168:171], v[212:215], 0
	v_mfma_f32_16x16x32_bf16 v[116:119], v[148:151], v[180:183], v[116:119]
	v_mfma_f32_16x16x32_bf16 v[112:115], v[172:175], v[180:183], v[112:115]
	v_mfma_f32_16x16x32_bf16 v[100:103], v[148:151], v[200:203], v[100:103]
	v_mfma_f32_16x16x32_bf16 v[96:99], v[172:175], v[200:203], v[96:99]
	v_mfma_f32_16x16x32_bf16 v[84:87], v[148:151], v[208:211], v[84:87]
	v_mfma_f32_16x16x32_bf16 v[80:83], v[172:175], v[208:211], v[80:83]
	v_mfma_f32_16x16x32_bf16 v[68:71], v[148:151], v[216:219], v[68:71]
	v_mfma_f32_16x16x32_bf16 v[64:67], v[172:175], v[216:219], v[64:67]
	s_setprio 0
	s_barrier
	s_add_u32 s98, s54, s12
	s_addc_u32 s99, s55, s13
	s_add_u32 s100, s56, s12
	s_addc_u32 s101, s57, s13
	s_add_i32 s74, s67, s29

; #define PG8_STAGE(bufoff, gbase, voff) do { _Pragma("unroll") for (int _i = 0; _i < 2; ++_i) \
;         __builtin_amdgcn_global_load_lds((const unsigned*)((const char*)(gbase) + (voff)[_i]), (PG8_LAS unsigned*)(lds + (bufoff) + ldsw + _i * 8192), 16, 0, 0); } while (0)
; #define PG8_LDA(dst, b, h) do { _Pragma("unroll") for (int m = 0; m < 4; ++m) _Pragma("unroll") for (int k = 0; k < 2; ++k) dst[m][k] = *(const PG8_LAS bf16x8*)(lds + PG8_SA(b, h) + aoff + m * 2048 + k * 1024); } while (0)
; template <class Epi, class Sched, bool ALIGN_EPI = false, bool SP2 = false, bool ATILED = false>
; __device__ __forceinline__ void gemm_phase(PG8_LAS unsigned char* lds, const Gemm g, const Sched& S, const Epi& E) {
;     ...
;             PG8_LDA(At, 0, 1); PG8_STAGE(PG8_SB(0, 0), b2, voffB); PG8_STAGE(PG8_SB(0, 1), b2 + hstep, voffB); PG8_STAGE(PG8_SA(0, 0), a2, voffA);
	s_mov_b32 m0, s74
	ds_read_b128 v[176:179], v191 offset:16384
	ds_read_b128 v[180:183], v191 offset:17408
	ds_read_b128 v[194:197], v191 offset:18432
	ds_read_b128 v[200:203], v191 offset:19456
	ds_read_b128 v[204:207], v191 offset:20480
	ds_read_b128 v[208:211], v191 offset:21504
	ds_read_b128 v[212:215], v191 offset:22528
	ds_read_b128 v[216:219], v191 offset:23552
	global_load_lds_dwordx4 v154, s[54:55]
	s_add_i32 m0, s74, 0x2000
	s_add_u32 s74, s54, 0x40000

; #define PG8_STAGE(bufoff, gbase, voff) do { _Pragma("unroll") for (int _i = 0; _i < 2; ++_i) \
;         __builtin_amdgcn_global_load_lds((const unsigned*)((const char*)(gbase) + (voff)[_i]), (PG8_LAS unsigned*)(lds + (bufoff) + ldsw + _i * 8192), 16, 0, 0); } while (0)
; #define PG8_LDA(dst, b, h) do { _Pragma("unroll") for (int m = 0; m < 4; ++m) _Pragma("unroll") for (int k = 0; k < 2; ++k) dst[m][k] = *(const PG8_LAS bf16x8*)(lds + PG8_SA(b, h) + aoff + m * 2048 + k * 1024); } while (0)
; template <class Epi, class Sched, bool ALIGN_EPI = false, bool SP2 = false, bool ATILED = false>
; __device__ __forceinline__ void gemm_phase(PG8_LAS unsigned char* lds, const Gemm g, const Sched& S, const Epi& E) {
;     ...
;             PG8_LDA(At, 0, 1); PG8_STAGE(PG8_SB(0, 0), b2, voffB); PG8_STAGE(PG8_SB(0, 1), b2 + hstep, voffB); PG8_STAGE(PG8_SA(0, 0), a2, voffA);
	s_addc_u32 s75, s55, 0
	s_add_i32 s76, s68, s29
	global_load_lds_dwordx4 v158, s[54:55]

; #define PG8_STAGE(bufoff, gbase, voff) do { _Pragma("unroll") for (int _i = 0; _i < 2; ++_i) \
;         __builtin_amdgcn_global_load_lds((const unsigned*)((const char*)(gbase) + (voff)[_i]), (PG8_LAS unsigned*)(lds + (bufoff) + ldsw + _i * 8192), 16, 0, 0); } while (0)
; #define PG8_LDA(dst, b, h) do { _Pragma("unroll") for (int m = 0; m < 4; ++m) _Pragma("unroll") for (int k = 0; k < 2; ++k) dst[m][k] = *(const PG8_LAS bf16x8*)(lds + PG8_SA(b, h) + aoff + m * 2048 + k * 1024); } while (0)
; template <class Epi, class Sched, bool ALIGN_EPI = false, bool SP2 = false, bool ATILED = false>
; __device__ __forceinline__ void gemm_phase(PG8_LAS unsigned char* lds, const Gemm g, const Sched& S, const Epi& E) {
;     ...
;             PG8_LDA(At, 0, 1); PG8_STAGE(PG8_SB(0, 0), b2, voffB); PG8_STAGE(PG8_SB(0, 1), b2 + hstep, voffB); PG8_STAGE(PG8_SA(0, 0), a2, voffA);
	s_mov_b32 m0, s76

; #define PG8_STAGE(bufoff, gbase, voff) do { _Pragma("unroll") for (int _i = 0; _i < 2; ++_i) \
;         __builtin_amdgcn_global_load_lds((const unsigned*)((const char*)(gbase) + (voff)[_i]), (PG8_LAS unsigned*)(lds + (bufoff) + ldsw + _i * 8192), 16, 0, 0); } while (0)
; #define PG8_LDA(dst, b, h) do { _Pragma("unroll") for (int m = 0; m < 4; ++m) _Pragma("unroll") for (int k = 0; k < 2; ++k) dst[m][k] = *(const PG8_LAS bf16x8*)(lds + PG8_SA(b, h) + aoff + m * 2048 + k * 1024); } while (0)
; template <class Epi, class Sched, bool ALIGN_EPI = false, bool SP2 = false, bool ATILED = false>
; __device__ __forceinline__ void gemm_phase(PG8_LAS unsigned char* lds, const Gemm g, const Sched& S, const Epi& E) {
;     ...
;             PG8_LDA(At, 0, 1); PG8_STAGE(PG8_SB(0, 0), b2, voffB); PG8_STAGE(PG8_SB(0, 1), b2 + hstep, voffB); PG8_STAGE(PG8_SA(0, 0), a2, voffA);
	s_nop 0
	global_load_lds_dwordx4 v154, s[74:75]

; #define PG8_STAGE(bufoff, gbase, voff) do { _Pragma("unroll") for (int _i = 0; _i < 2; ++_i) \
;         __builtin_amdgcn_global_load_lds((const unsigned*)((const char*)(gbase) + (voff)[_i]), (PG8_LAS unsigned*)(lds + (bufoff) + ldsw + _i * 8192), 16, 0, 0); } while (0)
; #define PG8_LDA(dst, b, h) do { _Pragma("unroll") for (int m = 0; m < 4; ++m) _Pragma("unroll") for (int k = 0; k < 2; ++k) dst[m][k] = *(const PG8_LAS bf16x8*)(lds + PG8_SA(b, h) + aoff + m * 2048 + k * 1024); } while (0)
; template <class Epi, class Sched, bool ALIGN_EPI = false, bool SP2 = false, bool ATILED = false>
; __device__ __forceinline__ void gemm_phase(PG8_LAS unsigned char* lds, const Gemm g, const Sched& S, const Epi& E) {
;     ...
;             PG8_LDA(At, 0, 1); PG8_STAGE(PG8_SB(0, 0), b2, voffB); PG8_STAGE(PG8_SB(0, 1), b2 + hstep, voffB); PG8_STAGE(PG8_SA(0, 0), a2, voffA);
	s_add_i32 m0, s76, 0x2000
	s_nop 0
	global_load_lds_dwordx4 v158, s[74:75]

; #define PG8_STAGE(bufoff, gbase, voff) do { _Pragma("unroll") for (int _i = 0; _i < 2; ++_i) \
;         __builtin_amdgcn_global_load_lds((const unsigned*)((const char*)(gbase) + (voff)[_i]), (PG8_LAS unsigned*)(lds + (bufoff) + ldsw + _i * 8192), 16, 0, 0); } while (0)
; #define PG8_LDA(dst, b, h) do { _Pragma("unroll") for (int m = 0; m < 4; ++m) _Pragma("unroll") for (int k = 0; k < 2; ++k) dst[m][k] = *(const PG8_LAS bf16x8*)(lds + PG8_SA(b, h) + aoff + m * 2048 + k * 1024); } while (0)
; #define PG8_LDB(dst, b, h) do { _Pragma("unroll") for (int n = 0; n < 2; ++n) _Pragma("unroll") for (int k = 0; k < 2; ++k) dst[n][k] = *(const PG8_LAS bf16x8*)(lds + PG8_SB(b, h) + boff + n * 2048 + k * 1024); } while (0)
; #define PG8_MMA(ai, bj, At, Bt) do { __builtin_amdgcn_s_setprio(1); _Pragma("unroll") for (int m = 0; m < 4; ++m) _Pragma("unroll") for (int n = 0; n < 2; ++n) _Pragma("unroll") for (int k = 0; k < 2; ++k) \
;         acc[ai][bj][m][n] = __builtin_amdgcn_mfma_f32_16x16x32_bf16(Bt[n][k], At[m][k], acc[ai][bj][m][n], 0, 0, 0); __builtin_amdgcn_s_setprio(0); } while (0)
; #define PG8_WAIT_V(n) asm volatile("s_waitcnt vmcnt(" #n ")" ::: "memory")
; #define PG8_WAIT_L(n) asm volatile("s_waitcnt lgkmcnt(" #n ")" ::: "memory")
; #define PG8_BAR __builtin_amdgcn_s_barrier()
; #define PG8_SCHED __builtin_amdgcn_sched_barrier(0)
; template <class Epi, class Sched, bool ALIGN_EPI = false, bool SP2 = false, bool ATILED = false>
; __device__ __forceinline__ void gemm_phase(PG8_LAS unsigned char* lds, const Gemm g, const Sched& S, const Epi& E) {
;     ...
;             PG8_LDA(At, 0, 1); PG8_STAGE(PG8_SB(0, 0), b2, voffB); PG8_STAGE(PG8_SB(0, 1), b2 + hstep, voffB); PG8_STAGE(PG8_SA(0, 0), a2, voffA);
;             PG8_WAIT_V(8); PG8_WAIT_L(0); PG8_BAR; PG8_MMA(1, 0, At, B0); PG8_MMA(1, 1, At, B1); PG8_BAR; PG8_SCHED;
;             PG8_LDB(B0, 1, 0); PG8_LDB(B1, 1, 1); PG8_SCHED; PG8_LDA(At, 1, 0); PG8_STAGE(PG8_SA(0, 1), a2 + hstepA, voffA);
	s_mov_b32 m0, s58
	s_nop 0
	global_load_lds_dwordx4 v152, s[56:57]
	s_mov_b32 m0, s59
	s_nop 0
	global_load_lds_dwordx4 v156, s[56:57]
	s_waitcnt vmcnt(8)
	s_waitcnt lgkmcnt(0)
	s_barrier
	s_setprio 1
	s_waitcnt lgkmcnt(0)
	v_mfma_f32_16x16x32_bf16 v[60:63], v[128:131], v[176:179], 0
	v_mfma_f32_16x16x32_bf16 v[56:59], v[136:139], v[176:179], 0
	v_mfma_f32_16x16x32_bf16 v[44:47], v[128:131], v[194:197], 0
	v_mfma_f32_16x16x32_bf16 v[40:43], v[136:139], v[194:197], 0
	v_mfma_f32_16x16x32_bf16 v[28:31], v[128:131], v[204:207], 0
	v_mfma_f32_16x16x32_bf16 v[24:27], v[136:139], v[204:207], 0
	v_mfma_f32_16x16x32_bf16 v[12:15], v[128:131], v[212:215], 0
	v_mfma_f32_16x16x32_bf16 v[8:11], v[136:139], v[212:215], 0
	v_mfma_f32_16x16x32_bf16 v[60:63], v[132:135], v[180:183], v[60:63]
	v_mfma_f32_16x16x32_bf16 v[56:59], v[140:143], v[180:183], v[56:59]
	v_mfma_f32_16x16x32_bf16 v[44:47], v[132:135], v[200:203], v[44:47]
	v_mfma_f32_16x16x32_bf16 v[40:43], v[140:143], v[200:203], v[40:43]
	v_mfma_f32_16x16x32_bf16 v[28:31], v[132:135], v[208:211], v[28:31]
	v_mfma_f32_16x16x32_bf16 v[24:27], v[140:143], v[208:211], v[24:27]
	v_mfma_f32_16x16x32_bf16 v[12:15], v[132:135], v[216:219], v[12:15]
	v_mfma_f32_16x16x32_bf16 v[8:11], v[140:143], v[216:219], v[8:11]
	s_setprio 0
	s_setprio 1
	v_mfma_f32_16x16x32_bf16 v[52:55], v[144:147], v[176:179], 0
	v_mfma_f32_16x16x32_bf16 v[48:51], v[168:171], v[176:179], 0
	v_mfma_f32_16x16x32_bf16 v[36:39], v[144:147], v[194:197], 0
	v_mfma_f32_16x16x32_bf16 v[32:35], v[168:171], v[194:197], 0
	v_mfma_f32_16x16x32_bf16 v[20:23], v[144:147], v[204:207], 0
	v_mfma_f32_16x16x32_bf16 v[16:19], v[168:171], v[204:207], 0
	v_mfma_f32_16x16x32_bf16 v[4:7], v[144:147], v[212:215], 0
	v_mfma_f32_16x16x32_bf16 v[0:3], v[168:171], v[212:215], 0
	v_mfma_f32_16x16x32_bf16 v[52:55], v[148:151], v[180:183], v[52:55]
	v_mfma_f32_16x16x32_bf16 v[48:51], v[172:175], v[180:183], v[48:51]
	v_mfma_f32_16x16x32_bf16 v[36:39], v[148:151], v[200:203], v[36:39]
	v_mfma_f32_16x16x32_bf16 v[32:35], v[172:175], v[200:203], v[32:35]
	v_mfma_f32_16x16x32_bf16 v[20:23], v[148:151], v[208:211], v[20:23]
	v_mfma_f32_16x16x32_bf16 v[16:19], v[172:175], v[208:211], v[16:19]
	v_mfma_f32_16x16x32_bf16 v[4:7], v[148:151], v[216:219], v[4:7]
	v_mfma_f32_16x16x32_bf16 v[0:3], v[172:175], v[216:219], v[0:3]
	s_setprio 0
	s_barrier
	s_add_i32 s74, 0, 0x18000
	s_add_i32 s75, 0, 0x1c000
	v_add_u32_e32 v140, s74, v187
	v_add_u32_e32 v172, s75, v187
	ds_read_b128 v[128:131], v140
	ds_read_b128 v[132:135], v140 offset:1024
	ds_read_b128 v[136:139], v140 offset:2048
	ds_read_b128 v[140:143], v140 offset:3072
	ds_read_b128 v[144:147], v172
	ds_read_b128 v[148:151], v172 offset:1024
	ds_read_b128 v[168:171], v172 offset:2048
	ds_read_b128 v[172:175], v172 offset:3072
	s_add_u32 s56, s56, 0x40000
	s_addc_u32 s57, s57, 0
	s_mov_b32 m0, s60

; #define PG8_STAGE(bufoff, gbase, voff) do { _Pragma("unroll") for (int _i = 0; _i < 2; ++_i) \
;         __builtin_amdgcn_global_load_lds((const unsigned*)((const char*)(gbase) + (voff)[_i]), (PG8_LAS unsigned*)(lds + (bufoff) + ldsw + _i * 8192), 16, 0, 0); } while (0)
; #define PG8_LDA(dst, b, h) do { _Pragma("unroll") for (int m = 0; m < 4; ++m) _Pragma("unroll") for (int k = 0; k < 2; ++k) dst[m][k] = *(const PG8_LAS bf16x8*)(lds + PG8_SA(b, h) + aoff + m * 2048 + k * 1024); } while (0)
; #define PG8_LDB(dst, b, h) do { _Pragma("unroll") for (int n = 0; n < 2; ++n) _Pragma("unroll") for (int k = 0; k < 2; ++k) dst[n][k] = *(const PG8_LAS bf16x8*)(lds + PG8_SB(b, h) + boff + n * 2048 + k * 1024); } while (0)
; #define PG8_SCHED __builtin_amdgcn_sched_barrier(0)
; template <class Epi, class Sched, bool ALIGN_EPI = false, bool SP2 = false, bool ATILED = false>
; __device__ __forceinline__ void gemm_phase(PG8_LAS unsigned char* lds, const Gemm g, const Sched& S, const Epi& E) {
;     ...
;             PG8_LDB(B0, 1, 0); PG8_LDB(B1, 1, 1); PG8_SCHED; PG8_LDA(At, 1, 0); PG8_STAGE(PG8_SA(0, 1), a2 + hstepA, voffA);
	ds_read_b128 v[176:179], v191 offset:32768
	ds_read_b128 v[180:183], v191 offset:33792
	ds_read_b128 v[194:197], v191 offset:34816
	ds_read_b128 v[200:203], v191 offset:35840
	ds_read_b128 v[204:207], v191 offset:36864
	ds_read_b128 v[208:211], v191 offset:37888
	ds_read_b128 v[212:215], v191 offset:38912
	ds_read_b128 v[216:219], v191 offset:39936
	global_load_lds_dwordx4 v152, s[56:57]

; #define PG8_STAGE(bufoff, gbase, voff) do { _Pragma("unroll") for (int _i = 0; _i < 2; ++_i) \
;         __builtin_amdgcn_global_load_lds((const unsigned*)((const char*)(gbase) + (voff)[_i]), (PG8_LAS unsigned*)(lds + (bufoff) + ldsw + _i * 8192), 16, 0, 0); } while (0)
; #define PG8_LDA(dst, b, h) do { _Pragma("unroll") for (int m = 0; m < 4; ++m) _Pragma("unroll") for (int k = 0; k < 2; ++k) dst[m][k] = *(const PG8_LAS bf16x8*)(lds + PG8_SA(b, h) + aoff + m * 2048 + k * 1024); } while (0)
; #define PG8_LDB(dst, b, h) do { _Pragma("unroll") for (int n = 0; n < 2; ++n) _Pragma("unroll") for (int k = 0; k < 2; ++k) dst[n][k] = *(const PG8_LAS bf16x8*)(lds + PG8_SB(b, h) + boff + n * 2048 + k * 1024); } while (0)
; #define PG8_MMA(ai, bj, At, Bt) do { __builtin_amdgcn_s_setprio(1); _Pragma("unroll") for (int m = 0; m < 4; ++m) _Pragma("unroll") for (int n = 0; n < 2; ++n) _Pragma("unroll") for (int k = 0; k < 2; ++k) \
;         acc[ai][bj][m][n] = __builtin_amdgcn_mfma_f32_16x16x32_bf16(Bt[n][k], At[m][k], acc[ai][bj][m][n], 0, 0, 0); __builtin_amdgcn_s_setprio(0); } while (0)
; #define PG8_WAIT_V(n) asm volatile("s_waitcnt vmcnt(" #n ")" ::: "memory")
; #define PG8_WAIT_L(n) asm volatile("s_waitcnt lgkmcnt(" #n ")" ::: "memory")
; #define PG8_BAR __builtin_amdgcn_s_barrier()
; #define PG8_SCHED __builtin_amdgcn_sched_barrier(0)
; template <class Epi, class Sched, bool ALIGN_EPI = false, bool SP2 = false, bool ATILED = false>
; __device__ __forceinline__ void gemm_phase(PG8_LAS unsigned char* lds, const Gemm g, const Sched& S, const Epi& E) {
;     ...
;             PG8_LDB(B0, 1, 0); PG8_LDB(B1, 1, 1); PG8_SCHED; PG8_LDA(At, 1, 0); PG8_STAGE(PG8_SA(0, 1), a2 + hstepA, voffA);
;             PG8_WAIT_V(8); PG8_WAIT_L(0); PG8_BAR; PG8_MMA(0, 0, At, B0); PG8_MMA(0, 1, At, B1); PG8_BAR; PG8_SCHED;
	s_mov_b32 m0, s61
	s_nop 0
	global_load_lds_dwordx4 v156, s[56:57]
	s_waitcnt vmcnt(8)
	s_waitcnt lgkmcnt(0)
	s_barrier
	s_setprio 1
	s_waitcnt lgkmcnt(0)
	v_mfma_f32_16x16x32_bf16 v[124:127], v[128:131], v[176:179], v[124:127]
	v_mfma_f32_16x16x32_bf16 v[120:123], v[136:139], v[176:179], v[120:123]
	v_mfma_f32_16x16x32_bf16 v[108:111], v[128:131], v[194:197], v[108:111]
	v_mfma_f32_16x16x32_bf16 v[104:107], v[136:139], v[194:197], v[104:107]
	v_mfma_f32_16x16x32_bf16 v[92:95], v[128:131], v[204:207], v[92:95]
	v_mfma_f32_16x16x32_bf16 v[88:91], v[136:139], v[204:207], v[88:91]
	v_mfma_f32_16x16x32_bf16 v[76:79], v[128:131], v[212:215], v[76:79]
	v_mfma_f32_16x16x32_bf16 v[72:75], v[136:139], v[212:215], v[72:75]
	v_mfma_f32_16x16x32_bf16 v[124:127], v[132:135], v[180:183], v[124:127]
	v_mfma_f32_16x16x32_bf16 v[120:123], v[140:143], v[180:183], v[120:123]
	v_mfma_f32_16x16x32_bf16 v[108:111], v[132:135], v[200:203], v[108:111]
	v_mfma_f32_16x16x32_bf16 v[104:107], v[140:143], v[200:203], v[104:107]
	v_mfma_f32_16x16x32_bf16 v[92:95], v[132:135], v[208:211], v[92:95]
	v_mfma_f32_16x16x32_bf16 v[88:91], v[140:143], v[208:211], v[88:91]
	v_mfma_f32_16x16x32_bf16 v[76:79], v[132:135], v[216:219], v[76:79]
	v_mfma_f32_16x16x32_bf16 v[72:75], v[140:143], v[216:219], v[72:75]
	s_setprio 0
	s_setprio 1
	v_mfma_f32_16x16x32_bf16 v[116:119], v[144:147], v[176:179], v[116:119]
	v_mfma_f32_16x16x32_bf16 v[112:115], v[168:171], v[176:179], v[112:115]
	v_mfma_f32_16x16x32_bf16 v[100:103], v[144:147], v[194:197], v[100:103]
	v_mfma_f32_16x16x32_bf16 v[96:99], v[168:171], v[194:197], v[96:99]
	v_mfma_f32_16x16x32_bf16 v[84:87], v[144:147], v[204:207], v[84:87]
	v_mfma_f32_16x16x32_bf16 v[80:83], v[168:171], v[204:207], v[80:83]
	v_mfma_f32_16x16x32_bf16 v[68:71], v[144:147], v[212:215], v[68:71]
	v_mfma_f32_16x16x32_bf16 v[64:67], v[168:171], v[212:215], v[64:67]
	v_mfma_f32_16x16x32_bf16 v[116:119], v[148:151], v[180:183], v[116:119]
	v_mfma_f32_16x16x32_bf16 v[112:115], v[172:175], v[180:183], v[112:115]
	v_mfma_f32_16x16x32_bf16 v[100:103], v[148:151], v[200:203], v[100:103]
	v_mfma_f32_16x16x32_bf16 v[96:99], v[172:175], v[200:203], v[96:99]
	v_mfma_f32_16x16x32_bf16 v[84:87], v[148:151], v[208:211], v[84:87]
	v_mfma_f32_16x16x32_bf16 v[80:83], v[172:175], v[208:211], v[80:83]
	v_mfma_f32_16x16x32_bf16 v[68:71], v[148:151], v[216:219], v[68:71]
	v_mfma_f32_16x16x32_bf16 v[64:67], v[172:175], v[216:219], v[64:67]
	s_setprio 0
	s_barrier
	s_add_i32 s56, s74, s29

; #define PG8_STAGE(bufoff, gbase, voff) do { _Pragma("unroll") for (int _i = 0; _i < 2; ++_i) \
;         __builtin_amdgcn_global_load_lds((const unsigned*)((const char*)(gbase) + (voff)[_i]), (PG8_LAS unsigned*)(lds + (bufoff) + ldsw + _i * 8192), 16, 0, 0); } while (0)
; #define PG8_LDA(dst, b, h) do { _Pragma("unroll") for (int m = 0; m < 4; ++m) _Pragma("unroll") for (int k = 0; k < 2; ++k) dst[m][k] = *(const PG8_LAS bf16x8*)(lds + PG8_SA(b, h) + aoff + m * 2048 + k * 1024); } while (0)
; template <class Epi, class Sched, bool ALIGN_EPI = false, bool SP2 = false, bool ATILED = false>
; __device__ __forceinline__ void gemm_phase(PG8_LAS unsigned char* lds, const Gemm g, const Sched& S, const Epi& E) {
;     ...
;             PG8_LDA(At, 1, 1); PG8_STAGE(PG8_SB(1, 0), b3, voffB); PG8_STAGE(PG8_SB(1, 1), b3 + hstep, voffB); PG8_STAGE(PG8_SA(1, 0), a3, voffA);
	s_mov_b32 m0, s56
	ds_read_b128 v[176:179], v191 offset:49152
	ds_read_b128 v[180:183], v191 offset:50176
	ds_read_b128 v[194:197], v191 offset:51200
	ds_read_b128 v[200:203], v191 offset:52224
	ds_read_b128 v[204:207], v191 offset:53248
	ds_read_b128 v[208:211], v191 offset:54272
	ds_read_b128 v[212:215], v191 offset:55296
	ds_read_b128 v[216:219], v191 offset:56320
	global_load_lds_dwordx4 v154, s[98:99]
	s_add_i32 m0, s56, 0x2000
	s_add_u32 s54, s54, 0x40080

; #define PG8_STAGE(bufoff, gbase, voff) do { _Pragma("unroll") for (int _i = 0; _i < 2; ++_i) \
;         __builtin_amdgcn_global_load_lds((const unsigned*)((const char*)(gbase) + (voff)[_i]), (PG8_LAS unsigned*)(lds + (bufoff) + ldsw + _i * 8192), 16, 0, 0); } while (0)
; #define PG8_LDA(dst, b, h) do { _Pragma("unroll") for (int m = 0; m < 4; ++m) _Pragma("unroll") for (int k = 0; k < 2; ++k) dst[m][k] = *(const PG8_LAS bf16x8*)(lds + PG8_SA(b, h) + aoff + m * 2048 + k * 1024); } while (0)
; template <class Epi, class Sched, bool ALIGN_EPI = false, bool SP2 = false, bool ATILED = false>
; __device__ __forceinline__ void gemm_phase(PG8_LAS unsigned char* lds, const Gemm g, const Sched& S, const Epi& E) {
;     ...
;             PG8_LDA(At, 1, 1); PG8_STAGE(PG8_SB(1, 0), b3, voffB); PG8_STAGE(PG8_SB(1, 1), b3 + hstep, voffB); PG8_STAGE(PG8_SA(1, 0), a3, voffA);
	s_addc_u32 s55, s55, 0
	s_add_i32 s56, s75, s29
	global_load_lds_dwordx4 v158, s[98:99]

; #define PG8_STAGE(bufoff, gbase, voff) do { _Pragma("unroll") for (int _i = 0; _i < 2; ++_i) \
;         __builtin_amdgcn_global_load_lds((const unsigned*)((const char*)(gbase) + (voff)[_i]), (PG8_LAS unsigned*)(lds + (bufoff) + ldsw + _i * 8192), 16, 0, 0); } while (0)
; #define PG8_LDA(dst, b, h) do { _Pragma("unroll") for (int m = 0; m < 4; ++m) _Pragma("unroll") for (int k = 0; k < 2; ++k) dst[m][k] = *(const PG8_LAS bf16x8*)(lds + PG8_SA(b, h) + aoff + m * 2048 + k * 1024); } while (0)
; template <class Epi, class Sched, bool ALIGN_EPI = false, bool SP2 = false, bool ATILED = false>
; __device__ __forceinline__ void gemm_phase(PG8_LAS unsigned char* lds, const Gemm g, const Sched& S, const Epi& E) {
;     ...
;             PG8_LDA(At, 1, 1); PG8_STAGE(PG8_SB(1, 0), b3, voffB); PG8_STAGE(PG8_SB(1, 1), b3 + hstep, voffB); PG8_STAGE(PG8_SA(1, 0), a3, voffA);
	s_mov_b32 m0, s56
	s_nop 0
	global_load_lds_dwordx4 v154, s[54:55]

; #define PG8_STAGE(bufoff, gbase, voff) do { _Pragma("unroll") for (int _i = 0; _i < 2; ++_i) \
;         __builtin_amdgcn_global_load_lds((const unsigned*)((const char*)(gbase) + (voff)[_i]), (PG8_LAS unsigned*)(lds + (bufoff) + ldsw + _i * 8192), 16, 0, 0); } while (0)
; #define PG8_LDA(dst, b, h) do { _Pragma("unroll") for (int m = 0; m < 4; ++m) _Pragma("unroll") for (int k = 0; k < 2; ++k) dst[m][k] = *(const PG8_LAS bf16x8*)(lds + PG8_SA(b, h) + aoff + m * 2048 + k * 1024); } while (0)
; template <class Epi, class Sched, bool ALIGN_EPI = false, bool SP2 = false, bool ATILED = false>
; __device__ __forceinline__ void gemm_phase(PG8_LAS unsigned char* lds, const Gemm g, const Sched& S, const Epi& E) {
;     ...
;             PG8_LDA(At, 1, 1); PG8_STAGE(PG8_SB(1, 0), b3, voffB); PG8_STAGE(PG8_SB(1, 1), b3 + hstep, voffB); PG8_STAGE(PG8_SA(1, 0), a3, voffA);
	s_add_i32 m0, s56, 0x2000
	s_nop 0
	global_load_lds_dwordx4 v158, s[54:55]

; #define PG8_STAGE(bufoff, gbase, voff) do { _Pragma("unroll") for (int _i = 0; _i < 2; ++_i) \
;         __builtin_amdgcn_global_load_lds((const unsigned*)((const char*)(gbase) + (voff)[_i]), (PG8_LAS unsigned*)(lds + (bufoff) + ldsw + _i * 8192), 16, 0, 0); } while (0)
; #define PG8_LDA(dst, b, h) do { _Pragma("unroll") for (int m = 0; m < 4; ++m) _Pragma("unroll") for (int k = 0; k < 2; ++k) dst[m][k] = *(const PG8_LAS bf16x8*)(lds + PG8_SA(b, h) + aoff + m * 2048 + k * 1024); } while (0)
; template <class Epi, class Sched, bool ALIGN_EPI = false, bool SP2 = false, bool ATILED = false>
; __device__ __forceinline__ void gemm_phase(PG8_LAS unsigned char* lds, const Gemm g, const Sched& S, const Epi& E) {
;     ...
;             PG8_LDA(At, 1, 1); PG8_STAGE(PG8_SB(1, 0), b3, voffB); PG8_STAGE(PG8_SB(1, 1), b3 + hstep, voffB); PG8_STAGE(PG8_SA(1, 0), a3, voffA);
	s_mov_b32 m0, s63
	s_nop 0
	global_load_lds_dwordx4 v152, s[100:101]

; #define PG8_STAGE(bufoff, gbase, voff) do { _Pragma("unroll") for (int _i = 0; _i < 2; ++_i) \
;         __builtin_amdgcn_global_load_lds((const unsigned*)((const char*)(gbase) + (voff)[_i]), (PG8_LAS unsigned*)(lds + (bufoff) + ldsw + _i * 8192), 16, 0, 0); } while (0)
; #define PG8_LDA(dst, b, h) do { _Pragma("unroll") for (int m = 0; m < 4; ++m) _Pragma("unroll") for (int k = 0; k < 2; ++k) dst[m][k] = *(const PG8_LAS bf16x8*)(lds + PG8_SA(b, h) + aoff + m * 2048 + k * 1024); } while (0)
; #define PG8_MMA(ai, bj, At, Bt) do { __builtin_amdgcn_s_setprio(1); _Pragma("unroll") for (int m = 0; m < 4; ++m) _Pragma("unroll") for (int n = 0; n < 2; ++n) _Pragma("unroll") for (int k = 0; k < 2; ++k) \
;         acc[ai][bj][m][n] = __builtin_amdgcn_mfma_f32_16x16x32_bf16(Bt[n][k], At[m][k], acc[ai][bj][m][n], 0, 0, 0); __builtin_amdgcn_s_setprio(0); } while (0)
; #define PG8_WAIT_V(n) asm volatile("s_waitcnt vmcnt(" #n ")" ::: "memory")
; #define PG8_WAIT_L(n) asm volatile("s_waitcnt lgkmcnt(" #n ")" ::: "memory")
; #define PG8_BAR __builtin_amdgcn_s_barrier()
; #define PG8_SCHED __builtin_amdgcn_sched_barrier(0)
; template <class Epi, class Sched, bool ALIGN_EPI = false, bool SP2 = false, bool ATILED = false>
; __device__ __forceinline__ void gemm_phase(PG8_LAS unsigned char* lds, const Gemm g, const Sched& S, const Epi& E) {
;     ...
;             PG8_LDA(At, 1, 1); PG8_STAGE(PG8_SB(1, 0), b3, voffB); PG8_STAGE(PG8_SB(1, 1), b3 + hstep, voffB); PG8_STAGE(PG8_SA(1, 0), a3, voffA);
;             PG8_WAIT_V(8); PG8_WAIT_L(0); PG8_BAR; PG8_MMA(1, 0, At, B0); PG8_MMA(1, 1, At, B1); PG8_BAR; PG8_SCHED;
	s_mov_b32 m0, s64
	s_nop 0
	global_load_lds_dwordx4 v156, s[100:101]
	s_waitcnt vmcnt(8)
	s_waitcnt lgkmcnt(0)
	s_barrier
	s_setprio 1
	s_waitcnt lgkmcnt(0)
	v_mfma_f32_16x16x32_bf16 v[60:63], v[128:131], v[176:179], v[60:63]
	v_mfma_f32_16x16x32_bf16 v[56:59], v[136:139], v[176:179], v[56:59]
	v_mfma_f32_16x16x32_bf16 v[44:47], v[128:131], v[194:197], v[44:47]
	v_mfma_f32_16x16x32_bf16 v[40:43], v[136:139], v[194:197], v[40:43]
	v_mfma_f32_16x16x32_bf16 v[28:31], v[128:131], v[204:207], v[28:31]
	v_mfma_f32_16x16x32_bf16 v[24:27], v[136:139], v[204:207], v[24:27]
	v_mfma_f32_16x16x32_bf16 v[12:15], v[128:131], v[212:215], v[12:15]
	v_mfma_f32_16x16x32_bf16 v[8:11], v[136:139], v[212:215], v[8:11]
	v_mfma_f32_16x16x32_bf16 v[60:63], v[132:135], v[180:183], v[60:63]
	v_mfma_f32_16x16x32_bf16 v[56:59], v[140:143], v[180:183], v[56:59]
	v_mfma_f32_16x16x32_bf16 v[44:47], v[132:135], v[200:203], v[44:47]
	v_mfma_f32_16x16x32_bf16 v[40:43], v[140:143], v[200:203], v[40:43]
	v_mfma_f32_16x16x32_bf16 v[28:31], v[132:135], v[208:211], v[28:31]
	v_mfma_f32_16x16x32_bf16 v[24:27], v[140:143], v[208:211], v[24:27]
	v_mfma_f32_16x16x32_bf16 v[12:15], v[132:135], v[216:219], v[12:15]
	v_mfma_f32_16x16x32_bf16 v[8:11], v[140:143], v[216:219], v[8:11]
	s_setprio 0
	s_setprio 1
	v_mfma_f32_16x16x32_bf16 v[52:55], v[144:147], v[176:179], v[52:55]
	v_mfma_f32_16x16x32_bf16 v[48:51], v[168:171], v[176:179], v[48:51]
	v_mfma_f32_16x16x32_bf16 v[36:39], v[144:147], v[194:197], v[36:39]
	v_mfma_f32_16x16x32_bf16 v[32:35], v[168:171], v[194:197], v[32:35]
	v_mfma_f32_16x16x32_bf16 v[20:23], v[144:147], v[204:207], v[20:23]
	v_mfma_f32_16x16x32_bf16 v[16:19], v[168:171], v[204:207], v[16:19]
	v_mfma_f32_16x16x32_bf16 v[4:7], v[144:147], v[212:215], v[4:7]
	v_mfma_f32_16x16x32_bf16 v[0:3], v[168:171], v[212:215], v[0:3]
	v_mfma_f32_16x16x32_bf16 v[52:55], v[148:151], v[180:183], v[52:55]
	v_mfma_f32_16x16x32_bf16 v[48:51], v[172:175], v[180:183], v[48:51]
	v_mfma_f32_16x16x32_bf16 v[36:39], v[148:151], v[200:203], v[36:39]
	v_mfma_f32_16x16x32_bf16 v[32:35], v[172:175], v[200:203], v[32:35]
	v_mfma_f32_16x16x32_bf16 v[20:23], v[148:151], v[208:211], v[20:23]
	v_mfma_f32_16x16x32_bf16 v[16:19], v[172:175], v[208:211], v[16:19]
	v_mfma_f32_16x16x32_bf16 v[4:7], v[148:151], v[216:219], v[4:7]
	v_mfma_f32_16x16x32_bf16 v[0:3], v[172:175], v[216:219], v[0:3]
	s_setprio 0
	s_barrier
	s_add_i32 s73, s73, 2
	s_add_u32 s50, s50, 0x100
	s_addc_u32 s51, s51, 0
	s_add_u32 s71, s71, 0x100
	s_addc_u32 s72, s72, 0
	s_cmp_gt_u32 s73, 13

; #define PG8_BAR __builtin_amdgcn_s_barrier()
; template <class Epi, class Sched, bool ALIGN_EPI = false, bool SP2 = false, bool ATILED = false>
; __device__ __forceinline__ void gemm_phase(PG8_LAS unsigned char* lds, const Gemm g, const Sched& S, const Epi& E) {
;     ...
;         if constexpr (ALIGN_EPI) { if (wr == 0) PG8_BAR; }
;         if constexpr (!Epi::AFTER_DRAIN) { E(acc, cur, wr, wc, fr, fq); S.done(cur); }
;         if (!has_next) break;
; #pragma unroll
;         for (int a = 0; a < 2; ++a)
; #pragma unroll
;             for (int b = 0; b < 2; ++b)
; #pragma unroll
;                 for (int m = 0; m < 4; ++m)
; #pragma unroll
;                     for (int n = 0; n < 2; ++n) acc[a][b][m][n] = (f32x4){0.f, 0.f, 0.f, 0.f};
;         cur = nxt; cA = nA; cB = nB; ++ui;
;         if constexpr (ALIGN_EPI) { if (wr == 1) PG8_BAR; }
;     }
.LBB0_754:
	s_or_b64 exec, exec, s[50:51]
	s_andn2_b64 vcc, exec, s[4:5]
	s_mov_b64 s[4:5], -1
	s_cbranch_vccnz .LBB0_727
	s_branch .LBB0_726

; template <class Epi, class Sched, bool ALIGN_EPI = false, bool SP2 = false, bool ATILED = false>
; __device__ __forceinline__ void gemm_phase(PG8_LAS unsigned char* lds, const Gemm g, const Sched& S, const Epi& E) {
;     const int tid = threadIdx.x, wid = __builtin_amdgcn_readfirstlane(tid >> 6), lane = tid & 63, wr = wid >> 2, wc = wid & 3, fr = lane & 15, fq = lane >> 4;
;     const int K = g.K, nt = K / BK;
;     unsigned voffA[2], voffB[2];
; #pragma unroll
;     for (int i = 0; i < 2; ++i) { int R, C; stage_rc(tid * 16 + i * 8192, R, C); const int Rb = Epi::PERM ? ((R & ~31) + perm32(R & 31)) : R;
;         voffA[i] = (unsigned)(R * (ATILED ? BK : K) + C) * 2u; voffB[i] = (unsigned)(Rb * K + C) * 2u; }
;     const size_t kstep = (size_t)(BK * 2);
;     const size_t hstep = (size_t)HALF * K * 2;
;     const size_t tstep = 2 * hstep;
;     const size_t kstepA = ATILED ? (size_t)(BM * BK * 2) : kstep, hstepA = ATILED ? (size_t)(HALF * BK * 2) : hstep, tstepA = ATILED ? (size_t)nt * (BM * BK * 2) : tstep;
;     const unsigned ldsw = (unsigned)wid * 1024u;
;     const int aoff = lds_byte(wr * 64 + fr, fq * 8), boff = lds_byte(wc * 32 + fr, fq * 8);
;     ...
;     Unit cur, nxt; int ui = 0;
;     if (!S.next(0, cur)) return;
;     f32x4 acc[2][2][4][2];
; #pragma unroll
;     for (int a = 0; a < 2; ++a)
; #pragma unroll
;         for (int b = 0; b < 2; ++b)
; #pragma unroll
;             for (int m = 0; m < 4; ++m)
; #pragma unroll
;                 for (int n = 0; n < 2; ++n) acc[a][b][m][n] = (f32x4){0.f, 0.f, 0.f, 0.f};
;     bf16x8 At[4][2], B0[2][2], B1[2][2];
;     const char* cA = (const char*)g.A + (size_t)cur.pm * tstepA; const char* cB = (const char*)g.Bt + (size_t)cur.pn * tstep;
;     S.a_ready(cur);
;     if constexpr (SP2) {
;         PG8_STAGE(PG8_SB(0, 0), cB, voffB); PG8_STAGE(PG8_SB(0, 1), cB + hstep, voffB); PG8_STAGE(PG8_SA(0, 0), cA, voffA); PG8_STAGE(PG8_SA(0, 1), cA + hstepA, voffA);
;         if (wr == 1) PG8_BAR;
;         PG8_WAIT_V(2); PG8_BAR;
;         PG8_STAGE(PG8_SB(1, 0), cB + kstep, voffB); PG8_STAGE(PG8_SA(1, 0), cA + kstepA, voffA); PG8_STAGE(PG8_SB(1, 1), cB + hstep + kstep, voffB);
;         PG8_WAIT_V(6); PG8_BAR;
;     } else {
;         PG8_STAGE(PG8_SB(0, 0), cB, voffB); PG8_STAGE(PG8_SA(0, 0), cA, voffA); PG8_STAGE(PG8_SB(0, 1), cB + hstep, voffB); PG8_STAGE(PG8_SA(0, 1), cA + hstepA, voffA);
.LBB0_807:
	s_cmp_lt_i32 s30, 7
	s_cselect_b64 s[0:1], -1, 0
	s_cmp_gt_i32 s31, 6
	s_cselect_b64 s[4:5], -1, 0
	s_and_b64 s[0:1], s[0:1], s[4:5]
	s_andn2_b64 vcc, exec, s[0:1]
	s_cbranch_vccnz .LBB0_874
	s_cmpk_gt_i32 s2, 0x15ff
	v_readfirstlane_b32 s1, v198
	s_cbranch_scc1 .LBB0_824
	s_waitcnt vmcnt(3)
	v_lshrrev_b32_e32 v2, 1, v198
	v_lshrrev_b32_e32 v3, 5, v198
	v_and_b32_e32 v2, 24, v2
	v_and_b32_e32 v3, 4, v3
	s_waitcnt vmcnt(2)
	v_bfe_u32 v4, v198, 2, 2
	v_lshlrev_b32_e32 v0, 4, v198
	s_waitcnt lgkmcnt(0)
	v_and_b32_e32 v1, 32, v198
	s_waitcnt vmcnt(1)
	v_bfe_u32 v10, v198, 2, 4
	v_or3_b32 v2, v3, v4, v2
	v_lshrrev_b32_e32 v3, 3, v198
	s_movk_i32 s0, 0x70
	v_bitop3_b32 v8, v0, v1, 48 bitop3:0x6c
	v_and_b32_e32 v9, 64, v198
	v_and_or_b32 v4, v3, s0, v10
	s_movk_i32 s0, 0x60
	v_add_u32_e32 v11, 0x2000, v0
	v_or_b32_e32 v1, v8, v9
	v_and_or_b32 v3, v3, s0, v2
	v_lshrrev_b32_e32 v0, 7, v11
	s_movk_i32 s0, 0xf0
	v_lshl_or_b32 v130, v3, 11, v1
	v_and_or_b32 v3, v0, s0, v10
	s_movk_i32 s0, 0xe0
	s_ashr_i32 s29, s2, 31
	v_and_or_b32 v0, v0, s0, v2
	s_lshr_b32 s0, s29, 29
	s_add_i32 s0, s2, s0
	s_lshr_b32 s6, s1, 6
	s_ashr_i32 s4, s0, 3
	s_and_b32 s0, s0, -8
	s_lshr_b32 s7, s1, 8
	s_lshl_b32 s46, s6, 10
	s_sub_i32 s0, s2, s0
	s_cmp_lt_i32 s0, 0
	s_movk_i32 s47, 0x2c1
	s_cselect_b32 s5, s47, 0x2c0
	s_mul_i32 s0, s0, s5
	s_add_i32 s0, s0, s4
	s_mul_hi_i32 s4, s0, 0x2e8ba2e9
	s_lshr_b32 s5, s4, 31
	s_ashr_i32 s4, s4, 5
	s_add_i32 s4, s4, s5
	s_lshl_b32 s5, s4, 3
	s_mulk_i32 s4, 0xb0
	s_sub_i32 s4, s0, s4
	s_bfe_u32 s0, s4, 0x3001c
	s_add_i32 s8, s4, s0
	s_sext_i32_i16 s0, s8
	s_and_b32 s8, s8, 0xfff8
	s_sub_i32 s4, s4, s8
	s_sext_i32_i16 s4, s4
	s_lshr_b32 s0, s0, 3
	s_add_i32 s18, s5, s4
	s_ashr_i32 s19, s18, 31
	s_bfe_i64 s[8:9], s[0:1], 0x100000
	s_lshl_b64 s[4:5], s[18:19], 19
	s_lshl_b64 s[8:9], s[8:9], 19
	s_add_u32 s42, s40, s8
	s_addc_u32 s43, s41, s9
	s_add_i32 s19, s46, 0
	s_add_i32 m0, s19, 0x10000
	v_lshl_or_b32 v134, v0, 11, v1
	global_load_lds_dwordx4 v130, s[42:43]
	s_add_i32 m0, s19, 0x12000
	s_add_u32 s8, s42, 0x40000
	global_load_lds_dwordx4 v134, s[42:43]
	s_addc_u32 s9, s43, 0
	s_add_i32 m0, s19, 0x14000
	v_lshl_or_b32 v128, v4, 11, v1
	global_load_lds_dwordx4 v130, s[8:9]
	s_add_i32 m0, s19, 0x16000
	s_add_u32 s20, s26, s4
	s_addc_u32 s21, s27, s5
	s_add_i32 s48, s19, 0x2000
	global_load_lds_dwordx4 v134, s[8:9]
	s_mov_b32 m0, s19
	s_add_u32 s4, s20, 0x40000
	v_lshl_or_b32 v132, v3, 11, v1
	global_load_lds_dwordx4 v128, s[20:21]
	s_mov_b32 m0, s48
	s_addc_u32 s5, s21, 0
	s_add_i32 s49, s19, 0x4000
	global_load_lds_dwordx4 v132, s[20:21]
	s_mov_b32 m0, s49
	s_add_i32 s50, s19, 0x6000
	global_load_lds_dwordx4 v128, s[4:5]
	s_mov_b32 m0, s50
	v_mov_b32_e32 v137, 0
	global_load_lds_dwordx4 v132, s[4:5]
	v_mov_b32_e32 v131, v137
	v_mov_b32_e32 v135, v137
	v_mov_b32_e32 v129, v137
	v_mov_b32_e32 v133, v137
	s_cmp_eq_u32 s7, 1
	s_movk_i32 s51, 0x2000
	s_mov_b32 s54, 0
	v_lshl_add_u64 v[6:7], s[42:43], 0, v[130:131]
	v_lshl_add_u64 v[4:5], s[42:43], 0, v[134:135]
	v_lshl_add_u64 v[0:1], s[20:21], 0, v[128:129]
	s_cselect_b64 s[4:5], -1, 0
	s_cmp_lg_u32 s7, 1
	v_lshl_add_u64 v[2:3], s[20:21], 0, v[132:133]
.LBB0_811:
	s_lshl_b32 s56, s7, 6
	s_lshl_b32 s12, s7, 13
	s_lshl_b32 s13, s6, 5
	s_mov_b64 s[6:7], 0x80
	s_and_b32 s57, s13, 0x60
	s_add_i32 m0, s19, 0x18000
	v_lshl_add_u64 v[6:7], v[6:7], 0, s[6:7]
	s_ashr_i32 s55, s28, 31
	s_lshl_b32 s14, s57, 7
	s_waitcnt vmcnt(2)
	s_barrier
	global_load_lds_dwordx4 v[6:7], off
	v_lshl_add_u64 v[4:5], v[4:5], 0, s[6:7]
	s_add_i32 m0, s19, 0x1a000
	s_add_i32 s58, s19, 0x8000
	s_add_i32 s59, s19, 0xa000
	global_load_lds_dwordx4 v[4:5], off
	v_lshl_add_u64 v[0:1], v[0:1], 0, s[6:7]
	s_mov_b32 m0, s58
	s_add_u32 s8, s42, 0x40080
	global_load_lds_dwordx4 v[0:1], off
	v_lshl_add_u64 v[0:1], v[2:3], 0, s[6:7]
	s_mov_b32 m0, s59
	s_addc_u32 s9, s43, 0
	global_load_lds_dwordx4 v[0:1], off
	s_add_i32 m0, s19, 0x1c000
	v_lshl_add_u64 v[0:1], s[8:9], 0, v[130:131]
	global_load_lds_dwordx4 v[0:1], off
	v_lshl_add_u64 v[0:1], s[8:9], 0, v[134:135]
	s_add_i32 m0, s19, 0x1e000
	s_sext_i32_i16 s63, s0
	global_load_lds_dwordx4 v[0:1], off
	v_bfe_u32 v0, v198, 4, 2
	v_lshlrev_b32_e32 v1, 3, v0
	v_lshlrev_b32_e32 v136, 4, v0
	v_lshlrev_b32_e32 v0, 6, v198
	s_movk_i32 s0, 0x3c0
	v_lshlrev_b32_e32 v2, 2, v198
	v_and_b32_e32 v154, 15, v198
	v_and_or_b32 v0, v0, s0, v136
	v_and_b32_e32 v2, 32, v2
	v_lshl_or_b32 v3, v154, 6, v136
	v_bitop3_b32 v155, s14, v0, v2 bitop3:0xf6
	v_and_or_b32 v0, s13, 32, v1
	v_lshlrev_b32_e32 v1, 8, v198
	v_bitop3_b32 v3, v3, s12, v2 bitop3:0xde
	v_and_b32_e32 v1, 0x38000, v1
	v_lshlrev_b32_e32 v2, 11, v10
	v_or3_b32 v1, v8, v1, v2
	v_add_u32_e32 v140, v1, v9
	v_lshlrev_b32_e32 v1, 4, v11
	v_and_b32_e32 v1, 0x78000, v1
	s_waitcnt vmcnt(6)
	s_cmpk_lt_u32 s1, 0x100
	v_or3_b32 v1, v8, v1, v2
	s_cselect_b64 s[8:9], -1, 0
	v_add_u32_e32 v142, v1, v9
	s_add_i32 s60, 0, 0x10000
	s_add_i32 s61, 0, 0x14000
	v_mbcnt_lo_u32_b32 v1, -1, 0
	v_lshl_add_u64 v[138:139], s[10:11], 0, v[136:137]
	v_mov_b32_e32 v141, v137
	v_mov_b32_e32 v143, v137
	v_mov_b64_e32 v[144:145], 0x1600
	v_mov_b64_e32 v[146:147], 0x15ff
	v_add_u32_e32 v156, s60, v155
	v_add_u32_e32 v157, s61, v155
	v_add_u32_e32 v158, 0, v3
	v_mbcnt_hi_u32_b32 v159, -1, v1
	v_mov_b32_e32 v160, 0x358637bd
	v_lshlrev_b32_e32 v148, 1, v0
	s_movk_i32 s62, 0x1000
	s_barrier
	s_branch .LBB0_814

; #define PG8_STAGE(bufoff, gbase, voff) do { _Pragma("unroll") for (int _i = 0; _i < 2; ++_i) \
;         __builtin_amdgcn_global_load_lds((const unsigned*)((const char*)(gbase) + (voff)[_i]), (PG8_LAS unsigned*)(lds + (bufoff) + ldsw + _i * 8192), 16, 0, 0); } while (0)
; #define PG8_LDA(dst, b, h) do { _Pragma("unroll") for (int m = 0; m < 4; ++m) _Pragma("unroll") for (int k = 0; k < 2; ++k) dst[m][k] = *(const PG8_LAS bf16x8*)(lds + PG8_SA(b, h) + aoff + m * 2048 + k * 1024); } while (0)
; #define PG8_LDB(dst, b, h) do { _Pragma("unroll") for (int n = 0; n < 2; ++n) _Pragma("unroll") for (int k = 0; k < 2; ++k) dst[n][k] = *(const PG8_LAS bf16x8*)(lds + PG8_SB(b, h) + boff + n * 2048 + k * 1024); } while (0)
; #define PG8_SCHED __builtin_amdgcn_sched_barrier(0)
; template <class Epi, class Sched, bool ALIGN_EPI = false, bool SP2 = false, bool ATILED = false>
; __device__ __forceinline__ void gemm_phase(PG8_LAS unsigned char* lds, const Gemm g, const Sched& S, const Epi& E) {
;     ...
;         const bool has_next = S.next(ui + 1, nxt);
;         const char* nA = has_next ? (const char*)g.A + (size_t)nxt.pm * tstepA : cA; const char* nB = has_next ? (const char*)g.Bt + (size_t)nxt.pn * tstep : cB;
;         for (int t = 0; t < nt; t += 2) {
;             const bool last = (t == nt - 2);
;             const char* a1 = cA + (size_t)(t + 1) * kstepA;
;             const char* a2 = last ? nA : cA + (size_t)(t + 2) * kstepA; const char* b2 = last ? nB : cB + (size_t)(t + 2) * kstep;
;             const char* a3 = a2 + kstepA; const char* b3 = b2 + kstep;
;             if (last && has_next) S.a_ready(nxt);
;             if constexpr (SP2) {
;             PG8_LDB(B0, 0, 0); PG8_LDB(B1, 0, 1); PG8_SCHED; PG8_LDA(At, 0, 0); PG8_STAGE(PG8_SA(1, 1), a1 + hstepA, voffA);
.LBB0_816:
	s_ashr_i32 s13, s12, 31
	s_lshl_b64 s[14:15], s[12:13], 19
	s_add_u32 s14, s26, s14
	s_addc_u32 s15, s27, s15
	s_and_b64 s[16:17], s[0:1], exec
	s_cselect_b32 s13, s15, s21
	s_cselect_b32 s64, s14, s20
	s_ashr_i32 s11, s10, 31
	s_lshl_b64 s[16:17], s[10:11], 19
	s_add_u32 s16, s40, s16
	s_addc_u32 s17, s41, s17
	s_and_b64 s[44:45], s[0:1], exec
	s_cselect_b32 s11, s17, s43
	s_cselect_b32 s65, s16, s42
	s_add_u32 s20, s20, 0x40080
	s_addc_u32 s21, s21, 0
	s_add_u32 s66, s42, 0x100
	s_addc_u32 s67, s43, 0
	s_mov_b32 s68, -2
	s_waitcnt vmcnt(0)
	s_cmp_lg_u64 s[4:5], 0
	s_cbranch_scc0 .Ltbar_skip4
	s_barrier
.Ltbar_skip4:
	ds_read_b128 v[150:153], v156
	ds_read_b128 v[162:165], v156 offset:1024
	ds_read_b128 v[166:169], v156 offset:2048
	ds_read_b128 v[170:173], v156 offset:3072
	ds_read_b128 v[174:177], v157
	ds_read_b128 v[178:181], v157 offset:1024
	ds_read_b128 v[182:185], v157 offset:2048
	ds_read_b128 v[186:189], v157 offset:3072
	s_add_u32 s42, s20, 0xfffc0080
	s_addc_u32 s43, s21, -1
	s_cmp_eq_u32 s68, 12
	s_cselect_b32 s45, s13, s43
	s_cselect_b32 s44, s64, s42
	s_cselect_b32 s43, s11, s67
	s_cselect_b32 s42, s65, s66

; #define PG8_STAGE(bufoff, gbase, voff) do { _Pragma("unroll") for (int _i = 0; _i < 2; ++_i) \
;         __builtin_amdgcn_global_load_lds((const unsigned*)((const char*)(gbase) + (voff)[_i]), (PG8_LAS unsigned*)(lds + (bufoff) + ldsw + _i * 8192), 16, 0, 0); } while (0)
; #define PG8_LDA(dst, b, h) do { _Pragma("unroll") for (int m = 0; m < 4; ++m) _Pragma("unroll") for (int k = 0; k < 2; ++k) dst[m][k] = *(const PG8_LAS bf16x8*)(lds + PG8_SA(b, h) + aoff + m * 2048 + k * 1024); } while (0)
; #define PG8_LDB(dst, b, h) do { _Pragma("unroll") for (int n = 0; n < 2; ++n) _Pragma("unroll") for (int k = 0; k < 2; ++k) dst[n][k] = *(const PG8_LAS bf16x8*)(lds + PG8_SB(b, h) + boff + n * 2048 + k * 1024); } while (0)
; #define PG8_SCHED __builtin_amdgcn_sched_barrier(0)
; template <class Epi, class Sched, bool ALIGN_EPI = false, bool SP2 = false, bool ATILED = false>
; __device__ __forceinline__ void gemm_phase(PG8_LAS unsigned char* lds, const Gemm g, const Sched& S, const Epi& E) {
;     ...
;             PG8_LDB(B0, 0, 0); PG8_LDB(B1, 0, 1); PG8_SCHED; PG8_LDA(At, 0, 0); PG8_STAGE(PG8_SA(1, 1), a1 + hstepA, voffA);
	s_add_i32 m0, s19, 0xc000
	ds_read_b128 v[190:193], v158
	ds_read_b128 v[194:197], v158 offset:1024
	ds_read_b128 v[200:203], v158 offset:2048
	ds_read_b128 v[204:207], v158 offset:3072
	ds_read_b128 v[208:211], v158 offset:4096
	ds_read_b128 v[212:215], v158 offset:5120
	ds_read_b128 v[216:219], v158 offset:6144
	ds_read_b128 v[220:223], v158 offset:7168
	global_load_lds_dwordx4 v140, s[20:21]

; #define PG8_STAGE(bufoff, gbase, voff) do { _Pragma("unroll") for (int _i = 0; _i < 2; ++_i) \
;         __builtin_amdgcn_global_load_lds((const unsigned*)((const char*)(gbase) + (voff)[_i]), (PG8_LAS unsigned*)(lds + (bufoff) + ldsw + _i * 8192), 16, 0, 0); } while (0)
; #define PG8_LDA(dst, b, h) do { _Pragma("unroll") for (int m = 0; m < 4; ++m) _Pragma("unroll") for (int k = 0; k < 2; ++k) dst[m][k] = *(const PG8_LAS bf16x8*)(lds + PG8_SA(b, h) + aoff + m * 2048 + k * 1024); } while (0)
; #define PG8_LDB(dst, b, h) do { _Pragma("unroll") for (int n = 0; n < 2; ++n) _Pragma("unroll") for (int k = 0; k < 2; ++k) dst[n][k] = *(const PG8_LAS bf16x8*)(lds + PG8_SB(b, h) + boff + n * 2048 + k * 1024); } while (0)
; #define PG8_MMA(ai, bj, At, Bt) do { __builtin_amdgcn_s_setprio(1); _Pragma("unroll") for (int m = 0; m < 4; ++m) _Pragma("unroll") for (int n = 0; n < 2; ++n) _Pragma("unroll") for (int k = 0; k < 2; ++k) \
;         acc[ai][bj][m][n] = __builtin_amdgcn_mfma_f32_16x16x32_bf16(Bt[n][k], At[m][k], acc[ai][bj][m][n], 0, 0, 0); __builtin_amdgcn_s_setprio(0); } while (0)
; #define PG8_WAIT_V(n) asm volatile("s_waitcnt vmcnt(" #n ")" ::: "memory")
; #define PG8_WAIT_L(n) asm volatile("s_waitcnt lgkmcnt(" #n ")" ::: "memory")
; #define PG8_BAR __builtin_amdgcn_s_barrier()
; #define PG8_SCHED __builtin_amdgcn_sched_barrier(0)
; template <class Epi, class Sched, bool ALIGN_EPI = false, bool SP2 = false, bool ATILED = false>
; __device__ __forceinline__ void gemm_phase(PG8_LAS unsigned char* lds, const Gemm g, const Sched& S, const Epi& E) {
;     ...
;             PG8_LDB(B0, 0, 0); PG8_LDB(B1, 0, 1); PG8_SCHED; PG8_LDA(At, 0, 0); PG8_STAGE(PG8_SA(1, 1), a1 + hstepA, voffA);
;             PG8_WAIT_V(8); PG8_WAIT_L(0); PG8_BAR; PG8_MMA(0, 0, At, B0); PG8_MMA(0, 1, At, B1); PG8_BAR; PG8_SCHED;
	s_add_i32 m0, s19, 0xe000
	s_nop 0
	global_load_lds_dwordx4 v142, s[20:21]
	s_waitcnt vmcnt(8)
	s_waitcnt lgkmcnt(0)
	s_barrier
	s_setprio 1
	s_waitcnt lgkmcnt(0)
	v_mfma_f32_16x16x32_bf16 v[124:127], v[150:153], v[190:193], 0
	v_mfma_f32_16x16x32_bf16 v[120:123], v[166:169], v[190:193], 0
	v_mfma_f32_16x16x32_bf16 v[108:111], v[150:153], v[200:203], 0
	v_mfma_f32_16x16x32_bf16 v[104:107], v[166:169], v[200:203], 0
	v_mfma_f32_16x16x32_bf16 v[92:95], v[150:153], v[208:211], 0
	v_mfma_f32_16x16x32_bf16 v[88:91], v[166:169], v[208:211], 0
	v_mfma_f32_16x16x32_bf16 v[76:79], v[150:153], v[216:219], 0
	v_mfma_f32_16x16x32_bf16 v[72:75], v[166:169], v[216:219], 0
	v_mfma_f32_16x16x32_bf16 v[124:127], v[162:165], v[194:197], v[124:127]
	v_mfma_f32_16x16x32_bf16 v[120:123], v[170:173], v[194:197], v[120:123]
	v_mfma_f32_16x16x32_bf16 v[108:111], v[162:165], v[204:207], v[108:111]
	v_mfma_f32_16x16x32_bf16 v[104:107], v[170:173], v[204:207], v[104:107]
	v_mfma_f32_16x16x32_bf16 v[92:95], v[162:165], v[212:215], v[92:95]
	v_mfma_f32_16x16x32_bf16 v[88:91], v[170:173], v[212:215], v[88:91]
	v_mfma_f32_16x16x32_bf16 v[76:79], v[162:165], v[220:223], v[76:79]
	v_mfma_f32_16x16x32_bf16 v[72:75], v[170:173], v[220:223], v[72:75]
	s_setprio 0
	s_setprio 1
	v_mfma_f32_16x16x32_bf16 v[116:119], v[174:177], v[190:193], 0
	v_mfma_f32_16x16x32_bf16 v[112:115], v[182:185], v[190:193], 0
	v_mfma_f32_16x16x32_bf16 v[100:103], v[174:177], v[200:203], 0
	v_mfma_f32_16x16x32_bf16 v[96:99], v[182:185], v[200:203], 0
	v_mfma_f32_16x16x32_bf16 v[84:87], v[174:177], v[208:211], 0
	v_mfma_f32_16x16x32_bf16 v[80:83], v[182:185], v[208:211], 0
	v_mfma_f32_16x16x32_bf16 v[68:71], v[174:177], v[216:219], 0
	v_mfma_f32_16x16x32_bf16 v[64:67], v[182:185], v[216:219], 0
	v_mfma_f32_16x16x32_bf16 v[116:119], v[178:181], v[194:197], v[116:119]
	v_mfma_f32_16x16x32_bf16 v[112:115], v[186:189], v[194:197], v[112:115]
	v_mfma_f32_16x16x32_bf16 v[100:103], v[178:181], v[204:207], v[100:103]
	v_mfma_f32_16x16x32_bf16 v[96:99], v[186:189], v[204:207], v[96:99]
	v_mfma_f32_16x16x32_bf16 v[84:87], v[178:181], v[212:215], v[84:87]
	v_mfma_f32_16x16x32_bf16 v[80:83], v[186:189], v[212:215], v[80:83]
	v_mfma_f32_16x16x32_bf16 v[68:71], v[178:181], v[220:223], v[68:71]
	v_mfma_f32_16x16x32_bf16 v[64:67], v[186:189], v[220:223], v[64:67]
	s_setprio 0
	s_barrier
	s_add_u32 s98, s42, s6
	s_addc_u32 s99, s43, s7
	s_add_u32 s100, s44, s6
	s_addc_u32 s101, s45, s7
	s_add_i32 s69, s60, s46

; #define PG8_STAGE(bufoff, gbase, voff) do { _Pragma("unroll") for (int _i = 0; _i < 2; ++_i) \
;         __builtin_amdgcn_global_load_lds((const unsigned*)((const char*)(gbase) + (voff)[_i]), (PG8_LAS unsigned*)(lds + (bufoff) + ldsw + _i * 8192), 16, 0, 0); } while (0)
; #define PG8_LDA(dst, b, h) do { _Pragma("unroll") for (int m = 0; m < 4; ++m) _Pragma("unroll") for (int k = 0; k < 2; ++k) dst[m][k] = *(const PG8_LAS bf16x8*)(lds + PG8_SA(b, h) + aoff + m * 2048 + k * 1024); } while (0)
; template <class Epi, class Sched, bool ALIGN_EPI = false, bool SP2 = false, bool ATILED = false>
; __device__ __forceinline__ void gemm_phase(PG8_LAS unsigned char* lds, const Gemm g, const Sched& S, const Epi& E) {
;     ...
;             PG8_LDA(At, 0, 1); PG8_STAGE(PG8_SB(0, 0), b2, voffB); PG8_STAGE(PG8_SB(0, 1), b2 + hstep, voffB); PG8_STAGE(PG8_SA(0, 0), a2, voffA);
	s_mov_b32 m0, s69
	ds_read_b128 v[190:193], v158 offset:16384
	ds_read_b128 v[194:197], v158 offset:17408
	ds_read_b128 v[200:203], v158 offset:18432
	ds_read_b128 v[204:207], v158 offset:19456
	ds_read_b128 v[208:211], v158 offset:20480
	ds_read_b128 v[212:215], v158 offset:21504
	ds_read_b128 v[216:219], v158 offset:22528
	ds_read_b128 v[220:223], v158 offset:23552
	global_load_lds_dwordx4 v130, s[42:43]
	s_add_i32 m0, s69, 0x2000
	s_add_u32 s70, s42, 0x40000

; #define PG8_STAGE(bufoff, gbase, voff) do { _Pragma("unroll") for (int _i = 0; _i < 2; ++_i) \
;         __builtin_amdgcn_global_load_lds((const unsigned*)((const char*)(gbase) + (voff)[_i]), (PG8_LAS unsigned*)(lds + (bufoff) + ldsw + _i * 8192), 16, 0, 0); } while (0)
; #define PG8_LDA(dst, b, h) do { _Pragma("unroll") for (int m = 0; m < 4; ++m) _Pragma("unroll") for (int k = 0; k < 2; ++k) dst[m][k] = *(const PG8_LAS bf16x8*)(lds + PG8_SA(b, h) + aoff + m * 2048 + k * 1024); } while (0)
; template <class Epi, class Sched, bool ALIGN_EPI = false, bool SP2 = false, bool ATILED = false>
; __device__ __forceinline__ void gemm_phase(PG8_LAS unsigned char* lds, const Gemm g, const Sched& S, const Epi& E) {
;     ...
;             PG8_LDA(At, 0, 1); PG8_STAGE(PG8_SB(0, 0), b2, voffB); PG8_STAGE(PG8_SB(0, 1), b2 + hstep, voffB); PG8_STAGE(PG8_SA(0, 0), a2, voffA);
	s_addc_u32 s71, s43, 0
	s_add_i32 s69, s61, s46
	global_load_lds_dwordx4 v134, s[42:43]

; #define PG8_STAGE(bufoff, gbase, voff) do { _Pragma("unroll") for (int _i = 0; _i < 2; ++_i) \
;         __builtin_amdgcn_global_load_lds((const unsigned*)((const char*)(gbase) + (voff)[_i]), (PG8_LAS unsigned*)(lds + (bufoff) + ldsw + _i * 8192), 16, 0, 0); } while (0)
; #define PG8_LDA(dst, b, h) do { _Pragma("unroll") for (int m = 0; m < 4; ++m) _Pragma("unroll") for (int k = 0; k < 2; ++k) dst[m][k] = *(const PG8_LAS bf16x8*)(lds + PG8_SA(b, h) + aoff + m * 2048 + k * 1024); } while (0)
; template <class Epi, class Sched, bool ALIGN_EPI = false, bool SP2 = false, bool ATILED = false>
; __device__ __forceinline__ void gemm_phase(PG8_LAS unsigned char* lds, const Gemm g, const Sched& S, const Epi& E) {
;     ...
;             PG8_LDA(At, 0, 1); PG8_STAGE(PG8_SB(0, 0), b2, voffB); PG8_STAGE(PG8_SB(0, 1), b2 + hstep, voffB); PG8_STAGE(PG8_SA(0, 0), a2, voffA);
	s_mov_b32 m0, s69

; #define PG8_STAGE(bufoff, gbase, voff) do { _Pragma("unroll") for (int _i = 0; _i < 2; ++_i) \
;         __builtin_amdgcn_global_load_lds((const unsigned*)((const char*)(gbase) + (voff)[_i]), (PG8_LAS unsigned*)(lds + (bufoff) + ldsw + _i * 8192), 16, 0, 0); } while (0)
; #define PG8_LDA(dst, b, h) do { _Pragma("unroll") for (int m = 0; m < 4; ++m) _Pragma("unroll") for (int k = 0; k < 2; ++k) dst[m][k] = *(const PG8_LAS bf16x8*)(lds + PG8_SA(b, h) + aoff + m * 2048 + k * 1024); } while (0)
; template <class Epi, class Sched, bool ALIGN_EPI = false, bool SP2 = false, bool ATILED = false>
; __device__ __forceinline__ void gemm_phase(PG8_LAS unsigned char* lds, const Gemm g, const Sched& S, const Epi& E) {
;     ...
;             PG8_LDA(At, 0, 1); PG8_STAGE(PG8_SB(0, 0), b2, voffB); PG8_STAGE(PG8_SB(0, 1), b2 + hstep, voffB); PG8_STAGE(PG8_SA(0, 0), a2, voffA);
	s_nop 0
	global_load_lds_dwordx4 v130, s[70:71]

; #define PG8_STAGE(bufoff, gbase, voff) do { _Pragma("unroll") for (int _i = 0; _i < 2; ++_i) \
;         __builtin_amdgcn_global_load_lds((const unsigned*)((const char*)(gbase) + (voff)[_i]), (PG8_LAS unsigned*)(lds + (bufoff) + ldsw + _i * 8192), 16, 0, 0); } while (0)
; #define PG8_LDA(dst, b, h) do { _Pragma("unroll") for (int m = 0; m < 4; ++m) _Pragma("unroll") for (int k = 0; k < 2; ++k) dst[m][k] = *(const PG8_LAS bf16x8*)(lds + PG8_SA(b, h) + aoff + m * 2048 + k * 1024); } while (0)
; template <class Epi, class Sched, bool ALIGN_EPI = false, bool SP2 = false, bool ATILED = false>
; __device__ __forceinline__ void gemm_phase(PG8_LAS unsigned char* lds, const Gemm g, const Sched& S, const Epi& E) {
;     ...
;             PG8_LDA(At, 0, 1); PG8_STAGE(PG8_SB(0, 0), b2, voffB); PG8_STAGE(PG8_SB(0, 1), b2 + hstep, voffB); PG8_STAGE(PG8_SA(0, 0), a2, voffA);
	s_add_i32 m0, s69, 0x2000
	s_nop 0
	global_load_lds_dwordx4 v134, s[70:71]

; #define PG8_STAGE(bufoff, gbase, voff) do { _Pragma("unroll") for (int _i = 0; _i < 2; ++_i) \
;         __builtin_amdgcn_global_load_lds((const unsigned*)((const char*)(gbase) + (voff)[_i]), (PG8_LAS unsigned*)(lds + (bufoff) + ldsw + _i * 8192), 16, 0, 0); } while (0)
; #define PG8_LDA(dst, b, h) do { _Pragma("unroll") for (int m = 0; m < 4; ++m) _Pragma("unroll") for (int k = 0; k < 2; ++k) dst[m][k] = *(const PG8_LAS bf16x8*)(lds + PG8_SA(b, h) + aoff + m * 2048 + k * 1024); } while (0)
; #define PG8_LDB(dst, b, h) do { _Pragma("unroll") for (int n = 0; n < 2; ++n) _Pragma("unroll") for (int k = 0; k < 2; ++k) dst[n][k] = *(const PG8_LAS bf16x8*)(lds + PG8_SB(b, h) + boff + n * 2048 + k * 1024); } while (0)
; #define PG8_MMA(ai, bj, At, Bt) do { __builtin_amdgcn_s_setprio(1); _Pragma("unroll") for (int m = 0; m < 4; ++m) _Pragma("unroll") for (int n = 0; n < 2; ++n) _Pragma("unroll") for (int k = 0; k < 2; ++k) \
;         acc[ai][bj][m][n] = __builtin_amdgcn_mfma_f32_16x16x32_bf16(Bt[n][k], At[m][k], acc[ai][bj][m][n], 0, 0, 0); __builtin_amdgcn_s_setprio(0); } while (0)
; #define PG8_WAIT_V(n) asm volatile("s_waitcnt vmcnt(" #n ")" ::: "memory")
; #define PG8_WAIT_L(n) asm volatile("s_waitcnt lgkmcnt(" #n ")" ::: "memory")
; #define PG8_BAR __builtin_amdgcn_s_barrier()
; #define PG8_SCHED __builtin_amdgcn_sched_barrier(0)
; template <class Epi, class Sched, bool ALIGN_EPI = false, bool SP2 = false, bool ATILED = false>
; __device__ __forceinline__ void gemm_phase(PG8_LAS unsigned char* lds, const Gemm g, const Sched& S, const Epi& E) {
;     ...
;             PG8_LDA(At, 0, 1); PG8_STAGE(PG8_SB(0, 0), b2, voffB); PG8_STAGE(PG8_SB(0, 1), b2 + hstep, voffB); PG8_STAGE(PG8_SA(0, 0), a2, voffA);
;             PG8_WAIT_V(8); PG8_WAIT_L(0); PG8_BAR; PG8_MMA(1, 0, At, B0); PG8_MMA(1, 1, At, B1); PG8_BAR; PG8_SCHED;
;             PG8_LDB(B0, 1, 0); PG8_LDB(B1, 1, 1); PG8_SCHED; PG8_LDA(At, 1, 0); PG8_STAGE(PG8_SA(0, 1), a2 + hstepA, voffA);
	s_mov_b32 m0, s19
	s_nop 0
	global_load_lds_dwordx4 v128, s[44:45]
	s_mov_b32 m0, s48
	s_nop 0
	global_load_lds_dwordx4 v132, s[44:45]
	s_waitcnt vmcnt(8)
	s_waitcnt lgkmcnt(0)
	s_barrier
	s_setprio 1
	s_waitcnt lgkmcnt(0)
	v_mfma_f32_16x16x32_bf16 v[60:63], v[150:153], v[190:193], 0
	v_mfma_f32_16x16x32_bf16 v[56:59], v[166:169], v[190:193], 0
	v_mfma_f32_16x16x32_bf16 v[44:47], v[150:153], v[200:203], 0
	v_mfma_f32_16x16x32_bf16 v[40:43], v[166:169], v[200:203], 0
	v_mfma_f32_16x16x32_bf16 v[28:31], v[150:153], v[208:211], 0
	v_mfma_f32_16x16x32_bf16 v[24:27], v[166:169], v[208:211], 0
	v_mfma_f32_16x16x32_bf16 v[12:15], v[150:153], v[216:219], 0
	v_mfma_f32_16x16x32_bf16 v[8:11], v[166:169], v[216:219], 0
	v_mfma_f32_16x16x32_bf16 v[60:63], v[162:165], v[194:197], v[60:63]
	v_mfma_f32_16x16x32_bf16 v[56:59], v[170:173], v[194:197], v[56:59]
	v_mfma_f32_16x16x32_bf16 v[44:47], v[162:165], v[204:207], v[44:47]
	v_mfma_f32_16x16x32_bf16 v[40:43], v[170:173], v[204:207], v[40:43]
	v_mfma_f32_16x16x32_bf16 v[28:31], v[162:165], v[212:215], v[28:31]
	v_mfma_f32_16x16x32_bf16 v[24:27], v[170:173], v[212:215], v[24:27]
	v_mfma_f32_16x16x32_bf16 v[12:15], v[162:165], v[220:223], v[12:15]
	v_mfma_f32_16x16x32_bf16 v[8:11], v[170:173], v[220:223], v[8:11]
	s_setprio 0
	s_setprio 1
	v_mfma_f32_16x16x32_bf16 v[52:55], v[174:177], v[190:193], 0
	v_mfma_f32_16x16x32_bf16 v[48:51], v[182:185], v[190:193], 0
	v_mfma_f32_16x16x32_bf16 v[36:39], v[174:177], v[200:203], 0
	v_mfma_f32_16x16x32_bf16 v[32:35], v[182:185], v[200:203], 0
	v_mfma_f32_16x16x32_bf16 v[20:23], v[174:177], v[208:211], 0
	v_mfma_f32_16x16x32_bf16 v[16:19], v[182:185], v[208:211], 0
	v_mfma_f32_16x16x32_bf16 v[4:7], v[174:177], v[216:219], 0
	v_mfma_f32_16x16x32_bf16 v[0:3], v[182:185], v[216:219], 0
	v_mfma_f32_16x16x32_bf16 v[52:55], v[178:181], v[194:197], v[52:55]
	v_mfma_f32_16x16x32_bf16 v[48:51], v[186:189], v[194:197], v[48:51]
	v_mfma_f32_16x16x32_bf16 v[36:39], v[178:181], v[204:207], v[36:39]
	v_mfma_f32_16x16x32_bf16 v[32:35], v[186:189], v[204:207], v[32:35]
	v_mfma_f32_16x16x32_bf16 v[20:23], v[178:181], v[212:215], v[20:23]
	v_mfma_f32_16x16x32_bf16 v[16:19], v[186:189], v[212:215], v[16:19]
	v_mfma_f32_16x16x32_bf16 v[4:7], v[178:181], v[220:223], v[4:7]
	v_mfma_f32_16x16x32_bf16 v[0:3], v[186:189], v[220:223], v[0:3]
	s_setprio 0
	s_barrier
	s_add_i32 s69, 0, 0x18000
	v_add_u32_e32 v136, s69, v155
	s_add_i32 s70, 0, 0x1c000
	ds_read_b128 v[150:153], v136
	ds_read_b128 v[162:165], v136 offset:1024
	ds_read_b128 v[166:169], v136 offset:2048
	ds_read_b128 v[170:173], v136 offset:3072
	v_add_u32_e32 v136, s70, v155
	ds_read_b128 v[174:177], v136
	ds_read_b128 v[178:181], v136 offset:1024
	ds_read_b128 v[182:185], v136 offset:2048
	ds_read_b128 v[186:189], v136 offset:3072
	s_add_u32 s44, s44, 0x40000
	s_addc_u32 s45, s45, 0
	s_mov_b32 m0, s49

; #define PG8_STAGE(bufoff, gbase, voff) do { _Pragma("unroll") for (int _i = 0; _i < 2; ++_i) \
;         __builtin_amdgcn_global_load_lds((const unsigned*)((const char*)(gbase) + (voff)[_i]), (PG8_LAS unsigned*)(lds + (bufoff) + ldsw + _i * 8192), 16, 0, 0); } while (0)
; #define PG8_LDA(dst, b, h) do { _Pragma("unroll") for (int m = 0; m < 4; ++m) _Pragma("unroll") for (int k = 0; k < 2; ++k) dst[m][k] = *(const PG8_LAS bf16x8*)(lds + PG8_SA(b, h) + aoff + m * 2048 + k * 1024); } while (0)
; #define PG8_LDB(dst, b, h) do { _Pragma("unroll") for (int n = 0; n < 2; ++n) _Pragma("unroll") for (int k = 0; k < 2; ++k) dst[n][k] = *(const PG8_LAS bf16x8*)(lds + PG8_SB(b, h) + boff + n * 2048 + k * 1024); } while (0)
; #define PG8_SCHED __builtin_amdgcn_sched_barrier(0)
; template <class Epi, class Sched, bool ALIGN_EPI = false, bool SP2 = false, bool ATILED = false>
; __device__ __forceinline__ void gemm_phase(PG8_LAS unsigned char* lds, const Gemm g, const Sched& S, const Epi& E) {
;     ...
;             PG8_LDB(B0, 1, 0); PG8_LDB(B1, 1, 1); PG8_SCHED; PG8_LDA(At, 1, 0); PG8_STAGE(PG8_SA(0, 1), a2 + hstepA, voffA);
	ds_read_b128 v[190:193], v158 offset:32768
	ds_read_b128 v[194:197], v158 offset:33792
	ds_read_b128 v[200:203], v158 offset:34816
	ds_read_b128 v[204:207], v158 offset:35840
	ds_read_b128 v[208:211], v158 offset:36864
	ds_read_b128 v[212:215], v158 offset:37888
	ds_read_b128 v[216:219], v158 offset:38912
	ds_read_b128 v[220:223], v158 offset:39936
	global_load_lds_dwordx4 v128, s[44:45]

; #define PG8_STAGE(bufoff, gbase, voff) do { _Pragma("unroll") for (int _i = 0; _i < 2; ++_i) \
;         __builtin_amdgcn_global_load_lds((const unsigned*)((const char*)(gbase) + (voff)[_i]), (PG8_LAS unsigned*)(lds + (bufoff) + ldsw + _i * 8192), 16, 0, 0); } while (0)
; #define PG8_LDA(dst, b, h) do { _Pragma("unroll") for (int m = 0; m < 4; ++m) _Pragma("unroll") for (int k = 0; k < 2; ++k) dst[m][k] = *(const PG8_LAS bf16x8*)(lds + PG8_SA(b, h) + aoff + m * 2048 + k * 1024); } while (0)
; #define PG8_LDB(dst, b, h) do { _Pragma("unroll") for (int n = 0; n < 2; ++n) _Pragma("unroll") for (int k = 0; k < 2; ++k) dst[n][k] = *(const PG8_LAS bf16x8*)(lds + PG8_SB(b, h) + boff + n * 2048 + k * 1024); } while (0)
; #define PG8_MMA(ai, bj, At, Bt) do { __builtin_amdgcn_s_setprio(1); _Pragma("unroll") for (int m = 0; m < 4; ++m) _Pragma("unroll") for (int n = 0; n < 2; ++n) _Pragma("unroll") for (int k = 0; k < 2; ++k) \
;         acc[ai][bj][m][n] = __builtin_amdgcn_mfma_f32_16x16x32_bf16(Bt[n][k], At[m][k], acc[ai][bj][m][n], 0, 0, 0); __builtin_amdgcn_s_setprio(0); } while (0)
; #define PG8_WAIT_V(n) asm volatile("s_waitcnt vmcnt(" #n ")" ::: "memory")
; #define PG8_WAIT_L(n) asm volatile("s_waitcnt lgkmcnt(" #n ")" ::: "memory")
; #define PG8_BAR __builtin_amdgcn_s_barrier()
; #define PG8_SCHED __builtin_amdgcn_sched_barrier(0)
; template <class Epi, class Sched, bool ALIGN_EPI = false, bool SP2 = false, bool ATILED = false>
; __device__ __forceinline__ void gemm_phase(PG8_LAS unsigned char* lds, const Gemm g, const Sched& S, const Epi& E) {
;     ...
;             PG8_LDB(B0, 1, 0); PG8_LDB(B1, 1, 1); PG8_SCHED; PG8_LDA(At, 1, 0); PG8_STAGE(PG8_SA(0, 1), a2 + hstepA, voffA);
;             PG8_WAIT_V(8); PG8_WAIT_L(0); PG8_BAR; PG8_MMA(0, 0, At, B0); PG8_MMA(0, 1, At, B1); PG8_BAR; PG8_SCHED;
	s_mov_b32 m0, s50
	s_nop 0
	global_load_lds_dwordx4 v132, s[44:45]
	s_waitcnt vmcnt(8)
	s_waitcnt lgkmcnt(0)
	s_barrier
	s_setprio 1
	s_waitcnt lgkmcnt(0)
	v_mfma_f32_16x16x32_bf16 v[124:127], v[150:153], v[190:193], v[124:127]
	v_mfma_f32_16x16x32_bf16 v[120:123], v[166:169], v[190:193], v[120:123]
	v_mfma_f32_16x16x32_bf16 v[108:111], v[150:153], v[200:203], v[108:111]
	v_mfma_f32_16x16x32_bf16 v[104:107], v[166:169], v[200:203], v[104:107]
	v_mfma_f32_16x16x32_bf16 v[92:95], v[150:153], v[208:211], v[92:95]
	v_mfma_f32_16x16x32_bf16 v[88:91], v[166:169], v[208:211], v[88:91]
	v_mfma_f32_16x16x32_bf16 v[76:79], v[150:153], v[216:219], v[76:79]
	v_mfma_f32_16x16x32_bf16 v[72:75], v[166:169], v[216:219], v[72:75]
	v_mfma_f32_16x16x32_bf16 v[124:127], v[162:165], v[194:197], v[124:127]
	v_mfma_f32_16x16x32_bf16 v[120:123], v[170:173], v[194:197], v[120:123]
	v_mfma_f32_16x16x32_bf16 v[108:111], v[162:165], v[204:207], v[108:111]
	v_mfma_f32_16x16x32_bf16 v[104:107], v[170:173], v[204:207], v[104:107]
	v_mfma_f32_16x16x32_bf16 v[92:95], v[162:165], v[212:215], v[92:95]
	v_mfma_f32_16x16x32_bf16 v[88:91], v[170:173], v[212:215], v[88:91]
	v_mfma_f32_16x16x32_bf16 v[76:79], v[162:165], v[220:223], v[76:79]
	v_mfma_f32_16x16x32_bf16 v[72:75], v[170:173], v[220:223], v[72:75]
	s_setprio 0
	s_setprio 1
	v_mfma_f32_16x16x32_bf16 v[116:119], v[174:177], v[190:193], v[116:119]
	v_mfma_f32_16x16x32_bf16 v[112:115], v[182:185], v[190:193], v[112:115]
	v_mfma_f32_16x16x32_bf16 v[100:103], v[174:177], v[200:203], v[100:103]
	v_mfma_f32_16x16x32_bf16 v[96:99], v[182:185], v[200:203], v[96:99]
	v_mfma_f32_16x16x32_bf16 v[84:87], v[174:177], v[208:211], v[84:87]
	v_mfma_f32_16x16x32_bf16 v[80:83], v[182:185], v[208:211], v[80:83]
	v_mfma_f32_16x16x32_bf16 v[68:71], v[174:177], v[216:219], v[68:71]
	v_mfma_f32_16x16x32_bf16 v[64:67], v[182:185], v[216:219], v[64:67]
	v_mfma_f32_16x16x32_bf16 v[116:119], v[178:181], v[194:197], v[116:119]
	v_mfma_f32_16x16x32_bf16 v[112:115], v[186:189], v[194:197], v[112:115]
	v_mfma_f32_16x16x32_bf16 v[100:103], v[178:181], v[204:207], v[100:103]
	v_mfma_f32_16x16x32_bf16 v[96:99], v[186:189], v[204:207], v[96:99]
	v_mfma_f32_16x16x32_bf16 v[84:87], v[178:181], v[212:215], v[84:87]
	v_mfma_f32_16x16x32_bf16 v[80:83], v[186:189], v[212:215], v[80:83]
	v_mfma_f32_16x16x32_bf16 v[68:71], v[178:181], v[220:223], v[68:71]
	v_mfma_f32_16x16x32_bf16 v[64:67], v[186:189], v[220:223], v[64:67]
	s_setprio 0
	s_barrier
	s_add_i32 s44, s69, s46

; #define PG8_STAGE(bufoff, gbase, voff) do { _Pragma("unroll") for (int _i = 0; _i < 2; ++_i) \
;         __builtin_amdgcn_global_load_lds((const unsigned*)((const char*)(gbase) + (voff)[_i]), (PG8_LAS unsigned*)(lds + (bufoff) + ldsw + _i * 8192), 16, 0, 0); } while (0)
; #define PG8_LDA(dst, b, h) do { _Pragma("unroll") for (int m = 0; m < 4; ++m) _Pragma("unroll") for (int k = 0; k < 2; ++k) dst[m][k] = *(const PG8_LAS bf16x8*)(lds + PG8_SA(b, h) + aoff + m * 2048 + k * 1024); } while (0)
; template <class Epi, class Sched, bool ALIGN_EPI = false, bool SP2 = false, bool ATILED = false>
; __device__ __forceinline__ void gemm_phase(PG8_LAS unsigned char* lds, const Gemm g, const Sched& S, const Epi& E) {
;     ...
;             PG8_LDA(At, 1, 1); PG8_STAGE(PG8_SB(1, 0), b3, voffB); PG8_STAGE(PG8_SB(1, 1), b3 + hstep, voffB); PG8_STAGE(PG8_SA(1, 0), a3, voffA);
	s_mov_b32 m0, s44
	ds_read_b128 v[190:193], v158 offset:49152
	ds_read_b128 v[194:197], v158 offset:50176
	ds_read_b128 v[200:203], v158 offset:51200
	ds_read_b128 v[204:207], v158 offset:52224
	ds_read_b128 v[208:211], v158 offset:53248
	ds_read_b128 v[212:215], v158 offset:54272
	ds_read_b128 v[216:219], v158 offset:55296
	ds_read_b128 v[220:223], v158 offset:56320
	global_load_lds_dwordx4 v130, s[98:99]
	s_add_i32 m0, s44, 0x2000
	s_add_u32 s42, s42, 0x40080

; #define PG8_STAGE(bufoff, gbase, voff) do { _Pragma("unroll") for (int _i = 0; _i < 2; ++_i) \
;         __builtin_amdgcn_global_load_lds((const unsigned*)((const char*)(gbase) + (voff)[_i]), (PG8_LAS unsigned*)(lds + (bufoff) + ldsw + _i * 8192), 16, 0, 0); } while (0)
; #define PG8_LDA(dst, b, h) do { _Pragma("unroll") for (int m = 0; m < 4; ++m) _Pragma("unroll") for (int k = 0; k < 2; ++k) dst[m][k] = *(const PG8_LAS bf16x8*)(lds + PG8_SA(b, h) + aoff + m * 2048 + k * 1024); } while (0)
; template <class Epi, class Sched, bool ALIGN_EPI = false, bool SP2 = false, bool ATILED = false>
; __device__ __forceinline__ void gemm_phase(PG8_LAS unsigned char* lds, const Gemm g, const Sched& S, const Epi& E) {
;     ...
;             PG8_LDA(At, 1, 1); PG8_STAGE(PG8_SB(1, 0), b3, voffB); PG8_STAGE(PG8_SB(1, 1), b3 + hstep, voffB); PG8_STAGE(PG8_SA(1, 0), a3, voffA);
	s_addc_u32 s43, s43, 0
	s_add_i32 s44, s70, s46
	global_load_lds_dwordx4 v134, s[98:99]

; #define PG8_STAGE(bufoff, gbase, voff) do { _Pragma("unroll") for (int _i = 0; _i < 2; ++_i) \
;         __builtin_amdgcn_global_load_lds((const unsigned*)((const char*)(gbase) + (voff)[_i]), (PG8_LAS unsigned*)(lds + (bufoff) + ldsw + _i * 8192), 16, 0, 0); } while (0)
; #define PG8_LDA(dst, b, h) do { _Pragma("unroll") for (int m = 0; m < 4; ++m) _Pragma("unroll") for (int k = 0; k < 2; ++k) dst[m][k] = *(const PG8_LAS bf16x8*)(lds + PG8_SA(b, h) + aoff + m * 2048 + k * 1024); } while (0)
; template <class Epi, class Sched, bool ALIGN_EPI = false, bool SP2 = false, bool ATILED = false>
; __device__ __forceinline__ void gemm_phase(PG8_LAS unsigned char* lds, const Gemm g, const Sched& S, const Epi& E) {
;     ...
;             PG8_LDA(At, 1, 1); PG8_STAGE(PG8_SB(1, 0), b3, voffB); PG8_STAGE(PG8_SB(1, 1), b3 + hstep, voffB); PG8_STAGE(PG8_SA(1, 0), a3, voffA);
	s_mov_b32 m0, s44
	s_nop 0
	global_load_lds_dwordx4 v130, s[42:43]

; #define PG8_STAGE(bufoff, gbase, voff) do { _Pragma("unroll") for (int _i = 0; _i < 2; ++_i) \
;         __builtin_amdgcn_global_load_lds((const unsigned*)((const char*)(gbase) + (voff)[_i]), (PG8_LAS unsigned*)(lds + (bufoff) + ldsw + _i * 8192), 16, 0, 0); } while (0)
; #define PG8_LDA(dst, b, h) do { _Pragma("unroll") for (int m = 0; m < 4; ++m) _Pragma("unroll") for (int k = 0; k < 2; ++k) dst[m][k] = *(const PG8_LAS bf16x8*)(lds + PG8_SA(b, h) + aoff + m * 2048 + k * 1024); } while (0)
; template <class Epi, class Sched, bool ALIGN_EPI = false, bool SP2 = false, bool ATILED = false>
; __device__ __forceinline__ void gemm_phase(PG8_LAS unsigned char* lds, const Gemm g, const Sched& S, const Epi& E) {
;     ...
;             PG8_LDA(At, 1, 1); PG8_STAGE(PG8_SB(1, 0), b3, voffB); PG8_STAGE(PG8_SB(1, 1), b3 + hstep, voffB); PG8_STAGE(PG8_SA(1, 0), a3, voffA);
	s_add_i32 m0, s44, 0x2000
	s_nop 0
	global_load_lds_dwordx4 v134, s[42:43]

; #define PG8_STAGE(bufoff, gbase, voff) do { _Pragma("unroll") for (int _i = 0; _i < 2; ++_i) \
;         __builtin_amdgcn_global_load_lds((const unsigned*)((const char*)(gbase) + (voff)[_i]), (PG8_LAS unsigned*)(lds + (bufoff) + ldsw + _i * 8192), 16, 0, 0); } while (0)
; #define PG8_LDA(dst, b, h) do { _Pragma("unroll") for (int m = 0; m < 4; ++m) _Pragma("unroll") for (int k = 0; k < 2; ++k) dst[m][k] = *(const PG8_LAS bf16x8*)(lds + PG8_SA(b, h) + aoff + m * 2048 + k * 1024); } while (0)
; template <class Epi, class Sched, bool ALIGN_EPI = false, bool SP2 = false, bool ATILED = false>
; __device__ __forceinline__ void gemm_phase(PG8_LAS unsigned char* lds, const Gemm g, const Sched& S, const Epi& E) {
;     ...
;             PG8_LDA(At, 1, 1); PG8_STAGE(PG8_SB(1, 0), b3, voffB); PG8_STAGE(PG8_SB(1, 1), b3 + hstep, voffB); PG8_STAGE(PG8_SA(1, 0), a3, voffA);
	s_mov_b32 m0, s58
	s_nop 0
	global_load_lds_dwordx4 v128, s[100:101]

; #define PG8_MMA(ai, bj, At, Bt) do { __builtin_amdgcn_s_setprio(1); _Pragma("unroll") for (int m = 0; m < 4; ++m) _Pragma("unroll") for (int n = 0; n < 2; ++n) _Pragma("unroll") for (int k = 0; k < 2; ++k) \
;         acc[ai][bj][m][n] = __builtin_amdgcn_mfma_f32_16x16x32_bf16(Bt[n][k], At[m][k], acc[ai][bj][m][n], 0, 0, 0); __builtin_amdgcn_s_setprio(0); } while (0)
; #define PG8_WAIT_V(n) asm volatile("s_waitcnt vmcnt(" #n ")" ::: "memory")
; #define PG8_WAIT_L(n) asm volatile("s_waitcnt lgkmcnt(" #n ")" ::: "memory")
; #define PG8_BAR __builtin_amdgcn_s_barrier()
; #define PG8_SCHED __builtin_amdgcn_sched_barrier(0)
; template <class Epi, class Sched, bool ALIGN_EPI = false, bool SP2 = false, bool ATILED = false>
; __device__ __forceinline__ void gemm_phase(PG8_LAS unsigned char* lds, const Gemm g, const Sched& S, const Epi& E) {
;     ...
;         for (int t = 0; t < nt; t += 2) {
;             const bool last = (t == nt - 2);
;             const char* a1 = cA + (size_t)(t + 1) * kstepA;
;             const char* a2 = last ? nA : cA + (size_t)(t + 2) * kstepA; const char* b2 = last ? nB : cB + (size_t)(t + 2) * kstep;
;             const char* a3 = a2 + kstepA; const char* b3 = b2 + kstep;
;     ...
;             PG8_WAIT_V(8); PG8_WAIT_L(0); PG8_BAR; PG8_MMA(1, 0, At, B0); PG8_MMA(1, 1, At, B1); PG8_BAR; PG8_SCHED;
	s_mov_b32 m0, s59
	s_nop 0
	global_load_lds_dwordx4 v132, s[100:101]
	s_waitcnt vmcnt(8)
	s_waitcnt lgkmcnt(0)
	s_barrier
	s_setprio 1
	s_waitcnt lgkmcnt(0)
	v_mfma_f32_16x16x32_bf16 v[60:63], v[150:153], v[190:193], v[60:63]
	v_mfma_f32_16x16x32_bf16 v[56:59], v[166:169], v[190:193], v[56:59]
	v_mfma_f32_16x16x32_bf16 v[44:47], v[150:153], v[200:203], v[44:47]
	v_mfma_f32_16x16x32_bf16 v[40:43], v[166:169], v[200:203], v[40:43]
	v_mfma_f32_16x16x32_bf16 v[28:31], v[150:153], v[208:211], v[28:31]
	v_mfma_f32_16x16x32_bf16 v[24:27], v[166:169], v[208:211], v[24:27]
	v_mfma_f32_16x16x32_bf16 v[12:15], v[150:153], v[216:219], v[12:15]
	v_mfma_f32_16x16x32_bf16 v[8:11], v[166:169], v[216:219], v[8:11]
	v_mfma_f32_16x16x32_bf16 v[60:63], v[162:165], v[194:197], v[60:63]
	v_mfma_f32_16x16x32_bf16 v[56:59], v[170:173], v[194:197], v[56:59]
	v_mfma_f32_16x16x32_bf16 v[44:47], v[162:165], v[204:207], v[44:47]
	v_mfma_f32_16x16x32_bf16 v[40:43], v[170:173], v[204:207], v[40:43]
	v_mfma_f32_16x16x32_bf16 v[28:31], v[162:165], v[212:215], v[28:31]
	v_mfma_f32_16x16x32_bf16 v[24:27], v[170:173], v[212:215], v[24:27]
	v_mfma_f32_16x16x32_bf16 v[12:15], v[162:165], v[220:223], v[12:15]
	v_mfma_f32_16x16x32_bf16 v[8:11], v[170:173], v[220:223], v[8:11]
	s_setprio 0
	s_setprio 1
	v_mfma_f32_16x16x32_bf16 v[52:55], v[174:177], v[190:193], v[52:55]
	v_mfma_f32_16x16x32_bf16 v[48:51], v[182:185], v[190:193], v[48:51]
	v_mfma_f32_16x16x32_bf16 v[36:39], v[174:177], v[200:203], v[36:39]
	v_mfma_f32_16x16x32_bf16 v[32:35], v[182:185], v[200:203], v[32:35]
	v_mfma_f32_16x16x32_bf16 v[20:23], v[174:177], v[208:211], v[20:23]
	v_mfma_f32_16x16x32_bf16 v[16:19], v[182:185], v[208:211], v[16:19]
	v_mfma_f32_16x16x32_bf16 v[4:7], v[174:177], v[216:219], v[4:7]
	v_mfma_f32_16x16x32_bf16 v[0:3], v[182:185], v[216:219], v[0:3]
	v_mfma_f32_16x16x32_bf16 v[52:55], v[178:181], v[194:197], v[52:55]
	v_mfma_f32_16x16x32_bf16 v[48:51], v[186:189], v[194:197], v[48:51]
	v_mfma_f32_16x16x32_bf16 v[36:39], v[178:181], v[204:207], v[36:39]
	v_mfma_f32_16x16x32_bf16 v[32:35], v[186:189], v[204:207], v[32:35]
	v_mfma_f32_16x16x32_bf16 v[20:23], v[178:181], v[212:215], v[20:23]
	v_mfma_f32_16x16x32_bf16 v[16:19], v[186:189], v[212:215], v[16:19]
	v_mfma_f32_16x16x32_bf16 v[4:7], v[178:181], v[220:223], v[4:7]
	v_mfma_f32_16x16x32_bf16 v[0:3], v[186:189], v[220:223], v[0:3]
	s_setprio 0
	s_barrier
	s_add_i32 s68, s68, 2
	s_add_u32 s20, s20, 0x100
	s_addc_u32 s21, s21, 0
	s_add_u32 s66, s66, 0x100
	s_addc_u32 s67, s67, 0
	s_cmp_gt_u32 s68, 13

; __device__ __forceinline__ void rows_rstd(const float* ssq, int row0, int fq, float (&rs)[2][4]) {
;     f32x4 p[2][4];
; #pragma unroll
;     for (int ai = 0; ai < 2; ++ai)
; #pragma unroll
;         for (int m = 0; m < 4; ++m) p[ai][m] = *(const f32x4*)(ssq + (size_t)(row0 + ai * HALF + m * 16) * 16 + 4 * fq);
; #pragma unroll
;     for (int ai = 0; ai < 2; ++ai)
; #pragma unroll
;         for (int m = 0; m < 4; ++m) { float s = (p[ai][m][0] + p[ai][m][1]) + (p[ai][m][2] + p[ai][m][3]); s += __shfl_xor(s, 16); s += __shfl_xor(s, 32); rs[ai][m] = __builtin_amdgcn_rsqf(s * (1.0f / (float)DM) + RMS_EPS); }
;     __device__ __forceinline__ void operator()(const f32x4 (&acc)[2][2][4][2], const Unit& u, int wr, int wc, int fr, int fq) const {
;         const int row0 = u.pm * BM + wr * 64 + fr, col0 = u.pn * HALF + wc * 32 + 8 * fq;
;         float rsv[2][4]; rows_rstd(ssq, row0, fq, rsv);
; #pragma unroll
;         for (int ai = 0; ai < 2; ++ai)
; #pragma unroll
;             for (int m = 0; m < 4; ++m) {
;                 const int row = row0 + ai * HALF + m * 16; const float rs = rsv[ai][m], cexp = -1.4426950408889634f * rs, rs2 = rs * rs;
;                 const f32x4 g0 = acc[ai][0][m][0], g1 = acc[ai][0][m][1], u0 = acc[ai][1][m][0], u1 = acc[ai][1][m][1];
;                 const f32x4 t0 = g0 * cexp, t1 = g1 * cexp;
;                 f32x4 d0 = (f32x4){__builtin_amdgcn_exp2f(t0[0]), __builtin_amdgcn_exp2f(t0[1]), __builtin_amdgcn_exp2f(t0[2]), __builtin_amdgcn_exp2f(t0[3])} + 1.0f;
;                 f32x4 d1 = (f32x4){__builtin_amdgcn_exp2f(t1[0]), __builtin_amdgcn_exp2f(t1[1]), __builtin_amdgcn_exp2f(t1[2]), __builtin_amdgcn_exp2f(t1[3])} + 1.0f;
;                 const f32x4 r0 = (f32x4){__builtin_amdgcn_rcpf(d0[0]), __builtin_amdgcn_rcpf(d0[1]), __builtin_amdgcn_rcpf(d0[2]), __builtin_amdgcn_rcpf(d0[3])} * rs2;
;                 const f32x4 r1 = (f32x4){__builtin_amdgcn_rcpf(d1[0]), __builtin_amdgcn_rcpf(d1[1]), __builtin_amdgcn_rcpf(d1[2]), __builtin_amdgcn_rcpf(d1[3])} * rs2;
;                 const f32x4 a0 = (g0 * u0) * r0, a1 = (g1 * u1) * r1;
;                 u32x4 w; w.x = cvt_pk_bf16(a0[0], a0[1]); w.y = cvt_pk_bf16(a0[2], a0[3]); w.z = cvt_pk_bf16(a1[0], a1[1]); w.w = cvt_pk_bf16(a1[2], a1[3]);
;                 *(u32x4*)(O + (((size_t)(row >> 8) * (DFF / BK) + (col0 >> 6)) * BM + (row & 255)) * BK + (col0 & 63)) = w;
.Lalign2_skip4:
	s_waitcnt vmcnt(0)
	v_mov_b32_e32 v194, v163
	v_mov_b32_e32 v195, v164
	v_mov_b32_e32 v163, v165
	v_pk_add_f32 v[162:163], v[194:195], v[162:163]
	v_mov_b32_e32 v164, v167
	v_mov_b32_e32 v165, v168
	v_mov_b32_e32 v167, v169
	v_add_f32_e32 v151, v162, v163
	v_pk_add_f32 v[162:163], v[164:165], v[166:167]
	v_mov_b32_e32 v168, v171
	v_mov_b32_e32 v169, v172
	v_mov_b32_e32 v171, v173
	v_mov_b32_e32 v172, v175
	v_mov_b32_e32 v173, v176
	v_mov_b32_e32 v175, v177
	v_mov_b32_e32 v176, v179
	v_mov_b32_e32 v177, v180
	v_mov_b32_e32 v179, v181
	v_pk_add_f32 v[164:165], v[168:169], v[170:171]
	v_pk_add_f32 v[166:167], v[172:173], v[174:175]
	ds_bpermute_b32 v153, v136, v151
	v_add_f32_e32 v161, v162, v163
	v_pk_add_f32 v[168:169], v[176:177], v[178:179]
	v_add_f32_e32 v162, v164, v165
	v_add_f32_e32 v163, v166, v167
	ds_bpermute_b32 v166, v136, v161
	v_add_f32_e32 v164, v168, v169
	ds_bpermute_b32 v167, v136, v162
	ds_bpermute_b32 v168, v136, v163
	ds_bpermute_b32 v169, v136, v164
	s_waitcnt lgkmcnt(4)
	v_add_f32_e32 v151, v151, v153
	ds_bpermute_b32 v153, v149, v151
	s_waitcnt lgkmcnt(4)
	v_add_f32_e32 v161, v161, v166
	s_waitcnt lgkmcnt(3)
	v_add_f32_e32 v162, v162, v167
	s_waitcnt lgkmcnt(2)
	v_add_f32_e32 v163, v163, v168
	ds_bpermute_b32 v166, v149, v161
	v_mov_b32_e32 v180, v183
	v_mov_b32_e32 v181, v184
	v_mov_b32_e32 v183, v185
	s_waitcnt lgkmcnt(2)
	v_add_f32_e32 v164, v164, v169
	ds_bpermute_b32 v167, v149, v162
	ds_bpermute_b32 v168, v149, v163
	v_pk_add_f32 v[170:171], v[180:181], v[182:183]
	ds_bpermute_b32 v169, v149, v164
	v_add_f32_e32 v165, v170, v171
	ds_bpermute_b32 v170, v136, v165
	s_waitcnt lgkmcnt(5)
	v_add_f32_e32 v151, v151, v153
	v_fmamk_f32 v232, v151, 0x3a800000, v160
	v_mov_b32_e32 v233, v232
	s_waitcnt lgkmcnt(4)
	v_add_f32_e32 v153, v161, v166
	s_waitcnt lgkmcnt(3)
	v_add_f32_e32 v161, v162, v167
	s_waitcnt lgkmcnt(2)
	v_add_f32_e32 v162, v163, v168
	v_rsq_f32_e32 v166, v232
	v_fmamk_f32 v234, v153, 0x3a800000, v160
	v_mov_b32_e32 v235, v234
	v_fmamk_f32 v238, v161, 0x3a800000, v160
	v_mov_b32_e32 v239, v238
	v_fmamk_f32 v240, v162, 0x3a800000, v160
	v_mov_b32_e32 v241, v240
	v_rsq_f32_e32 v172, v234
	s_waitcnt lgkmcnt(1)
	v_add_f32_e32 v151, v164, v169
	v_mov_b32_e32 v162, v187
	v_mov_b32_e32 v163, v188
	v_mov_b32_e32 v187, v189
	v_fmamk_f32 v236, v151, 0x3a800000, v160
	v_mov_b32_e32 v237, v236
	v_pk_add_f32 v[162:163], v[162:163], v[186:187]
	v_rsq_f32_e32 v173, v236
	s_waitcnt lgkmcnt(0)
	v_add_f32_e32 v151, v165, v170
	v_add_f32_e32 v165, v162, v163
	v_mov_b32_e32 v162, v191
	v_mov_b32_e32 v163, v192
	v_mov_b32_e32 v191, v193
	v_pk_add_f32 v[162:163], v[162:163], v[190:191]
	ds_bpermute_b32 v167, v136, v165
	v_add_f32_e32 v162, v162, v163
	ds_bpermute_b32 v136, v136, v162
	ds_bpermute_b32 v164, v149, v151
	v_rsq_f32_e32 v153, v238
	s_waitcnt lgkmcnt(2)
	v_add_f32_e32 v163, v165, v167
	v_rsq_f32_e32 v161, v240
	s_waitcnt lgkmcnt(1)
	v_add_f32_e32 v136, v162, v136
	s_waitcnt lgkmcnt(0)
	v_add_f32_e32 v151, v151, v164
	ds_bpermute_b32 v164, v149, v163
	ds_bpermute_b32 v149, v149, v136
	v_fmamk_f32 v242, v151, 0x3a800000, v160
	v_mov_b32_e32 v243, v242
	v_rsq_f32_e32 v174, v242
	s_waitcnt lgkmcnt(1)
	v_add_f32_e32 v151, v163, v164
	s_waitcnt lgkmcnt(0)
	v_add_f32_e32 v136, v136, v149
	v_fmamk_f32 v244, v151, 0x3a800000, v160
	v_mov_b32_e32 v245, v244
	v_fmamk_f32 v246, v136, 0x3a800000, v160
	v_mov_b32_e32 v247, v246
	v_rsq_f32_e32 v175, v244
	v_rsq_f32_e32 v151, v246
	v_mul_f32_e32 v136, 0xbfb8aa3b, v166
	v_pk_mul_f32 v[166:167], v[124:125], v[136:137] op_sel_hi:[1,0]
	v_pk_mul_f32 v[164:165], v[126:127], v[136:137] op_sel_hi:[1,0]
	v_pk_mul_f32 v[168:169], v[122:123], v[136:137] op_sel_hi:[1,0]
	v_pk_mul_f32 v[170:171], v[120:121], v[136:137] op_sel_hi:[1,0]
	v_exp_f32_e32 v166, v166
	v_exp_f32_e32 v167, v167
	v_exp_f32_e32 v164, v164
	v_exp_f32_e32 v165, v165
	v_exp_f32_e32 v170, v170
	v_exp_f32_e32 v168, v168
	v_exp_f32_e32 v169, v169
	v_exp_f32_e32 v171, v171
	v_pk_fma_f32 v[166:167], v[166:167], v[232:233], v[232:233]
	v_pk_fma_f32 v[164:165], v[164:165], v[232:233], v[232:233]
	v_pk_fma_f32 v[168:169], v[168:169], v[232:233], v[232:233]
	v_pk_fma_f32 v[170:171], v[170:171], v[232:233], v[232:233]
	v_rcp_f32_e32 v166, v166
	v_rcp_f32_e32 v167, v167
	v_rcp_f32_e32 v164, v164
	v_rcp_f32_e32 v165, v165
	v_rcp_f32_e32 v170, v170
	v_rcp_f32_e32 v171, v171
	v_rcp_f32_e32 v168, v168
	v_rcp_f32_e32 v169, v169
	s_nop 0
	v_pk_mul_f32 v[116:117], v[116:117], v[166:167]
	v_pk_mul_f32 v[120:121], v[114:115], v[168:169]
	v_pk_mul_f32 v[114:115], v[112:113], v[170:171]
	v_cvt_pk_bf16_f32 v112, v116, v117
	v_lshlrev_b32_e32 v116, 7, v152
	v_and_b32_e32 v136, 0x6780, v116
	v_pk_mul_f32 v[118:119], v[118:119], v[164:165]
	v_lshl_add_u64 v[116:117], s[20:21], 0, v[136:137]
	v_mov_b32_e32 v149, v137
	v_cvt_pk_bf16_f32 v113, v118, v119
	v_cvt_pk_bf16_f32 v114, v114, v115
	v_cvt_pk_bf16_f32 v115, v120, v121
	v_lshl_add_u64 v[116:117], v[116:117], 0, v[148:149]
	global_store_dwordx4 v[116:117], v[112:115], off
	s_nop 1
	v_mul_f32_e32 v112, 0xbfb8aa3b, v172
	v_pk_mul_f32 v[118:119], v[110:111], v[112:113] op_sel_hi:[1,0]
	v_pk_mul_f32 v[120:121], v[108:109], v[112:113] op_sel_hi:[1,0]
	v_pk_mul_f32 v[122:123], v[106:107], v[112:113] op_sel_hi:[1,0]
	v_pk_mul_f32 v[112:113], v[104:105], v[112:113] op_sel_hi:[1,0]
	v_exp_f32_e32 v120, v120
	v_exp_f32_e32 v121, v121
	v_exp_f32_e32 v118, v118
	v_exp_f32_e32 v119, v119
	v_exp_f32_e32 v112, v112
	v_exp_f32_e32 v122, v122
	v_exp_f32_e32 v123, v123
	v_exp_f32_e32 v113, v113
	v_pk_fma_f32 v[118:119], v[118:119], v[234:235], v[234:235]
	v_pk_fma_f32 v[120:121], v[120:121], v[234:235], v[234:235]
; __device__ __forceinline__ unsigned cvt_pk_bf16(float lo, float hi) { typedef float f2 __attribute__((ext_vector_type(2))); const bf16v2 r = __builtin_convertvector((f2){lo, hi}, bf16v2); return __builtin_bit_cast(unsigned, r); }
;     __device__ __forceinline__ void operator()(const f32x4 (&acc)[2][2][4][2], const Unit& u, int wr, int wc, int fr, int fq) const {
;     ...
;                 const int row = row0 + ai * HALF + m * 16; const float rs = rsv[ai][m], cexp = -1.4426950408889634f * rs, rs2 = rs * rs;
;                 const f32x4 g0 = acc[ai][0][m][0], g1 = acc[ai][0][m][1], u0 = acc[ai][1][m][0], u1 = acc[ai][1][m][1];
;                 const f32x4 t0 = g0 * cexp, t1 = g1 * cexp;
;                 f32x4 d0 = (f32x4){__builtin_amdgcn_exp2f(t0[0]), __builtin_amdgcn_exp2f(t0[1]), __builtin_amdgcn_exp2f(t0[2]), __builtin_amdgcn_exp2f(t0[3])} + 1.0f;
;                 f32x4 d1 = (f32x4){__builtin_amdgcn_exp2f(t1[0]), __builtin_amdgcn_exp2f(t1[1]), __builtin_amdgcn_exp2f(t1[2]), __builtin_amdgcn_exp2f(t1[3])} + 1.0f;
;                 const f32x4 r0 = (f32x4){__builtin_amdgcn_rcpf(d0[0]), __builtin_amdgcn_rcpf(d0[1]), __builtin_amdgcn_rcpf(d0[2]), __builtin_amdgcn_rcpf(d0[3])} * rs2;
;                 const f32x4 r1 = (f32x4){__builtin_amdgcn_rcpf(d1[0]), __builtin_amdgcn_rcpf(d1[1]), __builtin_amdgcn_rcpf(d1[2]), __builtin_amdgcn_rcpf(d1[3])} * rs2;
;                 const f32x4 a0 = (g0 * u0) * r0, a1 = (g1 * u1) * r1;
;                 u32x4 w; w.x = cvt_pk_bf16(a0[0], a0[1]); w.y = cvt_pk_bf16(a0[2], a0[3]); w.z = cvt_pk_bf16(a1[0], a1[1]); w.w = cvt_pk_bf16(a1[2], a1[3]);
;                 *(u32x4*)(O + (((size_t)(row >> 8) * (DFF / BK) + (col0 >> 6)) * BM + (row & 255)) * BK + (col0 & 63)) = w;
	v_pk_fma_f32 v[122:123], v[122:123], v[234:235], v[234:235]
	v_pk_fma_f32 v[112:113], v[112:113], v[234:235], v[234:235]
	v_rcp_f32_e32 v120, v120
	v_rcp_f32_e32 v121, v121
	v_rcp_f32_e32 v118, v118
	v_rcp_f32_e32 v119, v119
	v_rcp_f32_e32 v112, v112
	v_rcp_f32_e32 v113, v113
	v_rcp_f32_e32 v122, v122
	v_rcp_f32_e32 v123, v123
	s_nop 0
	v_pk_mul_f32 v[102:103], v[102:103], v[118:119]
	v_pk_mul_f32 v[100:101], v[100:101], v[120:121]
	v_pk_mul_f32 v[104:105], v[98:99], v[122:123]
	v_pk_mul_f32 v[98:99], v[96:97], v[112:113]
	v_cvt_pk_bf16_f32 v96, v100, v101
	v_cvt_pk_bf16_f32 v97, v102, v103
	v_cvt_pk_bf16_f32 v98, v98, v99
	v_cvt_pk_bf16_f32 v99, v104, v105
	global_store_dwordx4 v[116:117], v[96:99], off offset:2048
	s_nop 1
	v_mul_f32_e32 v96, 0xbfb8aa3b, v153
	v_pk_mul_f32 v[102:103], v[92:93], v[96:97] op_sel_hi:[1,0]
	v_pk_mul_f32 v[100:101], v[94:95], v[96:97] op_sel_hi:[1,0]
	v_pk_mul_f32 v[104:105], v[90:91], v[96:97] op_sel_hi:[1,0]
	v_pk_mul_f32 v[96:97], v[88:89], v[96:97] op_sel_hi:[1,0]
	v_exp_f32_e32 v102, v102
	v_exp_f32_e32 v103, v103
	v_exp_f32_e32 v100, v100
	v_exp_f32_e32 v101, v101
	v_exp_f32_e32 v96, v96
	v_exp_f32_e32 v104, v104
	v_exp_f32_e32 v105, v105
	v_exp_f32_e32 v97, v97
	v_pk_fma_f32 v[102:103], v[102:103], v[238:239], v[238:239]
	v_pk_fma_f32 v[100:101], v[100:101], v[238:239], v[238:239]
	v_pk_fma_f32 v[104:105], v[104:105], v[238:239], v[238:239]
	v_pk_fma_f32 v[96:97], v[96:97], v[238:239], v[238:239]
	v_rcp_f32_e32 v102, v102
	v_rcp_f32_e32 v103, v103
	v_rcp_f32_e32 v100, v100
	v_rcp_f32_e32 v101, v101
	v_rcp_f32_e32 v96, v96
	v_rcp_f32_e32 v97, v97
	v_rcp_f32_e32 v104, v104
	v_rcp_f32_e32 v105, v105
	s_nop 0
	v_pk_mul_f32 v[84:85], v[84:85], v[102:103]
	v_pk_mul_f32 v[86:87], v[86:87], v[100:101]
	v_pk_mul_f32 v[88:89], v[82:83], v[104:105]
	v_pk_mul_f32 v[82:83], v[80:81], v[96:97]
	v_cvt_pk_bf16_f32 v80, v84, v85
	v_add_co_u32_e32 v84, vcc, s62, v116
	v_cvt_pk_bf16_f32 v81, v86, v87
	v_cvt_pk_bf16_f32 v82, v82, v83
	v_cvt_pk_bf16_f32 v83, v88, v89
	v_addc_co_u32_e32 v85, vcc, 0, v117, vcc
	global_store_dwordx4 v[84:85], v[80:83], off
	s_nop 1
	v_mul_f32_e32 v80, 0xbfb8aa3b, v161
	v_pk_mul_f32 v[86:87], v[78:79], v[80:81] op_sel_hi:[1,0]
	v_pk_mul_f32 v[88:89], v[76:77], v[80:81] op_sel_hi:[1,0]
	v_pk_mul_f32 v[90:91], v[74:75], v[80:81] op_sel_hi:[1,0]
	v_pk_mul_f32 v[80:81], v[72:73], v[80:81] op_sel_hi:[1,0]
	v_exp_f32_e32 v88, v88
	v_exp_f32_e32 v89, v89
	v_exp_f32_e32 v86, v86
	v_exp_f32_e32 v87, v87
	v_exp_f32_e32 v80, v80
	v_exp_f32_e32 v90, v90
	v_exp_f32_e32 v91, v91
	v_exp_f32_e32 v81, v81
	v_pk_fma_f32 v[86:87], v[86:87], v[240:241], v[240:241]
	v_pk_fma_f32 v[88:89], v[88:89], v[240:241], v[240:241]
	v_pk_fma_f32 v[90:91], v[90:91], v[240:241], v[240:241]
	v_pk_fma_f32 v[80:81], v[80:81], v[240:241], v[240:241]
	v_rcp_f32_e32 v88, v88
	v_rcp_f32_e32 v89, v89
	v_rcp_f32_e32 v86, v86
	v_rcp_f32_e32 v87, v87
	v_rcp_f32_e32 v80, v80
	v_rcp_f32_e32 v81, v81
	v_rcp_f32_e32 v90, v90
	v_rcp_f32_e32 v91, v91
	s_nop 0
	v_pk_mul_f32 v[70:71], v[70:71], v[86:87]
	v_pk_mul_f32 v[68:69], v[68:69], v[88:89]
	v_pk_mul_f32 v[72:73], v[66:67], v[90:91]
	v_pk_mul_f32 v[66:67], v[64:65], v[80:81]
	v_cvt_pk_bf16_f32 v64, v68, v69
	v_cvt_pk_bf16_f32 v65, v70, v71
	v_cvt_pk_bf16_f32 v66, v66, v67
	v_cvt_pk_bf16_f32 v67, v72, v73
	global_store_dwordx4 v[84:85], v[64:67], off offset:2048
	s_nop 1
	v_mul_f32_e32 v66, 0xbfb8aa3b, v173
	v_pk_mul_f32 v[70:71], v[62:63], v[66:67] op_sel_hi:[1,0]
	v_pk_mul_f32 v[72:73], v[60:61], v[66:67] op_sel_hi:[1,0]
	v_pk_mul_f32 v[74:75], v[58:59], v[66:67] op_sel_hi:[1,0]
	v_pk_mul_f32 v[66:67], v[56:57], v[66:67] op_sel_hi:[1,0]
	v_exp_f32_e32 v70, v70
	v_exp_f32_e32 v71, v71
	v_exp_f32_e32 v72, v72
	v_exp_f32_e32 v73, v73
	v_exp_f32_e32 v66, v66
	v_exp_f32_e32 v74, v74
	v_exp_f32_e32 v75, v75
	v_exp_f32_e32 v67, v67
	v_pk_fma_f32 v[70:71], v[70:71], v[236:237], v[236:237]
	v_pk_fma_f32 v[72:73], v[72:73], v[236:237], v[236:237]
	v_pk_fma_f32 v[74:75], v[74:75], v[236:237], v[236:237]
	v_pk_fma_f32 v[66:67], v[66:67], v[236:237], v[236:237]
	v_rcp_f32_e32 v70, v70
	v_rcp_f32_e32 v71, v71
	v_rcp_f32_e32 v72, v72
	v_rcp_f32_e32 v73, v73
	v_rcp_f32_e32 v66, v66
	v_rcp_f32_e32 v67, v67
	v_rcp_f32_e32 v74, v74
	v_rcp_f32_e32 v75, v75
	v_lshrrev_b32_e32 v64, 8, v150
	v_mad_i32_i24 v64, v64, 44, s11
	v_ashrrev_i32_e32 v65, 31, v64
	s_nop 0
	v_pk_mul_f32 v[54:55], v[54:55], v[70:71]
	v_lshlrev_b64 v[64:65], 15, v[64:65]
; #define PG8_BAR __builtin_amdgcn_s_barrier()
;     __device__ __forceinline__ void operator()(const f32x4 (&acc)[2][2][4][2], const Unit& u, int wr, int wc, int fr, int fq) const {
;     ...
;                 const int row = row0 + ai * HALF + m * 16; const float rs = rsv[ai][m], cexp = -1.4426950408889634f * rs, rs2 = rs * rs;
;                 const f32x4 g0 = acc[ai][0][m][0], g1 = acc[ai][0][m][1], u0 = acc[ai][1][m][0], u1 = acc[ai][1][m][1];
;                 const f32x4 t0 = g0 * cexp, t1 = g1 * cexp;
;                 f32x4 d0 = (f32x4){__builtin_amdgcn_exp2f(t0[0]), __builtin_amdgcn_exp2f(t0[1]), __builtin_amdgcn_exp2f(t0[2]), __builtin_amdgcn_exp2f(t0[3])} + 1.0f;
;                 f32x4 d1 = (f32x4){__builtin_amdgcn_exp2f(t1[0]), __builtin_amdgcn_exp2f(t1[1]), __builtin_amdgcn_exp2f(t1[2]), __builtin_amdgcn_exp2f(t1[3])} + 1.0f;
;                 const f32x4 r0 = (f32x4){__builtin_amdgcn_rcpf(d0[0]), __builtin_amdgcn_rcpf(d0[1]), __builtin_amdgcn_rcpf(d0[2]), __builtin_amdgcn_rcpf(d0[3])} * rs2;
;                 const f32x4 r1 = (f32x4){__builtin_amdgcn_rcpf(d1[0]), __builtin_amdgcn_rcpf(d1[1]), __builtin_amdgcn_rcpf(d1[2]), __builtin_amdgcn_rcpf(d1[3])} * rs2;
;                 const f32x4 a0 = (g0 * u0) * r0, a1 = (g1 * u1) * r1;
;                 u32x4 w; w.x = cvt_pk_bf16(a0[0], a0[1]); w.y = cvt_pk_bf16(a0[2], a0[3]); w.z = cvt_pk_bf16(a1[0], a1[1]); w.w = cvt_pk_bf16(a1[2], a1[3]);
;                 *(u32x4*)(O + (((size_t)(row >> 8) * (DFF / BK) + (col0 >> 6)) * BM + (row & 255)) * BK + (col0 & 63)) = w;
; template <class Epi, class Sched, bool ALIGN_EPI = false, bool SP2 = false, bool ATILED = false>
; __device__ __forceinline__ void gemm_phase(PG8_LAS unsigned char* lds, const Gemm g, const Sched& S, const Epi& E) {
;     ...
;         if constexpr (!Epi::AFTER_DRAIN) { E(acc, cur, wr, wc, fr, fq); S.done(cur); }
;         if (!has_next) break;
; #pragma unroll
;         for (int a = 0; a < 2; ++a)
; #pragma unroll
;             for (int b = 0; b < 2; ++b)
; #pragma unroll
;                 for (int m = 0; m < 4; ++m)
; #pragma unroll
;                     for (int n = 0; n < 2; ++n) acc[a][b][m][n] = (f32x4){0.f, 0.f, 0.f, 0.f};
;         cur = nxt; cA = nA; cB = nB; ++ui;
;         if constexpr (ALIGN_EPI) { if (wr == 1) PG8_BAR; }
	v_pk_mul_f32 v[52:53], v[52:53], v[72:73]
	v_pk_mul_f32 v[56:57], v[50:51], v[74:75]
	v_pk_mul_f32 v[50:51], v[48:49], v[66:67]
	v_cvt_pk_bf16_f32 v49, v54, v55
	v_lshlrev_b32_e32 v54, 7, v150
	v_cvt_pk_bf16_f32 v48, v52, v53
	v_lshl_add_u64 v[52:53], s[36:37], 0, v[64:65]
	v_and_b32_e32 v136, 0x6780, v54
	v_lshl_add_u64 v[52:53], v[52:53], 0, v[136:137]
	v_cvt_pk_bf16_f32 v50, v50, v51
	v_cvt_pk_bf16_f32 v51, v56, v57
	v_lshl_add_u64 v[52:53], v[52:53], 0, v[148:149]
	global_store_dwordx4 v[52:53], v[48:51], off
	s_nop 1
	v_mul_f32_e32 v48, 0xbfb8aa3b, v174
	v_pk_mul_f32 v[54:55], v[46:47], v[48:49] op_sel_hi:[1,0]
	v_pk_mul_f32 v[56:57], v[44:45], v[48:49] op_sel_hi:[1,0]
	v_pk_mul_f32 v[58:59], v[42:43], v[48:49] op_sel_hi:[1,0]
	v_pk_mul_f32 v[48:49], v[40:41], v[48:49] op_sel_hi:[1,0]
	v_exp_f32_e32 v56, v56
	v_exp_f32_e32 v57, v57
	v_exp_f32_e32 v54, v54
	v_exp_f32_e32 v55, v55
	v_exp_f32_e32 v48, v48
	v_exp_f32_e32 v58, v58
	v_exp_f32_e32 v59, v59
	v_exp_f32_e32 v49, v49
	v_pk_fma_f32 v[54:55], v[54:55], v[242:243], v[242:243]
	v_pk_fma_f32 v[56:57], v[56:57], v[242:243], v[242:243]
	v_pk_fma_f32 v[58:59], v[58:59], v[242:243], v[242:243]
	v_pk_fma_f32 v[48:49], v[48:49], v[242:243], v[242:243]
	v_rcp_f32_e32 v56, v56
	v_rcp_f32_e32 v57, v57
	v_rcp_f32_e32 v54, v54
	v_rcp_f32_e32 v55, v55
	v_rcp_f32_e32 v48, v48
	v_rcp_f32_e32 v49, v49
	v_rcp_f32_e32 v58, v58
	v_rcp_f32_e32 v59, v59
	s_nop 0
	v_pk_mul_f32 v[38:39], v[38:39], v[54:55]
	v_pk_mul_f32 v[36:37], v[36:37], v[56:57]
	v_pk_mul_f32 v[40:41], v[34:35], v[58:59]
	v_pk_mul_f32 v[34:35], v[32:33], v[48:49]
	v_cvt_pk_bf16_f32 v32, v36, v37
	v_cvt_pk_bf16_f32 v33, v38, v39
	v_cvt_pk_bf16_f32 v34, v34, v35
	v_cvt_pk_bf16_f32 v35, v40, v41
	global_store_dwordx4 v[52:53], v[32:35], off offset:2048
	s_nop 1
	v_mul_f32_e32 v32, 0xbfb8aa3b, v175
	v_pk_mul_f32 v[38:39], v[28:29], v[32:33] op_sel_hi:[1,0]
	v_pk_mul_f32 v[36:37], v[30:31], v[32:33] op_sel_hi:[1,0]
	v_pk_mul_f32 v[40:41], v[26:27], v[32:33] op_sel_hi:[1,0]
	v_pk_mul_f32 v[32:33], v[24:25], v[32:33] op_sel_hi:[1,0]
	v_exp_f32_e32 v38, v38
	v_exp_f32_e32 v39, v39
	v_exp_f32_e32 v36, v36
	v_exp_f32_e32 v37, v37
	v_exp_f32_e32 v32, v32
	v_exp_f32_e32 v40, v40
	v_exp_f32_e32 v41, v41
	v_exp_f32_e32 v33, v33
	v_pk_fma_f32 v[38:39], v[38:39], v[244:245], v[244:245]
	v_pk_fma_f32 v[36:37], v[36:37], v[244:245], v[244:245]
	v_pk_fma_f32 v[40:41], v[40:41], v[244:245], v[244:245]
	v_pk_fma_f32 v[32:33], v[32:33], v[244:245], v[244:245]
	v_rcp_f32_e32 v38, v38
	v_rcp_f32_e32 v39, v39
	v_rcp_f32_e32 v36, v36
	v_rcp_f32_e32 v37, v37
	v_rcp_f32_e32 v32, v32
	v_rcp_f32_e32 v33, v33
	v_rcp_f32_e32 v40, v40
	v_rcp_f32_e32 v41, v41
	s_nop 0
	v_pk_mul_f32 v[20:21], v[20:21], v[38:39]
	v_pk_mul_f32 v[22:23], v[22:23], v[36:37]
	v_pk_mul_f32 v[24:25], v[18:19], v[40:41]
	v_pk_mul_f32 v[18:19], v[16:17], v[32:33]
	v_cvt_pk_bf16_f32 v16, v20, v21
	v_add_co_u32_e32 v20, vcc, s62, v52
	v_cvt_pk_bf16_f32 v17, v22, v23
	v_cvt_pk_bf16_f32 v18, v18, v19
	v_cvt_pk_bf16_f32 v19, v24, v25
	v_addc_co_u32_e32 v21, vcc, 0, v53, vcc
	global_store_dwordx4 v[20:21], v[16:19], off
	s_andn2_b64 vcc, exec, s[0:1]
	s_mov_b64 s[0:1], -1
	v_mul_f32_e32 v16, 0xbfb8aa3b, v151
	v_pk_mul_f32 v[22:23], v[14:15], v[16:17] op_sel_hi:[1,0]
	v_pk_mul_f32 v[24:25], v[12:13], v[16:17] op_sel_hi:[1,0]
	v_pk_mul_f32 v[26:27], v[10:11], v[16:17] op_sel_hi:[1,0]
	v_pk_mul_f32 v[16:17], v[8:9], v[16:17] op_sel_hi:[1,0]
	v_exp_f32_e32 v24, v24
	v_exp_f32_e32 v25, v25
	v_exp_f32_e32 v22, v22
	v_exp_f32_e32 v23, v23
	v_exp_f32_e32 v16, v16
	v_exp_f32_e32 v26, v26
	v_exp_f32_e32 v27, v27
	v_exp_f32_e32 v17, v17
	v_pk_fma_f32 v[22:23], v[22:23], v[246:247], v[246:247]
	v_pk_fma_f32 v[24:25], v[24:25], v[246:247], v[246:247]
	v_pk_fma_f32 v[26:27], v[26:27], v[246:247], v[246:247]
	v_pk_fma_f32 v[16:17], v[16:17], v[246:247], v[246:247]
	v_rcp_f32_e32 v24, v24
	v_rcp_f32_e32 v25, v25
	v_rcp_f32_e32 v22, v22
	v_rcp_f32_e32 v23, v23
	v_rcp_f32_e32 v16, v16
	v_rcp_f32_e32 v17, v17
	v_rcp_f32_e32 v26, v26
	v_rcp_f32_e32 v27, v27
	s_nop 0
	v_pk_mul_f32 v[6:7], v[6:7], v[22:23]
	v_pk_mul_f32 v[4:5], v[4:5], v[24:25]
	v_pk_mul_f32 v[8:9], v[2:3], v[26:27]
	v_pk_mul_f32 v[2:3], v[0:1], v[16:17]
	v_cvt_pk_bf16_f32 v0, v4, v5
	v_cvt_pk_bf16_f32 v1, v6, v7
	v_cvt_pk_bf16_f32 v2, v2, v3
	v_cvt_pk_bf16_f32 v3, v8, v9
	global_store_dwordx4 v[20:21], v[0:3], off offset:2048
	s_cbranch_vccnz .LBB0_813
	s_branch .LBB0_812
